# GEMM K-loops: loop-back barrier moved behind the counter/address SALU block (back edge rotated out of the critical path)
# baseline (speedup 1.0000x reference)
; #define PG8_STAGE(bufoff, gbase, voff) do { _Pragma("unroll") for (int _i = 0; _i < 2; ++_i) \
;         __builtin_amdgcn_global_load_lds((const unsigned*)((const char*)(gbase) + (voff)[_i]), (LAS unsigned*)(lds + (bufoff) + ldsw + _i * 8192), 16, 0, 0); } while (0)
; #define PG8_LDA(dst, b, h) do { _Pragma("unroll") for (int m = 0; m < 4; ++m) _Pragma("unroll") for (int k = 0; k < 2; ++k) dst[m][k] = *(const LAS bf16x8*)(lds + PG8_SA(b, h) + aoff + m * 2048 + k * 1024); } while (0)
; #define PG8_LDB(dst, b, h) do { _Pragma("unroll") for (int n = 0; n < 2; ++n) _Pragma("unroll") for (int k = 0; k < 2; ++k) dst[n][k] = *(const LAS bf16x8*)(lds + PG8_SB(b, h) + boff + n * 2048 + k * 1024); } while (0)
; #define PG8_MMA(ai, bj, At, Bt) do { __builtin_amdgcn_s_setprio(1); _Pragma("unroll") for (int m = 0; m < 4; ++m) _Pragma("unroll") for (int n = 0; n < 2; ++n) _Pragma("unroll") for (int k = 0; k < 2; ++k) \
;         acc[ai][bj][m][n] = __builtin_amdgcn_mfma_f32_16x16x32_bf16(Bt[n][k], At[m][k], acc[ai][bj][m][n], 0, 0, 0); __builtin_amdgcn_s_setprio(0); } while (0)
; #define PG8_WAIT_V(n) asm volatile("s_waitcnt vmcnt(" #n ")" ::: "memory")
; #define PG8_WAIT_L(n) asm volatile("s_waitcnt lgkmcnt(" #n ")" ::: "memory")
; #define PG8_BAR __builtin_amdgcn_s_barrier()
; #define PG8_SCHED __builtin_amdgcn_sched_barrier(0)
; template <class Epi>
; __device__ __forceinline__ void gemm_phase(LAS unsigned char* lds, const Gemm g, const StaticOrder& S, const Epi& E, int wave_s) {
;     ...
;             const bool last = (t == nt - 2);
;             const char* a1 = cA + (size_t)(t + 1) * kstep;
;             const char* a2 = last ? nA : cA + (size_t)(t + 2) * kstep; const char* b2 = last ? nB : cB + (size_t)(t + 2) * kstep;
;             const char* a3 = a2 + kstep; const char* b3 = b2 + kstep;
;             PG8_LDB(B0, 0, 0); PG8_LDB(B1, 0, 1); PG8_SCHED; PG8_LDA(At, 0, 0); PG8_STAGE(PG8_SA(1, 1), a1 + hstepA, voffA);
;             PG8_WAIT_V(8); PG8_WAIT_L(0); PG8_BAR; PG8_MMA(0, 0, At, B0); PG8_MMA(0, 1, At, B1); PG8_BAR; PG8_SCHED;
;             PG8_LDA(At, 0, 1); PG8_STAGE(PG8_SB(0, 0), b2, voffB); PG8_STAGE(PG8_SB(0, 1), b2 + hstepB, voffB); PG8_STAGE(PG8_SA(0, 0), a2, voffA);
;             PG8_WAIT_V(8); PG8_WAIT_L(0); PG8_BAR; PG8_MMA(1, 0, At, B0); PG8_MMA(1, 1, At, B1); PG8_BAR; PG8_SCHED;
.LBB0_121:
	ds_read_b128 v[128:131], v182
	ds_read_b128 v[132:135], v182 offset:1024
	ds_read_b128 v[136:139], v182 offset:2048
	ds_read_b128 v[140:143], v182 offset:3072
	ds_read_b128 v[144:147], v183
	ds_read_b128 v[174:177], v183 offset:1024
	ds_read_b128 v[190:193], v183 offset:2048
	ds_read_b128 v[194:197], v183 offset:3072
	s_add_u32 s38, s36, 0xfff80080
	s_addc_u32 s39, s37, -1
	s_cmp_eq_u32 s50, 28
	s_cselect_b32 s41, s7, s39
	s_cselect_b32 s40, s9, s38
	s_cselect_b32 s39, s79, vcc_hi
	s_cselect_b32 s38, s85, vcc_lo
	v_lshl_add_u64 v[230:231], s[36:37], 0, v[164:165]
	s_add_i32 m0, s45, 0xc000
	ds_read_b128 v[198:201], v184
	ds_read_b128 v[202:205], v184 offset:1024
	ds_read_b128 v[206:209], v184 offset:2048
	ds_read_b128 v[210:213], v184 offset:3072
	ds_read_b128 v[214:217], v184 offset:4096
	ds_read_b128 v[218:221], v184 offset:5120
	ds_read_b128 v[222:225], v184 offset:6144
	ds_read_b128 v[226:229], v184 offset:7168
	global_load_lds_dwordx4 v[230:231], off
	v_lshl_add_u64 v[230:231], s[36:37], 0, v[166:167]
	s_add_i32 m0, s45, 0xe000
	s_nop 0
	global_load_lds_dwordx4 v[230:231], off
	s_waitcnt vmcnt(8)
	s_waitcnt lgkmcnt(0)
	s_barrier
	s_setprio 1
	s_waitcnt lgkmcnt(0)
	v_mfma_f32_16x16x32_bf16 v[124:127], v[128:131], v[198:201], v[124:127]
	v_mfma_f32_16x16x32_bf16 v[120:123], v[136:139], v[198:201], v[120:123]
	v_mfma_f32_16x16x32_bf16 v[108:111], v[128:131], v[206:209], v[108:111]
	v_mfma_f32_16x16x32_bf16 v[104:107], v[136:139], v[206:209], v[104:107]
	v_mfma_f32_16x16x32_bf16 v[92:95], v[128:131], v[214:217], v[92:95]
	v_mfma_f32_16x16x32_bf16 v[88:91], v[136:139], v[214:217], v[88:91]
	v_mfma_f32_16x16x32_bf16 v[76:79], v[128:131], v[222:225], v[76:79]
	v_mfma_f32_16x16x32_bf16 v[72:75], v[136:139], v[222:225], v[72:75]
	v_mfma_f32_16x16x32_bf16 v[124:127], v[132:135], v[202:205], v[124:127]
	v_mfma_f32_16x16x32_bf16 v[120:123], v[140:143], v[202:205], v[120:123]
	v_mfma_f32_16x16x32_bf16 v[108:111], v[132:135], v[210:213], v[108:111]
	v_mfma_f32_16x16x32_bf16 v[104:107], v[140:143], v[210:213], v[104:107]
	v_mfma_f32_16x16x32_bf16 v[92:95], v[132:135], v[218:221], v[92:95]
	v_mfma_f32_16x16x32_bf16 v[88:91], v[140:143], v[218:221], v[88:91]
	v_mfma_f32_16x16x32_bf16 v[76:79], v[132:135], v[226:229], v[76:79]
	v_mfma_f32_16x16x32_bf16 v[72:75], v[140:143], v[226:229], v[72:75]
	s_setprio 0
	s_setprio 1
	v_mfma_f32_16x16x32_bf16 v[116:119], v[144:147], v[198:201], v[116:119]
	v_mfma_f32_16x16x32_bf16 v[112:115], v[190:193], v[198:201], v[112:115]
	v_mfma_f32_16x16x32_bf16 v[100:103], v[144:147], v[206:209], v[100:103]
	v_mfma_f32_16x16x32_bf16 v[96:99], v[190:193], v[206:209], v[96:99]
	v_mfma_f32_16x16x32_bf16 v[84:87], v[144:147], v[214:217], v[84:87]
	v_mfma_f32_16x16x32_bf16 v[80:83], v[190:193], v[214:217], v[80:83]
	v_mfma_f32_16x16x32_bf16 v[68:71], v[144:147], v[222:225], v[68:71]
	v_mfma_f32_16x16x32_bf16 v[64:67], v[190:193], v[222:225], v[64:67]
	v_mfma_f32_16x16x32_bf16 v[116:119], v[174:177], v[202:205], v[116:119]
	v_mfma_f32_16x16x32_bf16 v[112:115], v[194:197], v[202:205], v[112:115]
	v_mfma_f32_16x16x32_bf16 v[100:103], v[174:177], v[210:213], v[100:103]
	v_mfma_f32_16x16x32_bf16 v[96:99], v[194:197], v[210:213], v[96:99]
	v_mfma_f32_16x16x32_bf16 v[84:87], v[174:177], v[218:221], v[84:87]
	v_mfma_f32_16x16x32_bf16 v[80:83], v[194:197], v[218:221], v[80:83]
	v_mfma_f32_16x16x32_bf16 v[68:71], v[174:177], v[226:229], v[68:71]
	v_mfma_f32_16x16x32_bf16 v[64:67], v[194:197], v[226:229], v[64:67]
	s_setprio 0
	s_barrier
	s_add_i32 s56, s94, s44
	v_lshl_add_u64 v[230:231], s[38:39], 0, v[150:151]
	s_mov_b32 m0, s56
	ds_read_b128 v[198:201], v184 offset:16384
	ds_read_b128 v[202:205], v184 offset:17408
	ds_read_b128 v[206:209], v184 offset:18432
	ds_read_b128 v[210:213], v184 offset:19456
	ds_read_b128 v[214:217], v184 offset:20480
	ds_read_b128 v[218:221], v184 offset:21504
	ds_read_b128 v[222:225], v184 offset:22528
	ds_read_b128 v[226:229], v184 offset:23552
	global_load_lds_dwordx4 v[230:231], off
	s_add_i32 m0, s56, 0x2000
	s_add_u32 s56, s38, 0x80000
	v_lshl_add_u64 v[232:233], s[38:39], 0, v[154:155]
	s_addc_u32 s57, s39, 0
	s_add_i32 s34, s95, s44
	global_load_lds_dwordx4 v[232:233], off
	v_lshl_add_u64 v[234:235], s[56:57], 0, v[150:151]
	s_mov_b32 m0, s34
	v_lshl_add_u64 v[236:237], s[40:41], 0, v[152:153]
	global_load_lds_dwordx4 v[234:235], off
	v_lshl_add_u64 v[234:235], s[56:57], 0, v[154:155]
	s_add_i32 m0, s34, 0x2000
	s_nop 0
	global_load_lds_dwordx4 v[234:235], off
	v_lshl_add_u64 v[234:235], s[40:41], 0, v[148:149]
	s_mov_b32 m0, s45
	s_nop 0
	global_load_lds_dwordx4 v[234:235], off
	s_mov_b32 m0, s46
	s_nop 0
	global_load_lds_dwordx4 v[236:237], off
	s_waitcnt vmcnt(8)
	s_waitcnt lgkmcnt(0)
	s_barrier
; #define PG8_STAGE(bufoff, gbase, voff) do { _Pragma("unroll") for (int _i = 0; _i < 2; ++_i) \
;         __builtin_amdgcn_global_load_lds((const unsigned*)((const char*)(gbase) + (voff)[_i]), (LAS unsigned*)(lds + (bufoff) + ldsw + _i * 8192), 16, 0, 0); } while (0)
; #define PG8_LDA(dst, b, h) do { _Pragma("unroll") for (int m = 0; m < 4; ++m) _Pragma("unroll") for (int k = 0; k < 2; ++k) dst[m][k] = *(const LAS bf16x8*)(lds + PG8_SA(b, h) + aoff + m * 2048 + k * 1024); } while (0)
; #define PG8_LDB(dst, b, h) do { _Pragma("unroll") for (int n = 0; n < 2; ++n) _Pragma("unroll") for (int k = 0; k < 2; ++k) dst[n][k] = *(const LAS bf16x8*)(lds + PG8_SB(b, h) + boff + n * 2048 + k * 1024); } while (0)
; #define PG8_MMA(ai, bj, At, Bt) do { __builtin_amdgcn_s_setprio(1); _Pragma("unroll") for (int m = 0; m < 4; ++m) _Pragma("unroll") for (int n = 0; n < 2; ++n) _Pragma("unroll") for (int k = 0; k < 2; ++k) \
;         acc[ai][bj][m][n] = __builtin_amdgcn_mfma_f32_16x16x32_bf16(Bt[n][k], At[m][k], acc[ai][bj][m][n], 0, 0, 0); __builtin_amdgcn_s_setprio(0); } while (0)
; #define PG8_WAIT_V(n) asm volatile("s_waitcnt vmcnt(" #n ")" ::: "memory")
; #define PG8_WAIT_L(n) asm volatile("s_waitcnt lgkmcnt(" #n ")" ::: "memory")
; #define PG8_BAR __builtin_amdgcn_s_barrier()
; #define PG8_SCHED __builtin_amdgcn_sched_barrier(0)
; template <class Epi>
; __device__ __forceinline__ void gemm_phase(LAS unsigned char* lds, const Gemm g, const StaticOrder& S, const Epi& E, int wave_s) {
;     ...
;             PG8_WAIT_V(8); PG8_WAIT_L(0); PG8_BAR; PG8_MMA(1, 0, At, B0); PG8_MMA(1, 1, At, B1); PG8_BAR; PG8_SCHED;
;             PG8_LDB(B0, 1, 0); PG8_LDB(B1, 1, 1); PG8_SCHED; PG8_LDA(At, 1, 0); PG8_STAGE(PG8_SA(0, 1), a2 + hstepA, voffA);
;             PG8_WAIT_V(8); PG8_WAIT_L(0); PG8_BAR; PG8_MMA(0, 0, At, B0); PG8_MMA(0, 1, At, B1); PG8_BAR; PG8_SCHED;
	s_setprio 1
	s_waitcnt lgkmcnt(0)
	v_mfma_f32_16x16x32_bf16 v[60:63], v[128:131], v[198:201], v[60:63]
	v_mfma_f32_16x16x32_bf16 v[56:59], v[136:139], v[198:201], v[56:59]
	v_mfma_f32_16x16x32_bf16 v[44:47], v[128:131], v[206:209], v[44:47]
	v_mfma_f32_16x16x32_bf16 v[40:43], v[136:139], v[206:209], v[40:43]
	v_mfma_f32_16x16x32_bf16 v[28:31], v[128:131], v[214:217], v[28:31]
	v_mfma_f32_16x16x32_bf16 v[24:27], v[136:139], v[214:217], v[24:27]
	v_mfma_f32_16x16x32_bf16 v[12:15], v[128:131], v[222:225], v[12:15]
	v_mfma_f32_16x16x32_bf16 v[8:11], v[136:139], v[222:225], v[8:11]
	v_mfma_f32_16x16x32_bf16 v[60:63], v[132:135], v[202:205], v[60:63]
	v_mfma_f32_16x16x32_bf16 v[56:59], v[140:143], v[202:205], v[56:59]
	v_mfma_f32_16x16x32_bf16 v[44:47], v[132:135], v[210:213], v[44:47]
	v_mfma_f32_16x16x32_bf16 v[40:43], v[140:143], v[210:213], v[40:43]
	v_mfma_f32_16x16x32_bf16 v[28:31], v[132:135], v[218:221], v[28:31]
	v_mfma_f32_16x16x32_bf16 v[24:27], v[140:143], v[218:221], v[24:27]
	v_mfma_f32_16x16x32_bf16 v[12:15], v[132:135], v[226:229], v[12:15]
	v_mfma_f32_16x16x32_bf16 v[8:11], v[140:143], v[226:229], v[8:11]
	s_setprio 0
	s_setprio 1
	v_mfma_f32_16x16x32_bf16 v[52:55], v[144:147], v[198:201], v[52:55]
	v_mfma_f32_16x16x32_bf16 v[48:51], v[190:193], v[198:201], v[48:51]
	v_mfma_f32_16x16x32_bf16 v[36:39], v[144:147], v[206:209], v[36:39]
	v_mfma_f32_16x16x32_bf16 v[32:35], v[190:193], v[206:209], v[32:35]
	v_mfma_f32_16x16x32_bf16 v[20:23], v[144:147], v[214:217], v[20:23]
	v_mfma_f32_16x16x32_bf16 v[16:19], v[190:193], v[214:217], v[16:19]
	v_mfma_f32_16x16x32_bf16 v[4:7], v[144:147], v[222:225], v[4:7]
	v_mfma_f32_16x16x32_bf16 v[0:3], v[190:193], v[222:225], v[0:3]
	v_mfma_f32_16x16x32_bf16 v[52:55], v[174:177], v[202:205], v[52:55]
	v_mfma_f32_16x16x32_bf16 v[48:51], v[194:197], v[202:205], v[48:51]
	v_mfma_f32_16x16x32_bf16 v[36:39], v[174:177], v[210:213], v[36:39]
	v_mfma_f32_16x16x32_bf16 v[32:35], v[194:197], v[210:213], v[32:35]
	v_mfma_f32_16x16x32_bf16 v[20:23], v[174:177], v[218:221], v[20:23]
	v_mfma_f32_16x16x32_bf16 v[16:19], v[194:197], v[218:221], v[16:19]
	v_mfma_f32_16x16x32_bf16 v[4:7], v[174:177], v[226:229], v[4:7]
	v_mfma_f32_16x16x32_bf16 v[0:3], v[194:197], v[226:229], v[0:3]
	s_setprio 0
	s_barrier
	s_add_i32 s34, 0, 0x18000
	s_add_i32 s35, 0, 0x1c000
	v_add_u32_e32 v140, s34, v180
	v_add_u32_e32 v156, s35, v180
	ds_read_b128 v[128:131], v140
	ds_read_b128 v[132:135], v140 offset:1024
	ds_read_b128 v[136:139], v140 offset:2048
	ds_read_b128 v[140:143], v140 offset:3072
	ds_read_b128 v[144:147], v156
	ds_read_b128 v[174:177], v156 offset:1024
	ds_read_b128 v[190:193], v156 offset:2048
	ds_read_b128 v[194:197], v156 offset:3072
	s_add_u32 s40, s40, 0x80000
	s_addc_u32 s41, s41, 0
	s_mov_b32 m0, s47
	v_lshl_add_u64 v[238:239], s[40:41], 0, v[148:149]
	ds_read_b128 v[198:201], v184 offset:32768
	ds_read_b128 v[202:205], v184 offset:33792
	ds_read_b128 v[206:209], v184 offset:34816
	ds_read_b128 v[210:213], v184 offset:35840
	ds_read_b128 v[214:217], v184 offset:36864
	ds_read_b128 v[218:221], v184 offset:37888
	ds_read_b128 v[222:225], v184 offset:38912
	ds_read_b128 v[226:229], v184 offset:39936
	global_load_lds_dwordx4 v[238:239], off
	v_lshl_add_u64 v[238:239], s[40:41], 0, v[152:153]
	s_mov_b32 m0, s48
	s_nop 0
	global_load_lds_dwordx4 v[238:239], off
	s_waitcnt vmcnt(8)
	s_waitcnt lgkmcnt(0)
	s_barrier
	s_setprio 1
	s_waitcnt lgkmcnt(0)
	v_mfma_f32_16x16x32_bf16 v[124:127], v[128:131], v[198:201], v[124:127]
	v_mfma_f32_16x16x32_bf16 v[120:123], v[136:139], v[198:201], v[120:123]
	v_mfma_f32_16x16x32_bf16 v[108:111], v[128:131], v[206:209], v[108:111]
	v_mfma_f32_16x16x32_bf16 v[104:107], v[136:139], v[206:209], v[104:107]
	v_mfma_f32_16x16x32_bf16 v[92:95], v[128:131], v[214:217], v[92:95]
	v_mfma_f32_16x16x32_bf16 v[88:91], v[136:139], v[214:217], v[88:91]
	v_mfma_f32_16x16x32_bf16 v[76:79], v[128:131], v[222:225], v[76:79]
	v_mfma_f32_16x16x32_bf16 v[72:75], v[136:139], v[222:225], v[72:75]
	v_mfma_f32_16x16x32_bf16 v[124:127], v[132:135], v[202:205], v[124:127]
	v_mfma_f32_16x16x32_bf16 v[120:123], v[140:143], v[202:205], v[120:123]
	v_mfma_f32_16x16x32_bf16 v[108:111], v[132:135], v[210:213], v[108:111]
	v_mfma_f32_16x16x32_bf16 v[104:107], v[140:143], v[210:213], v[104:107]
	v_mfma_f32_16x16x32_bf16 v[92:95], v[132:135], v[218:221], v[92:95]
	v_mfma_f32_16x16x32_bf16 v[88:91], v[140:143], v[218:221], v[88:91]
	v_mfma_f32_16x16x32_bf16 v[76:79], v[132:135], v[226:229], v[76:79]
	v_mfma_f32_16x16x32_bf16 v[72:75], v[140:143], v[226:229], v[72:75]
	s_setprio 0
	s_setprio 1
	v_mfma_f32_16x16x32_bf16 v[116:119], v[144:147], v[198:201], v[116:119]
	v_mfma_f32_16x16x32_bf16 v[112:115], v[190:193], v[198:201], v[112:115]
	v_mfma_f32_16x16x32_bf16 v[100:103], v[144:147], v[206:209], v[100:103]
	v_mfma_f32_16x16x32_bf16 v[96:99], v[190:193], v[206:209], v[96:99]
	v_mfma_f32_16x16x32_bf16 v[84:87], v[144:147], v[214:217], v[84:87]
	v_mfma_f32_16x16x32_bf16 v[80:83], v[190:193], v[214:217], v[80:83]
	v_mfma_f32_16x16x32_bf16 v[68:71], v[144:147], v[222:225], v[68:71]
	v_mfma_f32_16x16x32_bf16 v[64:67], v[190:193], v[222:225], v[64:67]
	v_mfma_f32_16x16x32_bf16 v[116:119], v[174:177], v[202:205], v[116:119]
	v_mfma_f32_16x16x32_bf16 v[112:115], v[194:197], v[202:205], v[112:115]
	v_mfma_f32_16x16x32_bf16 v[100:103], v[174:177], v[210:213], v[100:103]
	v_mfma_f32_16x16x32_bf16 v[96:99], v[194:197], v[210:213], v[96:99]
	v_mfma_f32_16x16x32_bf16 v[84:87], v[174:177], v[218:221], v[84:87]
	v_mfma_f32_16x16x32_bf16 v[80:83], v[194:197], v[218:221], v[80:83]
	v_mfma_f32_16x16x32_bf16 v[68:71], v[174:177], v[226:229], v[68:71]
	v_mfma_f32_16x16x32_bf16 v[64:67], v[194:197], v[226:229], v[64:67]
	s_setprio 0
	s_barrier
; #define PG8_STAGE(bufoff, gbase, voff) do { _Pragma("unroll") for (int _i = 0; _i < 2; ++_i) \
;         __builtin_amdgcn_global_load_lds((const unsigned*)((const char*)(gbase) + (voff)[_i]), (LAS unsigned*)(lds + (bufoff) + ldsw + _i * 8192), 16, 0, 0); } while (0)
; #define PG8_LDA(dst, b, h) do { _Pragma("unroll") for (int m = 0; m < 4; ++m) _Pragma("unroll") for (int k = 0; k < 2; ++k) dst[m][k] = *(const LAS bf16x8*)(lds + PG8_SA(b, h) + aoff + m * 2048 + k * 1024); } while (0)
; #define PG8_MMA(ai, bj, At, Bt) do { __builtin_amdgcn_s_setprio(1); _Pragma("unroll") for (int m = 0; m < 4; ++m) _Pragma("unroll") for (int n = 0; n < 2; ++n) _Pragma("unroll") for (int k = 0; k < 2; ++k) \
;         acc[ai][bj][m][n] = __builtin_amdgcn_mfma_f32_16x16x32_bf16(Bt[n][k], At[m][k], acc[ai][bj][m][n], 0, 0, 0); __builtin_amdgcn_s_setprio(0); } while (0)
; #define PG8_WAIT_V(n) asm volatile("s_waitcnt vmcnt(" #n ")" ::: "memory")
; #define PG8_WAIT_L(n) asm volatile("s_waitcnt lgkmcnt(" #n ")" ::: "memory")
; #define PG8_BAR __builtin_amdgcn_s_barrier()
; #define PG8_SCHED __builtin_amdgcn_sched_barrier(0)
; template <class Epi>
; __device__ __forceinline__ void gemm_phase(LAS unsigned char* lds, const Gemm g, const StaticOrder& S, const Epi& E, int wave_s) {
;     ...
;             PG8_LDA(At, 1, 1); PG8_STAGE(PG8_SB(1, 0), b3, voffB); PG8_STAGE(PG8_SB(1, 1), b3 + hstepB, voffB); PG8_STAGE(PG8_SA(1, 0), a3, voffA);
;             PG8_WAIT_V(8); PG8_WAIT_L(0); PG8_BAR; PG8_MMA(1, 0, At, B0); PG8_MMA(1, 1, At, B1); PG8_BAR; PG8_SCHED;
;         }
	s_add_i32 s34, s34, s44
	v_lshl_add_u64 v[230:231], v[230:231], 0, s[26:27]
	s_mov_b32 m0, s34
	ds_read_b128 v[198:201], v184 offset:49152
	ds_read_b128 v[202:205], v184 offset:50176
	ds_read_b128 v[206:209], v184 offset:51200
	ds_read_b128 v[210:213], v184 offset:52224
	ds_read_b128 v[214:217], v184 offset:53248
	ds_read_b128 v[218:221], v184 offset:54272
	ds_read_b128 v[222:225], v184 offset:55296
	ds_read_b128 v[226:229], v184 offset:56320
	global_load_lds_dwordx4 v[230:231], off
	s_add_i32 m0, s34, 0x2000
	s_add_u32 s38, s38, 0x80080
	v_lshl_add_u64 v[230:231], v[232:233], 0, s[26:27]
	s_addc_u32 s39, s39, 0
	s_add_i32 s34, s35, s44
	global_load_lds_dwordx4 v[230:231], off
	v_lshl_add_u64 v[230:231], s[38:39], 0, v[150:151]
	s_mov_b32 m0, s34
	s_nop 0
	global_load_lds_dwordx4 v[230:231], off
	v_lshl_add_u64 v[230:231], s[38:39], 0, v[154:155]
	s_add_i32 m0, s34, 0x2000
	s_nop 0
	global_load_lds_dwordx4 v[230:231], off
	v_lshl_add_u64 v[230:231], v[234:235], 0, s[26:27]
	s_mov_b32 m0, s90
	s_nop 0
	global_load_lds_dwordx4 v[230:231], off
	v_lshl_add_u64 v[230:231], v[236:237], 0, s[26:27]
	s_mov_b32 m0, s91
	s_nop 0
	global_load_lds_dwordx4 v[230:231], off
	s_waitcnt vmcnt(8)
	s_waitcnt lgkmcnt(0)
	s_barrier
	s_setprio 1
	s_waitcnt lgkmcnt(0)
	v_mfma_f32_16x16x32_bf16 v[60:63], v[128:131], v[198:201], v[60:63]
	v_mfma_f32_16x16x32_bf16 v[56:59], v[136:139], v[198:201], v[56:59]
	v_mfma_f32_16x16x32_bf16 v[44:47], v[128:131], v[206:209], v[44:47]
	v_mfma_f32_16x16x32_bf16 v[40:43], v[136:139], v[206:209], v[40:43]
	v_mfma_f32_16x16x32_bf16 v[28:31], v[128:131], v[214:217], v[28:31]
	v_mfma_f32_16x16x32_bf16 v[24:27], v[136:139], v[214:217], v[24:27]
	v_mfma_f32_16x16x32_bf16 v[12:15], v[128:131], v[222:225], v[12:15]
	v_mfma_f32_16x16x32_bf16 v[8:11], v[136:139], v[222:225], v[8:11]
	v_mfma_f32_16x16x32_bf16 v[60:63], v[132:135], v[202:205], v[60:63]
	v_mfma_f32_16x16x32_bf16 v[56:59], v[140:143], v[202:205], v[56:59]
	v_mfma_f32_16x16x32_bf16 v[44:47], v[132:135], v[210:213], v[44:47]
	v_mfma_f32_16x16x32_bf16 v[40:43], v[140:143], v[210:213], v[40:43]
	v_mfma_f32_16x16x32_bf16 v[28:31], v[132:135], v[218:221], v[28:31]
	v_mfma_f32_16x16x32_bf16 v[24:27], v[140:143], v[218:221], v[24:27]
	v_mfma_f32_16x16x32_bf16 v[12:15], v[132:135], v[226:229], v[12:15]
	v_mfma_f32_16x16x32_bf16 v[8:11], v[140:143], v[226:229], v[8:11]
	s_setprio 0
	s_setprio 1
	v_mfma_f32_16x16x32_bf16 v[52:55], v[144:147], v[198:201], v[52:55]
	v_mfma_f32_16x16x32_bf16 v[48:51], v[190:193], v[198:201], v[48:51]
	v_mfma_f32_16x16x32_bf16 v[36:39], v[144:147], v[206:209], v[36:39]
	v_mfma_f32_16x16x32_bf16 v[32:35], v[190:193], v[206:209], v[32:35]
	v_mfma_f32_16x16x32_bf16 v[20:23], v[144:147], v[214:217], v[20:23]
	v_mfma_f32_16x16x32_bf16 v[16:19], v[190:193], v[214:217], v[16:19]
	v_mfma_f32_16x16x32_bf16 v[4:7], v[144:147], v[222:225], v[4:7]
	v_mfma_f32_16x16x32_bf16 v[0:3], v[190:193], v[222:225], v[0:3]
	v_mfma_f32_16x16x32_bf16 v[52:55], v[174:177], v[202:205], v[52:55]
	v_mfma_f32_16x16x32_bf16 v[48:51], v[194:197], v[202:205], v[48:51]
	v_mfma_f32_16x16x32_bf16 v[36:39], v[174:177], v[210:213], v[36:39]
	v_mfma_f32_16x16x32_bf16 v[32:35], v[194:197], v[210:213], v[32:35]
	v_mfma_f32_16x16x32_bf16 v[20:23], v[174:177], v[218:221], v[20:23]
	v_mfma_f32_16x16x32_bf16 v[16:19], v[194:197], v[218:221], v[16:19]
	v_mfma_f32_16x16x32_bf16 v[4:7], v[174:177], v[226:229], v[4:7]
	v_mfma_f32_16x16x32_bf16 v[0:3], v[194:197], v[226:229], v[0:3]
	s_setprio 0
	s_add_i32 s50, s50, 2
	s_add_u32 s36, s36, 0x100
	s_addc_u32 s37, s37, 0
	s_add_u32 vcc_lo, vcc_lo, 0x100
	s_addc_u32 vcc_hi, vcc_hi, 0
	s_cmp_gt_u32 s50, 29
	s_barrier
	s_cbranch_scc0 .LBB0_121
	s_and_b64 vcc, exec, s[28:29]
	s_cbranch_vccz .LBB0_125
	s_barrier
	v_lshl_or_b32 v174, s6, 8, v181
	s_cmp_gt_i32 s6, 35
	s_mov_b64 s[36:37], -1
	s_cbranch_scc1 .LBB0_126

; #define PG8_STAGE(bufoff, gbase, voff) do { _Pragma("unroll") for (int _i = 0; _i < 2; ++_i) \
;         __builtin_amdgcn_global_load_lds((const unsigned*)((const char*)(gbase) + (voff)[_i]), (LAS unsigned*)(lds + (bufoff) + ldsw + _i * 8192), 16, 0, 0); } while (0)
; #define PG8_LDA(dst, b, h) do { _Pragma("unroll") for (int m = 0; m < 4; ++m) _Pragma("unroll") for (int k = 0; k < 2; ++k) dst[m][k] = *(const LAS bf16x8*)(lds + PG8_SA(b, h) + aoff + m * 2048 + k * 1024); } while (0)
; #define PG8_LDB(dst, b, h) do { _Pragma("unroll") for (int n = 0; n < 2; ++n) _Pragma("unroll") for (int k = 0; k < 2; ++k) dst[n][k] = *(const LAS bf16x8*)(lds + PG8_SB(b, h) + boff + n * 2048 + k * 1024); } while (0)
; #define PG8_MMA(ai, bj, At, Bt) do { __builtin_amdgcn_s_setprio(1); _Pragma("unroll") for (int m = 0; m < 4; ++m) _Pragma("unroll") for (int n = 0; n < 2; ++n) _Pragma("unroll") for (int k = 0; k < 2; ++k) \
;         acc[ai][bj][m][n] = __builtin_amdgcn_mfma_f32_16x16x32_bf16(Bt[n][k], At[m][k], acc[ai][bj][m][n], 0, 0, 0); __builtin_amdgcn_s_setprio(0); } while (0)
; #define PG8_WAIT_V(n) asm volatile("s_waitcnt vmcnt(" #n ")" ::: "memory")
; #define PG8_WAIT_L(n) asm volatile("s_waitcnt lgkmcnt(" #n ")" ::: "memory")
; #define PG8_BAR __builtin_amdgcn_s_barrier()
; #define PG8_SCHED __builtin_amdgcn_sched_barrier(0)
; template <class Epi>
; __device__ __forceinline__ void gemm_phase(LAS unsigned char* lds, const Gemm g, const StaticOrder& S, const Epi& E, int wave_s) {
;     ...
;             const bool last = (t == nt - 2);
;             const char* a1 = cA + (size_t)(t + 1) * kstep;
;             const char* a2 = last ? nA : cA + (size_t)(t + 2) * kstep; const char* b2 = last ? nB : cB + (size_t)(t + 2) * kstep;
;             const char* a3 = a2 + kstep; const char* b3 = b2 + kstep;
;             PG8_LDB(B0, 0, 0); PG8_LDB(B1, 0, 1); PG8_SCHED; PG8_LDA(At, 0, 0); PG8_STAGE(PG8_SA(1, 1), a1 + hstepA, voffA);
;             PG8_WAIT_V(8); PG8_WAIT_L(0); PG8_BAR; PG8_MMA(0, 0, At, B0); PG8_MMA(0, 1, At, B1); PG8_BAR; PG8_SCHED;
;             PG8_LDA(At, 0, 1); PG8_STAGE(PG8_SB(0, 0), b2, voffB); PG8_STAGE(PG8_SB(0, 1), b2 + hstepB, voffB); PG8_STAGE(PG8_SA(0, 0), a2, voffA);
;             PG8_WAIT_V(8); PG8_WAIT_L(0); PG8_BAR; PG8_MMA(1, 0, At, B0); PG8_MMA(1, 1, At, B1); PG8_BAR; PG8_SCHED;
.LBB0_1016:
	ds_read_b128 v[144:147], v151
	ds_read_b128 v[154:157], v151 offset:1024
	ds_read_b128 v[158:161], v151 offset:2048
	ds_read_b128 v[162:165], v151 offset:3072
	ds_read_b128 v[166:169], v152
	ds_read_b128 v[170:173], v152 offset:1024
	ds_read_b128 v[174:177], v152 offset:2048
	ds_read_b128 v[178:181], v152 offset:3072
	s_add_u32 s44, s42, 0xfffc0080
	s_addc_u32 s45, s43, -1
	s_cmp_eq_u32 s66, 12
	s_cselect_b32 s47, s35, s45
	s_cselect_b32 s46, s62, s44
	s_cselect_b32 s45, s31, s65
	s_cselect_b32 s44, s63, s64
	v_lshl_add_u64 v[214:215], s[42:43], 0, v[136:137]
	s_add_i32 m0, s41, 0xc000
	ds_read_b128 v[182:185], v153
	ds_read_b128 v[186:189], v153 offset:1024
	ds_read_b128 v[190:193], v153 offset:2048
	ds_read_b128 v[194:197], v153 offset:3072
	ds_read_b128 v[198:201], v153 offset:4096
	ds_read_b128 v[202:205], v153 offset:5120
	ds_read_b128 v[206:209], v153 offset:6144
	ds_read_b128 v[210:213], v153 offset:7168
	global_load_lds_dwordx4 v[214:215], off
	v_lshl_add_u64 v[214:215], s[42:43], 0, v[138:139]
	s_add_i32 m0, s41, 0xe000
	s_nop 0
	global_load_lds_dwordx4 v[214:215], off
	s_waitcnt vmcnt(8)
	s_waitcnt lgkmcnt(0)
	s_barrier
	s_setprio 1
	s_waitcnt lgkmcnt(0)
	v_mfma_f32_16x16x32_bf16 v[124:127], v[144:147], v[182:185], v[124:127]
	v_mfma_f32_16x16x32_bf16 v[120:123], v[158:161], v[182:185], v[120:123]
	v_mfma_f32_16x16x32_bf16 v[108:111], v[144:147], v[190:193], v[108:111]
	v_mfma_f32_16x16x32_bf16 v[104:107], v[158:161], v[190:193], v[104:107]
	v_mfma_f32_16x16x32_bf16 v[92:95], v[144:147], v[198:201], v[92:95]
	v_mfma_f32_16x16x32_bf16 v[88:91], v[158:161], v[198:201], v[88:91]
	v_mfma_f32_16x16x32_bf16 v[76:79], v[144:147], v[206:209], v[76:79]
	v_mfma_f32_16x16x32_bf16 v[72:75], v[158:161], v[206:209], v[72:75]
	v_mfma_f32_16x16x32_bf16 v[124:127], v[154:157], v[186:189], v[124:127]
	v_mfma_f32_16x16x32_bf16 v[120:123], v[162:165], v[186:189], v[120:123]
	v_mfma_f32_16x16x32_bf16 v[108:111], v[154:157], v[194:197], v[108:111]
	v_mfma_f32_16x16x32_bf16 v[104:107], v[162:165], v[194:197], v[104:107]
	v_mfma_f32_16x16x32_bf16 v[92:95], v[154:157], v[202:205], v[92:95]
	v_mfma_f32_16x16x32_bf16 v[88:91], v[162:165], v[202:205], v[88:91]
	v_mfma_f32_16x16x32_bf16 v[76:79], v[154:157], v[210:213], v[76:79]
	v_mfma_f32_16x16x32_bf16 v[72:75], v[162:165], v[210:213], v[72:75]
	s_setprio 0
	s_setprio 1
	v_mfma_f32_16x16x32_bf16 v[116:119], v[166:169], v[182:185], v[116:119]
	v_mfma_f32_16x16x32_bf16 v[112:115], v[174:177], v[182:185], v[112:115]
	v_mfma_f32_16x16x32_bf16 v[100:103], v[166:169], v[190:193], v[100:103]
	v_mfma_f32_16x16x32_bf16 v[96:99], v[174:177], v[190:193], v[96:99]
	v_mfma_f32_16x16x32_bf16 v[84:87], v[166:169], v[198:201], v[84:87]
	v_mfma_f32_16x16x32_bf16 v[80:83], v[174:177], v[198:201], v[80:83]
	v_mfma_f32_16x16x32_bf16 v[68:71], v[166:169], v[206:209], v[68:71]
	v_mfma_f32_16x16x32_bf16 v[64:67], v[174:177], v[206:209], v[64:67]
	v_mfma_f32_16x16x32_bf16 v[116:119], v[170:173], v[186:189], v[116:119]
	v_mfma_f32_16x16x32_bf16 v[112:115], v[178:181], v[186:189], v[112:115]
	v_mfma_f32_16x16x32_bf16 v[100:103], v[170:173], v[194:197], v[100:103]
	v_mfma_f32_16x16x32_bf16 v[96:99], v[178:181], v[194:197], v[96:99]
	v_mfma_f32_16x16x32_bf16 v[84:87], v[170:173], v[202:205], v[84:87]
	v_mfma_f32_16x16x32_bf16 v[80:83], v[178:181], v[202:205], v[80:83]
	v_mfma_f32_16x16x32_bf16 v[68:71], v[170:173], v[210:213], v[68:71]
	v_mfma_f32_16x16x32_bf16 v[64:67], v[178:181], v[210:213], v[64:67]
	s_setprio 0
	s_barrier
	s_add_i32 s67, s59, s25
	v_lshl_add_u64 v[214:215], s[44:45], 0, v[130:131]
	s_mov_b32 m0, s67
	ds_read_b128 v[182:185], v153 offset:16384
	ds_read_b128 v[186:189], v153 offset:17408
	ds_read_b128 v[190:193], v153 offset:18432
	ds_read_b128 v[194:197], v153 offset:19456
	ds_read_b128 v[198:201], v153 offset:20480
	ds_read_b128 v[202:205], v153 offset:21504
	ds_read_b128 v[206:209], v153 offset:22528
	ds_read_b128 v[210:213], v153 offset:23552
	global_load_lds_dwordx4 v[214:215], off
	s_add_i32 m0, s67, 0x2000
	s_add_u32 s68, s44, 0x40000
	v_lshl_add_u64 v[216:217], s[44:45], 0, v[134:135]
	s_addc_u32 s69, s45, 0
	s_add_i32 s67, s60, s25
	global_load_lds_dwordx4 v[216:217], off
	v_lshl_add_u64 v[218:219], s[68:69], 0, v[130:131]
	s_mov_b32 m0, s67
	v_lshl_add_u64 v[220:221], s[46:47], 0, v[132:133]
	global_load_lds_dwordx4 v[218:219], off
	v_lshl_add_u64 v[218:219], s[68:69], 0, v[134:135]
	s_add_i32 m0, s67, 0x2000
	s_nop 0
	global_load_lds_dwordx4 v[218:219], off
	v_lshl_add_u64 v[218:219], s[46:47], 0, v[128:129]
	s_mov_b32 m0, s41
	s_nop 0
	global_load_lds_dwordx4 v[218:219], off
	s_mov_b32 m0, s48
	s_nop 0
	global_load_lds_dwordx4 v[220:221], off
	s_waitcnt vmcnt(8)
	s_waitcnt lgkmcnt(0)
	s_barrier
; #define PG8_STAGE(bufoff, gbase, voff) do { _Pragma("unroll") for (int _i = 0; _i < 2; ++_i) \
;         __builtin_amdgcn_global_load_lds((const unsigned*)((const char*)(gbase) + (voff)[_i]), (LAS unsigned*)(lds + (bufoff) + ldsw + _i * 8192), 16, 0, 0); } while (0)
; #define PG8_LDA(dst, b, h) do { _Pragma("unroll") for (int m = 0; m < 4; ++m) _Pragma("unroll") for (int k = 0; k < 2; ++k) dst[m][k] = *(const LAS bf16x8*)(lds + PG8_SA(b, h) + aoff + m * 2048 + k * 1024); } while (0)
; #define PG8_LDB(dst, b, h) do { _Pragma("unroll") for (int n = 0; n < 2; ++n) _Pragma("unroll") for (int k = 0; k < 2; ++k) dst[n][k] = *(const LAS bf16x8*)(lds + PG8_SB(b, h) + boff + n * 2048 + k * 1024); } while (0)
; #define PG8_MMA(ai, bj, At, Bt) do { __builtin_amdgcn_s_setprio(1); _Pragma("unroll") for (int m = 0; m < 4; ++m) _Pragma("unroll") for (int n = 0; n < 2; ++n) _Pragma("unroll") for (int k = 0; k < 2; ++k) \
;         acc[ai][bj][m][n] = __builtin_amdgcn_mfma_f32_16x16x32_bf16(Bt[n][k], At[m][k], acc[ai][bj][m][n], 0, 0, 0); __builtin_amdgcn_s_setprio(0); } while (0)
; #define PG8_WAIT_V(n) asm volatile("s_waitcnt vmcnt(" #n ")" ::: "memory")
; #define PG8_WAIT_L(n) asm volatile("s_waitcnt lgkmcnt(" #n ")" ::: "memory")
; #define PG8_BAR __builtin_amdgcn_s_barrier()
; #define PG8_SCHED __builtin_amdgcn_sched_barrier(0)
; template <class Epi>
; __device__ __forceinline__ void gemm_phase(LAS unsigned char* lds, const Gemm g, const StaticOrder& S, const Epi& E, int wave_s) {
;     ...
;             PG8_WAIT_V(8); PG8_WAIT_L(0); PG8_BAR; PG8_MMA(1, 0, At, B0); PG8_MMA(1, 1, At, B1); PG8_BAR; PG8_SCHED;
;             PG8_LDB(B0, 1, 0); PG8_LDB(B1, 1, 1); PG8_SCHED; PG8_LDA(At, 1, 0); PG8_STAGE(PG8_SA(0, 1), a2 + hstepA, voffA);
;             PG8_WAIT_V(8); PG8_WAIT_L(0); PG8_BAR; PG8_MMA(0, 0, At, B0); PG8_MMA(0, 1, At, B1); PG8_BAR; PG8_SCHED;
	s_setprio 1
	s_waitcnt lgkmcnt(0)
	v_mfma_f32_16x16x32_bf16 v[60:63], v[144:147], v[182:185], v[60:63]
	v_mfma_f32_16x16x32_bf16 v[56:59], v[158:161], v[182:185], v[56:59]
	v_mfma_f32_16x16x32_bf16 v[44:47], v[144:147], v[190:193], v[44:47]
	v_mfma_f32_16x16x32_bf16 v[40:43], v[158:161], v[190:193], v[40:43]
	v_mfma_f32_16x16x32_bf16 v[28:31], v[144:147], v[198:201], v[28:31]
	v_mfma_f32_16x16x32_bf16 v[24:27], v[158:161], v[198:201], v[24:27]
	v_mfma_f32_16x16x32_bf16 v[12:15], v[144:147], v[206:209], v[12:15]
	v_mfma_f32_16x16x32_bf16 v[8:11], v[158:161], v[206:209], v[8:11]
	v_mfma_f32_16x16x32_bf16 v[60:63], v[154:157], v[186:189], v[60:63]
	v_mfma_f32_16x16x32_bf16 v[56:59], v[162:165], v[186:189], v[56:59]
	v_mfma_f32_16x16x32_bf16 v[44:47], v[154:157], v[194:197], v[44:47]
	v_mfma_f32_16x16x32_bf16 v[40:43], v[162:165], v[194:197], v[40:43]
	v_mfma_f32_16x16x32_bf16 v[28:31], v[154:157], v[202:205], v[28:31]
	v_mfma_f32_16x16x32_bf16 v[24:27], v[162:165], v[202:205], v[24:27]
	v_mfma_f32_16x16x32_bf16 v[12:15], v[154:157], v[210:213], v[12:15]
	v_mfma_f32_16x16x32_bf16 v[8:11], v[162:165], v[210:213], v[8:11]
	s_setprio 0
	s_setprio 1
	v_mfma_f32_16x16x32_bf16 v[52:55], v[166:169], v[182:185], v[52:55]
	v_mfma_f32_16x16x32_bf16 v[48:51], v[174:177], v[182:185], v[48:51]
	v_mfma_f32_16x16x32_bf16 v[36:39], v[166:169], v[190:193], v[36:39]
	v_mfma_f32_16x16x32_bf16 v[32:35], v[174:177], v[190:193], v[32:35]
	v_mfma_f32_16x16x32_bf16 v[20:23], v[166:169], v[198:201], v[20:23]
	v_mfma_f32_16x16x32_bf16 v[16:19], v[174:177], v[198:201], v[16:19]
	v_mfma_f32_16x16x32_bf16 v[4:7], v[166:169], v[206:209], v[4:7]
	v_mfma_f32_16x16x32_bf16 v[0:3], v[174:177], v[206:209], v[0:3]
	v_mfma_f32_16x16x32_bf16 v[52:55], v[170:173], v[186:189], v[52:55]
	v_mfma_f32_16x16x32_bf16 v[48:51], v[178:181], v[186:189], v[48:51]
	v_mfma_f32_16x16x32_bf16 v[36:39], v[170:173], v[194:197], v[36:39]
	v_mfma_f32_16x16x32_bf16 v[32:35], v[178:181], v[194:197], v[32:35]
	v_mfma_f32_16x16x32_bf16 v[20:23], v[170:173], v[202:205], v[20:23]
	v_mfma_f32_16x16x32_bf16 v[16:19], v[178:181], v[202:205], v[16:19]
	v_mfma_f32_16x16x32_bf16 v[4:7], v[170:173], v[210:213], v[4:7]
	v_mfma_f32_16x16x32_bf16 v[0:3], v[178:181], v[210:213], v[0:3]
	s_setprio 0
	s_barrier
	s_add_i32 s67, 0, 0x18000
	s_add_i32 s68, 0, 0x1c000
	v_add_u32_e32 v162, s67, v149
	v_add_u32_e32 v178, s68, v149
	ds_read_b128 v[144:147], v162
	ds_read_b128 v[154:157], v162 offset:1024
	ds_read_b128 v[158:161], v162 offset:2048
	ds_read_b128 v[162:165], v162 offset:3072
	ds_read_b128 v[166:169], v178
	ds_read_b128 v[170:173], v178 offset:1024
	ds_read_b128 v[174:177], v178 offset:2048
	ds_read_b128 v[178:181], v178 offset:3072
	s_add_u32 s46, s46, 0x40000
	s_addc_u32 s47, s47, 0
	s_mov_b32 m0, s49
	v_lshl_add_u64 v[222:223], s[46:47], 0, v[128:129]
	ds_read_b128 v[182:185], v153 offset:32768
	ds_read_b128 v[186:189], v153 offset:33792
	ds_read_b128 v[190:193], v153 offset:34816
	ds_read_b128 v[194:197], v153 offset:35840
	ds_read_b128 v[198:201], v153 offset:36864
	ds_read_b128 v[202:205], v153 offset:37888
	ds_read_b128 v[206:209], v153 offset:38912
	ds_read_b128 v[210:213], v153 offset:39936
	global_load_lds_dwordx4 v[222:223], off
	v_lshl_add_u64 v[222:223], s[46:47], 0, v[132:133]
	s_mov_b32 m0, s50
	s_nop 0
	global_load_lds_dwordx4 v[222:223], off
	s_waitcnt vmcnt(8)
	s_waitcnt lgkmcnt(0)
	s_barrier
	s_setprio 1
	s_waitcnt lgkmcnt(0)
	v_mfma_f32_16x16x32_bf16 v[124:127], v[144:147], v[182:185], v[124:127]
	v_mfma_f32_16x16x32_bf16 v[120:123], v[158:161], v[182:185], v[120:123]
	v_mfma_f32_16x16x32_bf16 v[108:111], v[144:147], v[190:193], v[108:111]
	v_mfma_f32_16x16x32_bf16 v[104:107], v[158:161], v[190:193], v[104:107]
	v_mfma_f32_16x16x32_bf16 v[92:95], v[144:147], v[198:201], v[92:95]
	v_mfma_f32_16x16x32_bf16 v[88:91], v[158:161], v[198:201], v[88:91]
	v_mfma_f32_16x16x32_bf16 v[76:79], v[144:147], v[206:209], v[76:79]
	v_mfma_f32_16x16x32_bf16 v[72:75], v[158:161], v[206:209], v[72:75]
	v_mfma_f32_16x16x32_bf16 v[124:127], v[154:157], v[186:189], v[124:127]
	v_mfma_f32_16x16x32_bf16 v[120:123], v[162:165], v[186:189], v[120:123]
	v_mfma_f32_16x16x32_bf16 v[108:111], v[154:157], v[194:197], v[108:111]
	v_mfma_f32_16x16x32_bf16 v[104:107], v[162:165], v[194:197], v[104:107]
	v_mfma_f32_16x16x32_bf16 v[92:95], v[154:157], v[202:205], v[92:95]
	v_mfma_f32_16x16x32_bf16 v[88:91], v[162:165], v[202:205], v[88:91]
	v_mfma_f32_16x16x32_bf16 v[76:79], v[154:157], v[210:213], v[76:79]
	v_mfma_f32_16x16x32_bf16 v[72:75], v[162:165], v[210:213], v[72:75]
	s_setprio 0
	s_setprio 1
	v_mfma_f32_16x16x32_bf16 v[116:119], v[166:169], v[182:185], v[116:119]
	v_mfma_f32_16x16x32_bf16 v[112:115], v[174:177], v[182:185], v[112:115]
	v_mfma_f32_16x16x32_bf16 v[100:103], v[166:169], v[190:193], v[100:103]
	v_mfma_f32_16x16x32_bf16 v[96:99], v[174:177], v[190:193], v[96:99]
	v_mfma_f32_16x16x32_bf16 v[84:87], v[166:169], v[198:201], v[84:87]
	v_mfma_f32_16x16x32_bf16 v[80:83], v[174:177], v[198:201], v[80:83]
	v_mfma_f32_16x16x32_bf16 v[68:71], v[166:169], v[206:209], v[68:71]
	v_mfma_f32_16x16x32_bf16 v[64:67], v[174:177], v[206:209], v[64:67]
	v_mfma_f32_16x16x32_bf16 v[116:119], v[170:173], v[186:189], v[116:119]
	v_mfma_f32_16x16x32_bf16 v[112:115], v[178:181], v[186:189], v[112:115]
	v_mfma_f32_16x16x32_bf16 v[100:103], v[170:173], v[194:197], v[100:103]
	v_mfma_f32_16x16x32_bf16 v[96:99], v[178:181], v[194:197], v[96:99]
	v_mfma_f32_16x16x32_bf16 v[84:87], v[170:173], v[202:205], v[84:87]
	v_mfma_f32_16x16x32_bf16 v[80:83], v[178:181], v[202:205], v[80:83]
	v_mfma_f32_16x16x32_bf16 v[68:71], v[170:173], v[210:213], v[68:71]
	v_mfma_f32_16x16x32_bf16 v[64:67], v[178:181], v[210:213], v[64:67]
	s_setprio 0
	s_barrier
; #define PG8_STAGE(bufoff, gbase, voff) do { _Pragma("unroll") for (int _i = 0; _i < 2; ++_i) \
;         __builtin_amdgcn_global_load_lds((const unsigned*)((const char*)(gbase) + (voff)[_i]), (LAS unsigned*)(lds + (bufoff) + ldsw + _i * 8192), 16, 0, 0); } while (0)
; #define PG8_LDA(dst, b, h) do { _Pragma("unroll") for (int m = 0; m < 4; ++m) _Pragma("unroll") for (int k = 0; k < 2; ++k) dst[m][k] = *(const LAS bf16x8*)(lds + PG8_SA(b, h) + aoff + m * 2048 + k * 1024); } while (0)
; #define PG8_MMA(ai, bj, At, Bt) do { __builtin_amdgcn_s_setprio(1); _Pragma("unroll") for (int m = 0; m < 4; ++m) _Pragma("unroll") for (int n = 0; n < 2; ++n) _Pragma("unroll") for (int k = 0; k < 2; ++k) \
;         acc[ai][bj][m][n] = __builtin_amdgcn_mfma_f32_16x16x32_bf16(Bt[n][k], At[m][k], acc[ai][bj][m][n], 0, 0, 0); __builtin_amdgcn_s_setprio(0); } while (0)
; #define PG8_WAIT_V(n) asm volatile("s_waitcnt vmcnt(" #n ")" ::: "memory")
; #define PG8_WAIT_L(n) asm volatile("s_waitcnt lgkmcnt(" #n ")" ::: "memory")
; #define PG8_BAR __builtin_amdgcn_s_barrier()
; #define PG8_SCHED __builtin_amdgcn_sched_barrier(0)
; template <class Epi>
; __device__ __forceinline__ void gemm_phase(LAS unsigned char* lds, const Gemm g, const StaticOrder& S, const Epi& E, int wave_s) {
;     ...
;             PG8_LDA(At, 1, 1); PG8_STAGE(PG8_SB(1, 0), b3, voffB); PG8_STAGE(PG8_SB(1, 1), b3 + hstepB, voffB); PG8_STAGE(PG8_SA(1, 0), a3, voffA);
;             PG8_WAIT_V(8); PG8_WAIT_L(0); PG8_BAR; PG8_MMA(1, 0, At, B0); PG8_MMA(1, 1, At, B1); PG8_BAR; PG8_SCHED;
;         }
	s_add_i32 s46, s67, s25
	v_lshl_add_u64 v[214:215], v[214:215], 0, s[16:17]
	s_mov_b32 m0, s46
	ds_read_b128 v[182:185], v153 offset:49152
	ds_read_b128 v[186:189], v153 offset:50176
	ds_read_b128 v[190:193], v153 offset:51200
	ds_read_b128 v[194:197], v153 offset:52224
	ds_read_b128 v[198:201], v153 offset:53248
	ds_read_b128 v[202:205], v153 offset:54272
	ds_read_b128 v[206:209], v153 offset:55296
	ds_read_b128 v[210:213], v153 offset:56320
	global_load_lds_dwordx4 v[214:215], off
	s_add_i32 m0, s46, 0x2000
	s_add_u32 s44, s44, 0x40080
	v_lshl_add_u64 v[214:215], v[216:217], 0, s[16:17]
	s_addc_u32 s45, s45, 0
	s_add_i32 s46, s68, s25
	global_load_lds_dwordx4 v[214:215], off
	v_lshl_add_u64 v[214:215], s[44:45], 0, v[130:131]
	s_mov_b32 m0, s46
	s_nop 0
	global_load_lds_dwordx4 v[214:215], off
	v_lshl_add_u64 v[214:215], s[44:45], 0, v[134:135]
	s_add_i32 m0, s46, 0x2000
	s_nop 0
	global_load_lds_dwordx4 v[214:215], off
	v_lshl_add_u64 v[214:215], v[218:219], 0, s[16:17]
	s_mov_b32 m0, s56
	s_nop 0
	global_load_lds_dwordx4 v[214:215], off
	v_lshl_add_u64 v[214:215], v[220:221], 0, s[16:17]
	s_mov_b32 m0, s57
	s_nop 0
	global_load_lds_dwordx4 v[214:215], off
	s_waitcnt vmcnt(8)
	s_waitcnt lgkmcnt(0)
	s_barrier
	s_setprio 1
	s_waitcnt lgkmcnt(0)
	v_mfma_f32_16x16x32_bf16 v[60:63], v[144:147], v[182:185], v[60:63]
	v_mfma_f32_16x16x32_bf16 v[56:59], v[158:161], v[182:185], v[56:59]
	v_mfma_f32_16x16x32_bf16 v[44:47], v[144:147], v[190:193], v[44:47]
	v_mfma_f32_16x16x32_bf16 v[40:43], v[158:161], v[190:193], v[40:43]
	v_mfma_f32_16x16x32_bf16 v[28:31], v[144:147], v[198:201], v[28:31]
	v_mfma_f32_16x16x32_bf16 v[24:27], v[158:161], v[198:201], v[24:27]
	v_mfma_f32_16x16x32_bf16 v[12:15], v[144:147], v[206:209], v[12:15]
	v_mfma_f32_16x16x32_bf16 v[8:11], v[158:161], v[206:209], v[8:11]
	v_mfma_f32_16x16x32_bf16 v[60:63], v[154:157], v[186:189], v[60:63]
	v_mfma_f32_16x16x32_bf16 v[56:59], v[162:165], v[186:189], v[56:59]
	v_mfma_f32_16x16x32_bf16 v[44:47], v[154:157], v[194:197], v[44:47]
	v_mfma_f32_16x16x32_bf16 v[40:43], v[162:165], v[194:197], v[40:43]
	v_mfma_f32_16x16x32_bf16 v[28:31], v[154:157], v[202:205], v[28:31]
	v_mfma_f32_16x16x32_bf16 v[24:27], v[162:165], v[202:205], v[24:27]
	v_mfma_f32_16x16x32_bf16 v[12:15], v[154:157], v[210:213], v[12:15]
	v_mfma_f32_16x16x32_bf16 v[8:11], v[162:165], v[210:213], v[8:11]
	s_setprio 0
	s_setprio 1
	v_mfma_f32_16x16x32_bf16 v[52:55], v[166:169], v[182:185], v[52:55]
	v_mfma_f32_16x16x32_bf16 v[48:51], v[174:177], v[182:185], v[48:51]
	v_mfma_f32_16x16x32_bf16 v[36:39], v[166:169], v[190:193], v[36:39]
	v_mfma_f32_16x16x32_bf16 v[32:35], v[174:177], v[190:193], v[32:35]
	v_mfma_f32_16x16x32_bf16 v[20:23], v[166:169], v[198:201], v[20:23]
	v_mfma_f32_16x16x32_bf16 v[16:19], v[174:177], v[198:201], v[16:19]
	v_mfma_f32_16x16x32_bf16 v[4:7], v[166:169], v[206:209], v[4:7]
	v_mfma_f32_16x16x32_bf16 v[0:3], v[174:177], v[206:209], v[0:3]
	v_mfma_f32_16x16x32_bf16 v[52:55], v[170:173], v[186:189], v[52:55]
	v_mfma_f32_16x16x32_bf16 v[48:51], v[178:181], v[186:189], v[48:51]
	v_mfma_f32_16x16x32_bf16 v[36:39], v[170:173], v[194:197], v[36:39]
	v_mfma_f32_16x16x32_bf16 v[32:35], v[178:181], v[194:197], v[32:35]
	v_mfma_f32_16x16x32_bf16 v[20:23], v[170:173], v[202:205], v[20:23]
	v_mfma_f32_16x16x32_bf16 v[16:19], v[178:181], v[202:205], v[16:19]
	v_mfma_f32_16x16x32_bf16 v[4:7], v[170:173], v[210:213], v[4:7]
	v_mfma_f32_16x16x32_bf16 v[0:3], v[178:181], v[210:213], v[0:3]
	s_setprio 0
	s_add_i32 s66, s66, 2
	s_add_u32 s42, s42, 0x100
	s_addc_u32 s43, s43, 0
	s_add_u32 s64, s64, 0x100
	s_addc_u32 s65, s65, 0
	s_cmp_gt_u32 s66, 13
	s_barrier
	s_cbranch_scc0 .LBB0_1016
	s_and_b64 vcc, exec, s[26:27]
	s_cbranch_vccz .LBB0_1019
	s_barrier

; #define PG8_STAGE(bufoff, gbase, voff) do { _Pragma("unroll") for (int _i = 0; _i < 2; ++_i) \
;         __builtin_amdgcn_global_load_lds((const unsigned*)((const char*)(gbase) + (voff)[_i]), (LAS unsigned*)(lds + (bufoff) + ldsw + _i * 8192), 16, 0, 0); } while (0)
; #define PG8_LDA(dst, b, h) do { _Pragma("unroll") for (int m = 0; m < 4; ++m) _Pragma("unroll") for (int k = 0; k < 2; ++k) dst[m][k] = *(const LAS bf16x8*)(lds + PG8_SA(b, h) + aoff + m * 2048 + k * 1024); } while (0)
; #define PG8_LDB(dst, b, h) do { _Pragma("unroll") for (int n = 0; n < 2; ++n) _Pragma("unroll") for (int k = 0; k < 2; ++k) dst[n][k] = *(const LAS bf16x8*)(lds + PG8_SB(b, h) + boff + n * 2048 + k * 1024); } while (0)
; #define PG8_MMA(ai, bj, At, Bt) do { __builtin_amdgcn_s_setprio(1); _Pragma("unroll") for (int m = 0; m < 4; ++m) _Pragma("unroll") for (int n = 0; n < 2; ++n) _Pragma("unroll") for (int k = 0; k < 2; ++k) \
;         acc[ai][bj][m][n] = __builtin_amdgcn_mfma_f32_16x16x32_bf16(Bt[n][k], At[m][k], acc[ai][bj][m][n], 0, 0, 0); __builtin_amdgcn_s_setprio(0); } while (0)
; #define PG8_WAIT_V(n) asm volatile("s_waitcnt vmcnt(" #n ")" ::: "memory")
; #define PG8_WAIT_L(n) asm volatile("s_waitcnt lgkmcnt(" #n ")" ::: "memory")
; #define PG8_BAR __builtin_amdgcn_s_barrier()
; #define PG8_SCHED __builtin_amdgcn_sched_barrier(0)
; template <class Epi>
; __device__ __forceinline__ void gemm_phase(LAS unsigned char* lds, const Gemm g, const StaticOrder& S, const Epi& E, int wave_s) {
;     ...
;             const bool last = (t == nt - 2);
;             const char* a1 = cA + (size_t)(t + 1) * kstep;
;             const char* a2 = last ? nA : cA + (size_t)(t + 2) * kstep; const char* b2 = last ? nB : cB + (size_t)(t + 2) * kstep;
;             const char* a3 = a2 + kstep; const char* b3 = b2 + kstep;
;             PG8_LDB(B0, 0, 0); PG8_LDB(B1, 0, 1); PG8_SCHED; PG8_LDA(At, 0, 0); PG8_STAGE(PG8_SA(1, 1), a1 + hstepA, voffA);
;             PG8_WAIT_V(8); PG8_WAIT_L(0); PG8_BAR; PG8_MMA(0, 0, At, B0); PG8_MMA(0, 1, At, B1); PG8_BAR; PG8_SCHED;
;             PG8_LDA(At, 0, 1); PG8_STAGE(PG8_SB(0, 0), b2, voffB); PG8_STAGE(PG8_SB(0, 1), b2 + hstepB, voffB); PG8_STAGE(PG8_SA(0, 0), a2, voffA);
;             PG8_WAIT_V(8); PG8_WAIT_L(0); PG8_BAR; PG8_MMA(1, 0, At, B0); PG8_MMA(1, 1, At, B1); PG8_BAR; PG8_SCHED;
.LBB0_1040:
	ds_read_b128 v[144:147], v151
	ds_read_b128 v[154:157], v151 offset:1024
	ds_read_b128 v[158:161], v151 offset:2048
	ds_read_b128 v[162:165], v151 offset:3072
	ds_read_b128 v[166:169], v152
	ds_read_b128 v[170:173], v152 offset:1024
	ds_read_b128 v[174:177], v152 offset:2048
	ds_read_b128 v[178:181], v152 offset:3072
	s_add_u32 s50, s48, 0xfff80080
	s_addc_u32 s51, s49, -1
	s_cmp_eq_u32 s73, 28
	s_cselect_b32 s57, s41, s51
	s_cselect_b32 s56, s69, s50
	s_cselect_b32 s51, s39, s72
	s_cselect_b32 s50, s70, s71
	v_lshl_add_u64 v[214:215], s[48:49], 0, v[136:137]
	s_add_i32 m0, s47, 0xc000
	ds_read_b128 v[182:185], v153
	ds_read_b128 v[186:189], v153 offset:1024
	ds_read_b128 v[190:193], v153 offset:2048
	ds_read_b128 v[194:197], v153 offset:3072
	ds_read_b128 v[198:201], v153 offset:4096
	ds_read_b128 v[202:205], v153 offset:5120
	ds_read_b128 v[206:209], v153 offset:6144
	ds_read_b128 v[210:213], v153 offset:7168
	global_load_lds_dwordx4 v[214:215], off
	v_lshl_add_u64 v[214:215], s[48:49], 0, v[138:139]
	s_add_i32 m0, s47, 0xe000
	s_nop 0
	global_load_lds_dwordx4 v[214:215], off
	s_waitcnt vmcnt(8)
	s_waitcnt lgkmcnt(0)
	s_barrier
	s_setprio 1
	s_waitcnt lgkmcnt(0)
	v_mfma_f32_16x16x32_bf16 v[124:127], v[144:147], v[182:185], v[124:127]
	v_mfma_f32_16x16x32_bf16 v[120:123], v[158:161], v[182:185], v[120:123]
	v_mfma_f32_16x16x32_bf16 v[108:111], v[144:147], v[190:193], v[108:111]
	v_mfma_f32_16x16x32_bf16 v[104:107], v[158:161], v[190:193], v[104:107]
	v_mfma_f32_16x16x32_bf16 v[92:95], v[144:147], v[198:201], v[92:95]
	v_mfma_f32_16x16x32_bf16 v[88:91], v[158:161], v[198:201], v[88:91]
	v_mfma_f32_16x16x32_bf16 v[76:79], v[144:147], v[206:209], v[76:79]
	v_mfma_f32_16x16x32_bf16 v[72:75], v[158:161], v[206:209], v[72:75]
	v_mfma_f32_16x16x32_bf16 v[124:127], v[154:157], v[186:189], v[124:127]
	v_mfma_f32_16x16x32_bf16 v[120:123], v[162:165], v[186:189], v[120:123]
	v_mfma_f32_16x16x32_bf16 v[108:111], v[154:157], v[194:197], v[108:111]
	v_mfma_f32_16x16x32_bf16 v[104:107], v[162:165], v[194:197], v[104:107]
	v_mfma_f32_16x16x32_bf16 v[92:95], v[154:157], v[202:205], v[92:95]
	v_mfma_f32_16x16x32_bf16 v[88:91], v[162:165], v[202:205], v[88:91]
	v_mfma_f32_16x16x32_bf16 v[76:79], v[154:157], v[210:213], v[76:79]
	v_mfma_f32_16x16x32_bf16 v[72:75], v[162:165], v[210:213], v[72:75]
	s_setprio 0
	s_setprio 1
	v_mfma_f32_16x16x32_bf16 v[116:119], v[166:169], v[182:185], v[116:119]
	v_mfma_f32_16x16x32_bf16 v[112:115], v[174:177], v[182:185], v[112:115]
	v_mfma_f32_16x16x32_bf16 v[100:103], v[166:169], v[190:193], v[100:103]
	v_mfma_f32_16x16x32_bf16 v[96:99], v[174:177], v[190:193], v[96:99]
	v_mfma_f32_16x16x32_bf16 v[84:87], v[166:169], v[198:201], v[84:87]
	v_mfma_f32_16x16x32_bf16 v[80:83], v[174:177], v[198:201], v[80:83]
	v_mfma_f32_16x16x32_bf16 v[68:71], v[166:169], v[206:209], v[68:71]
	v_mfma_f32_16x16x32_bf16 v[64:67], v[174:177], v[206:209], v[64:67]
	v_mfma_f32_16x16x32_bf16 v[116:119], v[170:173], v[186:189], v[116:119]
	v_mfma_f32_16x16x32_bf16 v[112:115], v[178:181], v[186:189], v[112:115]
	v_mfma_f32_16x16x32_bf16 v[100:103], v[170:173], v[194:197], v[100:103]
	v_mfma_f32_16x16x32_bf16 v[96:99], v[178:181], v[194:197], v[96:99]
	v_mfma_f32_16x16x32_bf16 v[84:87], v[170:173], v[202:205], v[84:87]
	v_mfma_f32_16x16x32_bf16 v[80:83], v[178:181], v[202:205], v[80:83]
	v_mfma_f32_16x16x32_bf16 v[68:71], v[170:173], v[210:213], v[68:71]
	v_mfma_f32_16x16x32_bf16 v[64:67], v[178:181], v[210:213], v[64:67]
	s_setprio 0
	s_barrier
	s_add_i32 s74, s65, s25
	v_lshl_add_u64 v[214:215], s[50:51], 0, v[130:131]
	s_mov_b32 m0, s74
	ds_read_b128 v[182:185], v153 offset:16384
	ds_read_b128 v[186:189], v153 offset:17408
	ds_read_b128 v[190:193], v153 offset:18432
	ds_read_b128 v[194:197], v153 offset:19456
	ds_read_b128 v[198:201], v153 offset:20480
	ds_read_b128 v[202:205], v153 offset:21504
	ds_read_b128 v[206:209], v153 offset:22528
	ds_read_b128 v[210:213], v153 offset:23552
	global_load_lds_dwordx4 v[214:215], off
	s_add_i32 m0, s74, 0x2000
	s_add_u32 s74, s50, 0x80000
	v_lshl_add_u64 v[216:217], s[50:51], 0, v[134:135]
	s_addc_u32 s75, s51, 0
	s_add_i32 s76, s66, s25
	global_load_lds_dwordx4 v[216:217], off
	v_lshl_add_u64 v[218:219], s[74:75], 0, v[130:131]
	s_mov_b32 m0, s76
	v_lshl_add_u64 v[220:221], s[56:57], 0, v[132:133]
	global_load_lds_dwordx4 v[218:219], off
	v_lshl_add_u64 v[218:219], s[74:75], 0, v[134:135]
	s_add_i32 m0, s76, 0x2000
	s_nop 0
	global_load_lds_dwordx4 v[218:219], off
	v_lshl_add_u64 v[218:219], s[56:57], 0, v[128:129]
	s_mov_b32 m0, s47
	s_nop 0
	global_load_lds_dwordx4 v[218:219], off
	s_mov_b32 m0, s58
	s_nop 0
	global_load_lds_dwordx4 v[220:221], off
	s_waitcnt vmcnt(8)
	s_waitcnt lgkmcnt(0)
	s_barrier
; #define PG8_STAGE(bufoff, gbase, voff) do { _Pragma("unroll") for (int _i = 0; _i < 2; ++_i) \
;         __builtin_amdgcn_global_load_lds((const unsigned*)((const char*)(gbase) + (voff)[_i]), (LAS unsigned*)(lds + (bufoff) + ldsw + _i * 8192), 16, 0, 0); } while (0)
; #define PG8_LDA(dst, b, h) do { _Pragma("unroll") for (int m = 0; m < 4; ++m) _Pragma("unroll") for (int k = 0; k < 2; ++k) dst[m][k] = *(const LAS bf16x8*)(lds + PG8_SA(b, h) + aoff + m * 2048 + k * 1024); } while (0)
; #define PG8_LDB(dst, b, h) do { _Pragma("unroll") for (int n = 0; n < 2; ++n) _Pragma("unroll") for (int k = 0; k < 2; ++k) dst[n][k] = *(const LAS bf16x8*)(lds + PG8_SB(b, h) + boff + n * 2048 + k * 1024); } while (0)
; #define PG8_MMA(ai, bj, At, Bt) do { __builtin_amdgcn_s_setprio(1); _Pragma("unroll") for (int m = 0; m < 4; ++m) _Pragma("unroll") for (int n = 0; n < 2; ++n) _Pragma("unroll") for (int k = 0; k < 2; ++k) \
;         acc[ai][bj][m][n] = __builtin_amdgcn_mfma_f32_16x16x32_bf16(Bt[n][k], At[m][k], acc[ai][bj][m][n], 0, 0, 0); __builtin_amdgcn_s_setprio(0); } while (0)
; #define PG8_WAIT_V(n) asm volatile("s_waitcnt vmcnt(" #n ")" ::: "memory")
; #define PG8_WAIT_L(n) asm volatile("s_waitcnt lgkmcnt(" #n ")" ::: "memory")
; #define PG8_BAR __builtin_amdgcn_s_barrier()
; #define PG8_SCHED __builtin_amdgcn_sched_barrier(0)
; template <class Epi>
; __device__ __forceinline__ void gemm_phase(LAS unsigned char* lds, const Gemm g, const StaticOrder& S, const Epi& E, int wave_s) {
;     ...
;             PG8_WAIT_V(8); PG8_WAIT_L(0); PG8_BAR; PG8_MMA(1, 0, At, B0); PG8_MMA(1, 1, At, B1); PG8_BAR; PG8_SCHED;
;             PG8_LDB(B0, 1, 0); PG8_LDB(B1, 1, 1); PG8_SCHED; PG8_LDA(At, 1, 0); PG8_STAGE(PG8_SA(0, 1), a2 + hstepA, voffA);
;             PG8_WAIT_V(8); PG8_WAIT_L(0); PG8_BAR; PG8_MMA(0, 0, At, B0); PG8_MMA(0, 1, At, B1); PG8_BAR; PG8_SCHED;
	s_setprio 1
	s_waitcnt lgkmcnt(0)
	v_mfma_f32_16x16x32_bf16 v[60:63], v[144:147], v[182:185], v[60:63]
	v_mfma_f32_16x16x32_bf16 v[56:59], v[158:161], v[182:185], v[56:59]
	v_mfma_f32_16x16x32_bf16 v[44:47], v[144:147], v[190:193], v[44:47]
	v_mfma_f32_16x16x32_bf16 v[40:43], v[158:161], v[190:193], v[40:43]
	v_mfma_f32_16x16x32_bf16 v[28:31], v[144:147], v[198:201], v[28:31]
	v_mfma_f32_16x16x32_bf16 v[24:27], v[158:161], v[198:201], v[24:27]
	v_mfma_f32_16x16x32_bf16 v[12:15], v[144:147], v[206:209], v[12:15]
	v_mfma_f32_16x16x32_bf16 v[8:11], v[158:161], v[206:209], v[8:11]
	v_mfma_f32_16x16x32_bf16 v[60:63], v[154:157], v[186:189], v[60:63]
	v_mfma_f32_16x16x32_bf16 v[56:59], v[162:165], v[186:189], v[56:59]
	v_mfma_f32_16x16x32_bf16 v[44:47], v[154:157], v[194:197], v[44:47]
	v_mfma_f32_16x16x32_bf16 v[40:43], v[162:165], v[194:197], v[40:43]
	v_mfma_f32_16x16x32_bf16 v[28:31], v[154:157], v[202:205], v[28:31]
	v_mfma_f32_16x16x32_bf16 v[24:27], v[162:165], v[202:205], v[24:27]
	v_mfma_f32_16x16x32_bf16 v[12:15], v[154:157], v[210:213], v[12:15]
	v_mfma_f32_16x16x32_bf16 v[8:11], v[162:165], v[210:213], v[8:11]
	s_setprio 0
	s_setprio 1
	v_mfma_f32_16x16x32_bf16 v[52:55], v[166:169], v[182:185], v[52:55]
	v_mfma_f32_16x16x32_bf16 v[48:51], v[174:177], v[182:185], v[48:51]
	v_mfma_f32_16x16x32_bf16 v[36:39], v[166:169], v[190:193], v[36:39]
	v_mfma_f32_16x16x32_bf16 v[32:35], v[174:177], v[190:193], v[32:35]
	v_mfma_f32_16x16x32_bf16 v[20:23], v[166:169], v[198:201], v[20:23]
	v_mfma_f32_16x16x32_bf16 v[16:19], v[174:177], v[198:201], v[16:19]
	v_mfma_f32_16x16x32_bf16 v[4:7], v[166:169], v[206:209], v[4:7]
	v_mfma_f32_16x16x32_bf16 v[0:3], v[174:177], v[206:209], v[0:3]
	v_mfma_f32_16x16x32_bf16 v[52:55], v[170:173], v[186:189], v[52:55]
	v_mfma_f32_16x16x32_bf16 v[48:51], v[178:181], v[186:189], v[48:51]
	v_mfma_f32_16x16x32_bf16 v[36:39], v[170:173], v[194:197], v[36:39]
	v_mfma_f32_16x16x32_bf16 v[32:35], v[178:181], v[194:197], v[32:35]
	v_mfma_f32_16x16x32_bf16 v[20:23], v[170:173], v[202:205], v[20:23]
	v_mfma_f32_16x16x32_bf16 v[16:19], v[178:181], v[202:205], v[16:19]
	v_mfma_f32_16x16x32_bf16 v[4:7], v[170:173], v[210:213], v[4:7]
	v_mfma_f32_16x16x32_bf16 v[0:3], v[178:181], v[210:213], v[0:3]
	s_setprio 0
	s_barrier
	s_add_i32 s74, 0, 0x18000
	s_add_i32 s75, 0, 0x1c000
	v_add_u32_e32 v162, s74, v149
	v_add_u32_e32 v178, s75, v149
	ds_read_b128 v[144:147], v162
	ds_read_b128 v[154:157], v162 offset:1024
	ds_read_b128 v[158:161], v162 offset:2048
	ds_read_b128 v[162:165], v162 offset:3072
	ds_read_b128 v[166:169], v178
	ds_read_b128 v[170:173], v178 offset:1024
	ds_read_b128 v[174:177], v178 offset:2048
	ds_read_b128 v[178:181], v178 offset:3072
	s_add_u32 s56, s56, 0x80000
	s_addc_u32 s57, s57, 0
	s_mov_b32 m0, s59
	v_lshl_add_u64 v[222:223], s[56:57], 0, v[128:129]
	ds_read_b128 v[182:185], v153 offset:32768
	ds_read_b128 v[186:189], v153 offset:33792
	ds_read_b128 v[190:193], v153 offset:34816
	ds_read_b128 v[194:197], v153 offset:35840
	ds_read_b128 v[198:201], v153 offset:36864
	ds_read_b128 v[202:205], v153 offset:37888
	ds_read_b128 v[206:209], v153 offset:38912
	ds_read_b128 v[210:213], v153 offset:39936
	global_load_lds_dwordx4 v[222:223], off
	v_lshl_add_u64 v[222:223], s[56:57], 0, v[132:133]
	s_mov_b32 m0, s60
	s_nop 0
	global_load_lds_dwordx4 v[222:223], off
	s_waitcnt vmcnt(8)
	s_waitcnt lgkmcnt(0)
	s_barrier
	s_setprio 1
	s_waitcnt lgkmcnt(0)
	v_mfma_f32_16x16x32_bf16 v[124:127], v[144:147], v[182:185], v[124:127]
	v_mfma_f32_16x16x32_bf16 v[120:123], v[158:161], v[182:185], v[120:123]
	v_mfma_f32_16x16x32_bf16 v[108:111], v[144:147], v[190:193], v[108:111]
	v_mfma_f32_16x16x32_bf16 v[104:107], v[158:161], v[190:193], v[104:107]
	v_mfma_f32_16x16x32_bf16 v[92:95], v[144:147], v[198:201], v[92:95]
	v_mfma_f32_16x16x32_bf16 v[88:91], v[158:161], v[198:201], v[88:91]
	v_mfma_f32_16x16x32_bf16 v[76:79], v[144:147], v[206:209], v[76:79]
	v_mfma_f32_16x16x32_bf16 v[72:75], v[158:161], v[206:209], v[72:75]
	v_mfma_f32_16x16x32_bf16 v[124:127], v[154:157], v[186:189], v[124:127]
	v_mfma_f32_16x16x32_bf16 v[120:123], v[162:165], v[186:189], v[120:123]
	v_mfma_f32_16x16x32_bf16 v[108:111], v[154:157], v[194:197], v[108:111]
	v_mfma_f32_16x16x32_bf16 v[104:107], v[162:165], v[194:197], v[104:107]
	v_mfma_f32_16x16x32_bf16 v[92:95], v[154:157], v[202:205], v[92:95]
	v_mfma_f32_16x16x32_bf16 v[88:91], v[162:165], v[202:205], v[88:91]
	v_mfma_f32_16x16x32_bf16 v[76:79], v[154:157], v[210:213], v[76:79]
	v_mfma_f32_16x16x32_bf16 v[72:75], v[162:165], v[210:213], v[72:75]
	s_setprio 0
	s_setprio 1
	v_mfma_f32_16x16x32_bf16 v[116:119], v[166:169], v[182:185], v[116:119]
	v_mfma_f32_16x16x32_bf16 v[112:115], v[174:177], v[182:185], v[112:115]
	v_mfma_f32_16x16x32_bf16 v[100:103], v[166:169], v[190:193], v[100:103]
	v_mfma_f32_16x16x32_bf16 v[96:99], v[174:177], v[190:193], v[96:99]
	v_mfma_f32_16x16x32_bf16 v[84:87], v[166:169], v[198:201], v[84:87]
	v_mfma_f32_16x16x32_bf16 v[80:83], v[174:177], v[198:201], v[80:83]
	v_mfma_f32_16x16x32_bf16 v[68:71], v[166:169], v[206:209], v[68:71]
	v_mfma_f32_16x16x32_bf16 v[64:67], v[174:177], v[206:209], v[64:67]
	v_mfma_f32_16x16x32_bf16 v[116:119], v[170:173], v[186:189], v[116:119]
	v_mfma_f32_16x16x32_bf16 v[112:115], v[178:181], v[186:189], v[112:115]
	v_mfma_f32_16x16x32_bf16 v[100:103], v[170:173], v[194:197], v[100:103]
	v_mfma_f32_16x16x32_bf16 v[96:99], v[178:181], v[194:197], v[96:99]
	v_mfma_f32_16x16x32_bf16 v[84:87], v[170:173], v[202:205], v[84:87]
	v_mfma_f32_16x16x32_bf16 v[80:83], v[178:181], v[202:205], v[80:83]
	v_mfma_f32_16x16x32_bf16 v[68:71], v[170:173], v[210:213], v[68:71]
	v_mfma_f32_16x16x32_bf16 v[64:67], v[178:181], v[210:213], v[64:67]
	s_setprio 0
	s_barrier
; #define PG8_STAGE(bufoff, gbase, voff) do { _Pragma("unroll") for (int _i = 0; _i < 2; ++_i) \
;         __builtin_amdgcn_global_load_lds((const unsigned*)((const char*)(gbase) + (voff)[_i]), (LAS unsigned*)(lds + (bufoff) + ldsw + _i * 8192), 16, 0, 0); } while (0)
; #define PG8_LDA(dst, b, h) do { _Pragma("unroll") for (int m = 0; m < 4; ++m) _Pragma("unroll") for (int k = 0; k < 2; ++k) dst[m][k] = *(const LAS bf16x8*)(lds + PG8_SA(b, h) + aoff + m * 2048 + k * 1024); } while (0)
; #define PG8_MMA(ai, bj, At, Bt) do { __builtin_amdgcn_s_setprio(1); _Pragma("unroll") for (int m = 0; m < 4; ++m) _Pragma("unroll") for (int n = 0; n < 2; ++n) _Pragma("unroll") for (int k = 0; k < 2; ++k) \
;         acc[ai][bj][m][n] = __builtin_amdgcn_mfma_f32_16x16x32_bf16(Bt[n][k], At[m][k], acc[ai][bj][m][n], 0, 0, 0); __builtin_amdgcn_s_setprio(0); } while (0)
; #define PG8_WAIT_V(n) asm volatile("s_waitcnt vmcnt(" #n ")" ::: "memory")
; #define PG8_WAIT_L(n) asm volatile("s_waitcnt lgkmcnt(" #n ")" ::: "memory")
; #define PG8_BAR __builtin_amdgcn_s_barrier()
; #define PG8_SCHED __builtin_amdgcn_sched_barrier(0)
; template <class Epi>
; __device__ __forceinline__ void gemm_phase(LAS unsigned char* lds, const Gemm g, const StaticOrder& S, const Epi& E, int wave_s) {
;     ...
;             PG8_LDA(At, 1, 1); PG8_STAGE(PG8_SB(1, 0), b3, voffB); PG8_STAGE(PG8_SB(1, 1), b3 + hstepB, voffB); PG8_STAGE(PG8_SA(1, 0), a3, voffA);
;             PG8_WAIT_V(8); PG8_WAIT_L(0); PG8_BAR; PG8_MMA(1, 0, At, B0); PG8_MMA(1, 1, At, B1); PG8_BAR; PG8_SCHED;
;         }
	s_add_i32 s56, s74, s25
	v_lshl_add_u64 v[214:215], v[214:215], 0, s[30:31]
	s_mov_b32 m0, s56
	ds_read_b128 v[182:185], v153 offset:49152
	ds_read_b128 v[186:189], v153 offset:50176
	ds_read_b128 v[190:193], v153 offset:51200
	ds_read_b128 v[194:197], v153 offset:52224
	ds_read_b128 v[198:201], v153 offset:53248
	ds_read_b128 v[202:205], v153 offset:54272
	ds_read_b128 v[206:209], v153 offset:55296
	ds_read_b128 v[210:213], v153 offset:56320
	global_load_lds_dwordx4 v[214:215], off
	s_add_i32 m0, s56, 0x2000
	s_add_u32 s50, s50, 0x80080
	v_lshl_add_u64 v[214:215], v[216:217], 0, s[30:31]
	s_addc_u32 s51, s51, 0
	s_add_i32 s56, s75, s25
	global_load_lds_dwordx4 v[214:215], off
	v_lshl_add_u64 v[214:215], s[50:51], 0, v[130:131]
	s_mov_b32 m0, s56
	s_nop 0
	global_load_lds_dwordx4 v[214:215], off
	v_lshl_add_u64 v[214:215], s[50:51], 0, v[134:135]
	s_add_i32 m0, s56, 0x2000
	s_nop 0
	global_load_lds_dwordx4 v[214:215], off
	v_lshl_add_u64 v[214:215], v[218:219], 0, s[30:31]
	s_mov_b32 m0, s62
	s_nop 0
	global_load_lds_dwordx4 v[214:215], off
	v_lshl_add_u64 v[214:215], v[220:221], 0, s[30:31]
	s_mov_b32 m0, s63
	s_nop 0
	global_load_lds_dwordx4 v[214:215], off
	s_waitcnt vmcnt(8)
	s_waitcnt lgkmcnt(0)
	s_barrier
	s_setprio 1
	s_waitcnt lgkmcnt(0)
	v_mfma_f32_16x16x32_bf16 v[60:63], v[144:147], v[182:185], v[60:63]
	v_mfma_f32_16x16x32_bf16 v[56:59], v[158:161], v[182:185], v[56:59]
	v_mfma_f32_16x16x32_bf16 v[44:47], v[144:147], v[190:193], v[44:47]
	v_mfma_f32_16x16x32_bf16 v[40:43], v[158:161], v[190:193], v[40:43]
	v_mfma_f32_16x16x32_bf16 v[28:31], v[144:147], v[198:201], v[28:31]
	v_mfma_f32_16x16x32_bf16 v[24:27], v[158:161], v[198:201], v[24:27]
	v_mfma_f32_16x16x32_bf16 v[12:15], v[144:147], v[206:209], v[12:15]
	v_mfma_f32_16x16x32_bf16 v[8:11], v[158:161], v[206:209], v[8:11]
	v_mfma_f32_16x16x32_bf16 v[60:63], v[154:157], v[186:189], v[60:63]
	v_mfma_f32_16x16x32_bf16 v[56:59], v[162:165], v[186:189], v[56:59]
	v_mfma_f32_16x16x32_bf16 v[44:47], v[154:157], v[194:197], v[44:47]
	v_mfma_f32_16x16x32_bf16 v[40:43], v[162:165], v[194:197], v[40:43]
	v_mfma_f32_16x16x32_bf16 v[28:31], v[154:157], v[202:205], v[28:31]
	v_mfma_f32_16x16x32_bf16 v[24:27], v[162:165], v[202:205], v[24:27]
	v_mfma_f32_16x16x32_bf16 v[12:15], v[154:157], v[210:213], v[12:15]
	v_mfma_f32_16x16x32_bf16 v[8:11], v[162:165], v[210:213], v[8:11]
	s_setprio 0
	s_setprio 1
	v_mfma_f32_16x16x32_bf16 v[52:55], v[166:169], v[182:185], v[52:55]
	v_mfma_f32_16x16x32_bf16 v[48:51], v[174:177], v[182:185], v[48:51]
	v_mfma_f32_16x16x32_bf16 v[36:39], v[166:169], v[190:193], v[36:39]
	v_mfma_f32_16x16x32_bf16 v[32:35], v[174:177], v[190:193], v[32:35]
	v_mfma_f32_16x16x32_bf16 v[20:23], v[166:169], v[198:201], v[20:23]
	v_mfma_f32_16x16x32_bf16 v[16:19], v[174:177], v[198:201], v[16:19]
	v_mfma_f32_16x16x32_bf16 v[4:7], v[166:169], v[206:209], v[4:7]
	v_mfma_f32_16x16x32_bf16 v[0:3], v[174:177], v[206:209], v[0:3]
	v_mfma_f32_16x16x32_bf16 v[52:55], v[170:173], v[186:189], v[52:55]
	v_mfma_f32_16x16x32_bf16 v[48:51], v[178:181], v[186:189], v[48:51]
	v_mfma_f32_16x16x32_bf16 v[36:39], v[170:173], v[194:197], v[36:39]
	v_mfma_f32_16x16x32_bf16 v[32:35], v[178:181], v[194:197], v[32:35]
	v_mfma_f32_16x16x32_bf16 v[20:23], v[170:173], v[202:205], v[20:23]
	v_mfma_f32_16x16x32_bf16 v[16:19], v[178:181], v[202:205], v[16:19]
	v_mfma_f32_16x16x32_bf16 v[4:7], v[170:173], v[210:213], v[4:7]
	v_mfma_f32_16x16x32_bf16 v[0:3], v[178:181], v[210:213], v[0:3]
	s_setprio 0
	s_add_i32 s73, s73, 2
	s_add_u32 s48, s48, 0x100
	s_addc_u32 s49, s49, 0
	s_add_u32 s71, s71, 0x100
	s_addc_u32 s72, s72, 0
	s_cmp_gt_u32 s73, 29
	s_barrier
	s_cbranch_scc0 .LBB0_1040
	s_and_b64 vcc, exec, s[34:35]
	s_cbranch_vccz .LBB0_1043
	s_barrier

; #define PG8_STAGE(bufoff, gbase, voff) do { _Pragma("unroll") for (int _i = 0; _i < 2; ++_i) \
;         __builtin_amdgcn_global_load_lds((const unsigned*)((const char*)(gbase) + (voff)[_i]), (LAS unsigned*)(lds + (bufoff) + ldsw + _i * 8192), 16, 0, 0); } while (0)
; #define PG8_LDA(dst, b, h) do { _Pragma("unroll") for (int m = 0; m < 4; ++m) _Pragma("unroll") for (int k = 0; k < 2; ++k) dst[m][k] = *(const LAS bf16x8*)(lds + PG8_SA(b, h) + aoff + m * 2048 + k * 1024); } while (0)
; #define PG8_LDB(dst, b, h) do { _Pragma("unroll") for (int n = 0; n < 2; ++n) _Pragma("unroll") for (int k = 0; k < 2; ++k) dst[n][k] = *(const LAS bf16x8*)(lds + PG8_SB(b, h) + boff + n * 2048 + k * 1024); } while (0)
; #define PG8_MMA(ai, bj, At, Bt) do { __builtin_amdgcn_s_setprio(1); _Pragma("unroll") for (int m = 0; m < 4; ++m) _Pragma("unroll") for (int n = 0; n < 2; ++n) _Pragma("unroll") for (int k = 0; k < 2; ++k) \
;         acc[ai][bj][m][n] = __builtin_amdgcn_mfma_f32_16x16x32_bf16(Bt[n][k], At[m][k], acc[ai][bj][m][n], 0, 0, 0); __builtin_amdgcn_s_setprio(0); } while (0)
; #define PG8_WAIT_V(n) asm volatile("s_waitcnt vmcnt(" #n ")" ::: "memory")
; #define PG8_WAIT_L(n) asm volatile("s_waitcnt lgkmcnt(" #n ")" ::: "memory")
; #define PG8_BAR __builtin_amdgcn_s_barrier()
; #define PG8_SCHED __builtin_amdgcn_sched_barrier(0)
; template <class Epi>
; __device__ __forceinline__ void gemm_phase(LAS unsigned char* lds, const Gemm g, const StaticOrder& S, const Epi& E, int wave_s) {
;     ...
;             const bool last = (t == nt - 2);
;             const char* a1 = cA + (size_t)(t + 1) * kstep;
;             const char* a2 = last ? nA : cA + (size_t)(t + 2) * kstep; const char* b2 = last ? nB : cB + (size_t)(t + 2) * kstep;
;             const char* a3 = a2 + kstep; const char* b3 = b2 + kstep;
;             PG8_LDB(B0, 0, 0); PG8_LDB(B1, 0, 1); PG8_SCHED; PG8_LDA(At, 0, 0); PG8_STAGE(PG8_SA(1, 1), a1 + hstepA, voffA);
;             PG8_WAIT_V(8); PG8_WAIT_L(0); PG8_BAR; PG8_MMA(0, 0, At, B0); PG8_MMA(0, 1, At, B1); PG8_BAR; PG8_SCHED;
;             PG8_LDA(At, 0, 1); PG8_STAGE(PG8_SB(0, 0), b2, voffB); PG8_STAGE(PG8_SB(0, 1), b2 + hstepB, voffB); PG8_STAGE(PG8_SA(0, 0), a2, voffA);
;             PG8_WAIT_V(8); PG8_WAIT_L(0); PG8_BAR; PG8_MMA(1, 0, At, B0); PG8_MMA(1, 1, At, B1); PG8_BAR; PG8_SCHED;
.LBB0_1101:
	ds_read_b128 v[146:149], v157
	ds_read_b128 v[150:153], v157 offset:1024
	ds_read_b128 v[160:163], v157 offset:2048
	ds_read_b128 v[164:167], v157 offset:3072
	ds_read_b128 v[168:171], v158
	ds_read_b128 v[172:175], v158 offset:1024
	ds_read_b128 v[176:179], v158 offset:2048
	ds_read_b128 v[180:183], v158 offset:3072
	s_add_u32 s42, s40, 0xfff80080
	s_addc_u32 s43, s41, -1
	s_cmp_eq_u32 s64, 28
	s_cselect_b32 s45, s29, s43
	s_cselect_b32 s44, s37, s42
	s_cselect_b32 s43, s27, s63
	s_cselect_b32 s42, s39, s62
	v_lshl_add_u64 v[216:217], s[40:41], 0, v[138:139]
	s_add_i32 m0, s25, 0xc000
	ds_read_b128 v[184:187], v159
	ds_read_b128 v[188:191], v159 offset:1024
	ds_read_b128 v[192:195], v159 offset:2048
	ds_read_b128 v[196:199], v159 offset:3072
	ds_read_b128 v[200:203], v159 offset:4096
	ds_read_b128 v[204:207], v159 offset:5120
	ds_read_b128 v[208:211], v159 offset:6144
	ds_read_b128 v[212:215], v159 offset:7168
	global_load_lds_dwordx4 v[216:217], off
	v_lshl_add_u64 v[216:217], s[40:41], 0, v[140:141]
	s_add_i32 m0, s25, 0xe000
	s_nop 0
	global_load_lds_dwordx4 v[216:217], off
	s_waitcnt vmcnt(8)
	s_waitcnt lgkmcnt(0)
	s_barrier
	s_setprio 1
	s_waitcnt lgkmcnt(0)
	v_mfma_f32_16x16x32_bf16 v[124:127], v[146:149], v[184:187], v[124:127]
	v_mfma_f32_16x16x32_bf16 v[120:123], v[160:163], v[184:187], v[120:123]
	v_mfma_f32_16x16x32_bf16 v[108:111], v[146:149], v[192:195], v[108:111]
	v_mfma_f32_16x16x32_bf16 v[104:107], v[160:163], v[192:195], v[104:107]
	v_mfma_f32_16x16x32_bf16 v[92:95], v[146:149], v[200:203], v[92:95]
	v_mfma_f32_16x16x32_bf16 v[88:91], v[160:163], v[200:203], v[88:91]
	v_mfma_f32_16x16x32_bf16 v[76:79], v[146:149], v[208:211], v[76:79]
	v_mfma_f32_16x16x32_bf16 v[72:75], v[160:163], v[208:211], v[72:75]
	v_mfma_f32_16x16x32_bf16 v[124:127], v[150:153], v[188:191], v[124:127]
	v_mfma_f32_16x16x32_bf16 v[120:123], v[164:167], v[188:191], v[120:123]
	v_mfma_f32_16x16x32_bf16 v[108:111], v[150:153], v[196:199], v[108:111]
	v_mfma_f32_16x16x32_bf16 v[104:107], v[164:167], v[196:199], v[104:107]
	v_mfma_f32_16x16x32_bf16 v[92:95], v[150:153], v[204:207], v[92:95]
	v_mfma_f32_16x16x32_bf16 v[88:91], v[164:167], v[204:207], v[88:91]
	v_mfma_f32_16x16x32_bf16 v[76:79], v[150:153], v[212:215], v[76:79]
	v_mfma_f32_16x16x32_bf16 v[72:75], v[164:167], v[212:215], v[72:75]
	s_setprio 0
	s_setprio 1
	v_mfma_f32_16x16x32_bf16 v[116:119], v[168:171], v[184:187], v[116:119]
	v_mfma_f32_16x16x32_bf16 v[112:115], v[176:179], v[184:187], v[112:115]
	v_mfma_f32_16x16x32_bf16 v[100:103], v[168:171], v[192:195], v[100:103]
	v_mfma_f32_16x16x32_bf16 v[96:99], v[176:179], v[192:195], v[96:99]
	v_mfma_f32_16x16x32_bf16 v[84:87], v[168:171], v[200:203], v[84:87]
	v_mfma_f32_16x16x32_bf16 v[80:83], v[176:179], v[200:203], v[80:83]
	v_mfma_f32_16x16x32_bf16 v[68:71], v[168:171], v[208:211], v[68:71]
	v_mfma_f32_16x16x32_bf16 v[64:67], v[176:179], v[208:211], v[64:67]
	v_mfma_f32_16x16x32_bf16 v[116:119], v[172:175], v[188:191], v[116:119]
	v_mfma_f32_16x16x32_bf16 v[112:115], v[180:183], v[188:191], v[112:115]
	v_mfma_f32_16x16x32_bf16 v[100:103], v[172:175], v[196:199], v[100:103]
	v_mfma_f32_16x16x32_bf16 v[96:99], v[180:183], v[196:199], v[96:99]
	v_mfma_f32_16x16x32_bf16 v[84:87], v[172:175], v[204:207], v[84:87]
	v_mfma_f32_16x16x32_bf16 v[80:83], v[180:183], v[204:207], v[80:83]
	v_mfma_f32_16x16x32_bf16 v[68:71], v[172:175], v[212:215], v[68:71]
	v_mfma_f32_16x16x32_bf16 v[64:67], v[180:183], v[212:215], v[64:67]
	s_setprio 0
	s_barrier
	s_add_i32 s65, s59, s3
	v_lshl_add_u64 v[216:217], s[42:43], 0, v[130:131]
	s_mov_b32 m0, s65
	ds_read_b128 v[184:187], v159 offset:16384
	ds_read_b128 v[188:191], v159 offset:17408
	ds_read_b128 v[192:195], v159 offset:18432
	ds_read_b128 v[196:199], v159 offset:19456
	ds_read_b128 v[200:203], v159 offset:20480
	ds_read_b128 v[204:207], v159 offset:21504
	ds_read_b128 v[208:211], v159 offset:22528
	ds_read_b128 v[212:215], v159 offset:23552
	global_load_lds_dwordx4 v[216:217], off
	s_add_i32 m0, s65, 0x2000
	s_add_u32 s66, s42, 0x80000
	v_lshl_add_u64 v[218:219], s[42:43], 0, v[134:135]
	s_addc_u32 s67, s43, 0
	s_add_i32 s65, s60, s3
	global_load_lds_dwordx4 v[218:219], off
	v_lshl_add_u64 v[220:221], s[66:67], 0, v[130:131]
	s_mov_b32 m0, s65
	v_lshl_add_u64 v[222:223], s[44:45], 0, v[132:133]
	global_load_lds_dwordx4 v[220:221], off
	v_lshl_add_u64 v[220:221], s[66:67], 0, v[134:135]
	s_add_i32 m0, s65, 0x2000
	s_nop 0
	global_load_lds_dwordx4 v[220:221], off
	v_lshl_add_u64 v[220:221], s[44:45], 0, v[128:129]
	s_mov_b32 m0, s25
	s_nop 0
	global_load_lds_dwordx4 v[220:221], off
	s_mov_b32 m0, s46
	s_nop 0
	global_load_lds_dwordx4 v[222:223], off
	s_waitcnt vmcnt(8)
	s_waitcnt lgkmcnt(0)
	s_barrier
; #define PG8_STAGE(bufoff, gbase, voff) do { _Pragma("unroll") for (int _i = 0; _i < 2; ++_i) \
;         __builtin_amdgcn_global_load_lds((const unsigned*)((const char*)(gbase) + (voff)[_i]), (LAS unsigned*)(lds + (bufoff) + ldsw + _i * 8192), 16, 0, 0); } while (0)
; #define PG8_LDA(dst, b, h) do { _Pragma("unroll") for (int m = 0; m < 4; ++m) _Pragma("unroll") for (int k = 0; k < 2; ++k) dst[m][k] = *(const LAS bf16x8*)(lds + PG8_SA(b, h) + aoff + m * 2048 + k * 1024); } while (0)
; #define PG8_LDB(dst, b, h) do { _Pragma("unroll") for (int n = 0; n < 2; ++n) _Pragma("unroll") for (int k = 0; k < 2; ++k) dst[n][k] = *(const LAS bf16x8*)(lds + PG8_SB(b, h) + boff + n * 2048 + k * 1024); } while (0)
; #define PG8_MMA(ai, bj, At, Bt) do { __builtin_amdgcn_s_setprio(1); _Pragma("unroll") for (int m = 0; m < 4; ++m) _Pragma("unroll") for (int n = 0; n < 2; ++n) _Pragma("unroll") for (int k = 0; k < 2; ++k) \
;         acc[ai][bj][m][n] = __builtin_amdgcn_mfma_f32_16x16x32_bf16(Bt[n][k], At[m][k], acc[ai][bj][m][n], 0, 0, 0); __builtin_amdgcn_s_setprio(0); } while (0)
; #define PG8_WAIT_V(n) asm volatile("s_waitcnt vmcnt(" #n ")" ::: "memory")
; #define PG8_WAIT_L(n) asm volatile("s_waitcnt lgkmcnt(" #n ")" ::: "memory")
; #define PG8_BAR __builtin_amdgcn_s_barrier()
; #define PG8_SCHED __builtin_amdgcn_sched_barrier(0)
; template <class Epi>
; __device__ __forceinline__ void gemm_phase(LAS unsigned char* lds, const Gemm g, const StaticOrder& S, const Epi& E, int wave_s) {
;     ...
;             PG8_WAIT_V(8); PG8_WAIT_L(0); PG8_BAR; PG8_MMA(1, 0, At, B0); PG8_MMA(1, 1, At, B1); PG8_BAR; PG8_SCHED;
;             PG8_LDB(B0, 1, 0); PG8_LDB(B1, 1, 1); PG8_SCHED; PG8_LDA(At, 1, 0); PG8_STAGE(PG8_SA(0, 1), a2 + hstepA, voffA);
;             PG8_WAIT_V(8); PG8_WAIT_L(0); PG8_BAR; PG8_MMA(0, 0, At, B0); PG8_MMA(0, 1, At, B1); PG8_BAR; PG8_SCHED;
	s_setprio 1
	s_waitcnt lgkmcnt(0)
	v_mfma_f32_16x16x32_bf16 v[60:63], v[146:149], v[184:187], v[60:63]
	v_mfma_f32_16x16x32_bf16 v[56:59], v[160:163], v[184:187], v[56:59]
	v_mfma_f32_16x16x32_bf16 v[44:47], v[146:149], v[192:195], v[44:47]
	v_mfma_f32_16x16x32_bf16 v[40:43], v[160:163], v[192:195], v[40:43]
	v_mfma_f32_16x16x32_bf16 v[28:31], v[146:149], v[200:203], v[28:31]
	v_mfma_f32_16x16x32_bf16 v[24:27], v[160:163], v[200:203], v[24:27]
	v_mfma_f32_16x16x32_bf16 v[12:15], v[146:149], v[208:211], v[12:15]
	v_mfma_f32_16x16x32_bf16 v[8:11], v[160:163], v[208:211], v[8:11]
	v_mfma_f32_16x16x32_bf16 v[60:63], v[150:153], v[188:191], v[60:63]
	v_mfma_f32_16x16x32_bf16 v[56:59], v[164:167], v[188:191], v[56:59]
	v_mfma_f32_16x16x32_bf16 v[44:47], v[150:153], v[196:199], v[44:47]
	v_mfma_f32_16x16x32_bf16 v[40:43], v[164:167], v[196:199], v[40:43]
	v_mfma_f32_16x16x32_bf16 v[28:31], v[150:153], v[204:207], v[28:31]
	v_mfma_f32_16x16x32_bf16 v[24:27], v[164:167], v[204:207], v[24:27]
	v_mfma_f32_16x16x32_bf16 v[12:15], v[150:153], v[212:215], v[12:15]
	v_mfma_f32_16x16x32_bf16 v[8:11], v[164:167], v[212:215], v[8:11]
	s_setprio 0
	s_setprio 1
	v_mfma_f32_16x16x32_bf16 v[52:55], v[168:171], v[184:187], v[52:55]
	v_mfma_f32_16x16x32_bf16 v[48:51], v[176:179], v[184:187], v[48:51]
	v_mfma_f32_16x16x32_bf16 v[36:39], v[168:171], v[192:195], v[36:39]
	v_mfma_f32_16x16x32_bf16 v[32:35], v[176:179], v[192:195], v[32:35]
	v_mfma_f32_16x16x32_bf16 v[20:23], v[168:171], v[200:203], v[20:23]
	v_mfma_f32_16x16x32_bf16 v[16:19], v[176:179], v[200:203], v[16:19]
	v_mfma_f32_16x16x32_bf16 v[4:7], v[168:171], v[208:211], v[4:7]
	v_mfma_f32_16x16x32_bf16 v[0:3], v[176:179], v[208:211], v[0:3]
	v_mfma_f32_16x16x32_bf16 v[52:55], v[172:175], v[188:191], v[52:55]
	v_mfma_f32_16x16x32_bf16 v[48:51], v[180:183], v[188:191], v[48:51]
	v_mfma_f32_16x16x32_bf16 v[36:39], v[172:175], v[196:199], v[36:39]
	v_mfma_f32_16x16x32_bf16 v[32:35], v[180:183], v[196:199], v[32:35]
	v_mfma_f32_16x16x32_bf16 v[20:23], v[172:175], v[204:207], v[20:23]
	v_mfma_f32_16x16x32_bf16 v[16:19], v[180:183], v[204:207], v[16:19]
	v_mfma_f32_16x16x32_bf16 v[4:7], v[172:175], v[212:215], v[4:7]
	v_mfma_f32_16x16x32_bf16 v[0:3], v[180:183], v[212:215], v[0:3]
	s_setprio 0
	s_barrier
	s_add_i32 s65, 0, 0x18000
	v_add_u32_e32 v136, s65, v155
	s_add_i32 s66, 0, 0x1c000
	ds_read_b128 v[146:149], v136
	ds_read_b128 v[150:153], v136 offset:1024
	ds_read_b128 v[160:163], v136 offset:2048
	ds_read_b128 v[164:167], v136 offset:3072
	v_add_u32_e32 v136, s66, v155
	ds_read_b128 v[168:171], v136
	ds_read_b128 v[172:175], v136 offset:1024
	ds_read_b128 v[176:179], v136 offset:2048
	ds_read_b128 v[180:183], v136 offset:3072
	s_add_u32 s44, s44, 0x80000
	s_addc_u32 s45, s45, 0
	s_mov_b32 m0, s47
	v_lshl_add_u64 v[224:225], s[44:45], 0, v[128:129]
	ds_read_b128 v[184:187], v159 offset:32768
	ds_read_b128 v[188:191], v159 offset:33792
	ds_read_b128 v[192:195], v159 offset:34816
	ds_read_b128 v[196:199], v159 offset:35840
	ds_read_b128 v[200:203], v159 offset:36864
	ds_read_b128 v[204:207], v159 offset:37888
	ds_read_b128 v[208:211], v159 offset:38912
	ds_read_b128 v[212:215], v159 offset:39936
	global_load_lds_dwordx4 v[224:225], off
	v_lshl_add_u64 v[224:225], s[44:45], 0, v[132:133]
	s_mov_b32 m0, s48
	s_nop 0
	global_load_lds_dwordx4 v[224:225], off
	s_waitcnt vmcnt(8)
	s_waitcnt lgkmcnt(0)
	s_barrier
	s_setprio 1
	s_waitcnt lgkmcnt(0)
	v_mfma_f32_16x16x32_bf16 v[124:127], v[146:149], v[184:187], v[124:127]
	v_mfma_f32_16x16x32_bf16 v[120:123], v[160:163], v[184:187], v[120:123]
	v_mfma_f32_16x16x32_bf16 v[108:111], v[146:149], v[192:195], v[108:111]
	v_mfma_f32_16x16x32_bf16 v[104:107], v[160:163], v[192:195], v[104:107]
	v_mfma_f32_16x16x32_bf16 v[92:95], v[146:149], v[200:203], v[92:95]
	v_mfma_f32_16x16x32_bf16 v[88:91], v[160:163], v[200:203], v[88:91]
	v_mfma_f32_16x16x32_bf16 v[76:79], v[146:149], v[208:211], v[76:79]
	v_mfma_f32_16x16x32_bf16 v[72:75], v[160:163], v[208:211], v[72:75]
	v_mfma_f32_16x16x32_bf16 v[124:127], v[150:153], v[188:191], v[124:127]
	v_mfma_f32_16x16x32_bf16 v[120:123], v[164:167], v[188:191], v[120:123]
	v_mfma_f32_16x16x32_bf16 v[108:111], v[150:153], v[196:199], v[108:111]
	v_mfma_f32_16x16x32_bf16 v[104:107], v[164:167], v[196:199], v[104:107]
	v_mfma_f32_16x16x32_bf16 v[92:95], v[150:153], v[204:207], v[92:95]
	v_mfma_f32_16x16x32_bf16 v[88:91], v[164:167], v[204:207], v[88:91]
	v_mfma_f32_16x16x32_bf16 v[76:79], v[150:153], v[212:215], v[76:79]
	v_mfma_f32_16x16x32_bf16 v[72:75], v[164:167], v[212:215], v[72:75]
	s_setprio 0
	s_setprio 1
	v_mfma_f32_16x16x32_bf16 v[116:119], v[168:171], v[184:187], v[116:119]
	v_mfma_f32_16x16x32_bf16 v[112:115], v[176:179], v[184:187], v[112:115]
	v_mfma_f32_16x16x32_bf16 v[100:103], v[168:171], v[192:195], v[100:103]
	v_mfma_f32_16x16x32_bf16 v[96:99], v[176:179], v[192:195], v[96:99]
	v_mfma_f32_16x16x32_bf16 v[84:87], v[168:171], v[200:203], v[84:87]
	v_mfma_f32_16x16x32_bf16 v[80:83], v[176:179], v[200:203], v[80:83]
	v_mfma_f32_16x16x32_bf16 v[68:71], v[168:171], v[208:211], v[68:71]
	v_mfma_f32_16x16x32_bf16 v[64:67], v[176:179], v[208:211], v[64:67]
	v_mfma_f32_16x16x32_bf16 v[116:119], v[172:175], v[188:191], v[116:119]
	v_mfma_f32_16x16x32_bf16 v[112:115], v[180:183], v[188:191], v[112:115]
	v_mfma_f32_16x16x32_bf16 v[100:103], v[172:175], v[196:199], v[100:103]
	v_mfma_f32_16x16x32_bf16 v[96:99], v[180:183], v[196:199], v[96:99]
	v_mfma_f32_16x16x32_bf16 v[84:87], v[172:175], v[204:207], v[84:87]
	v_mfma_f32_16x16x32_bf16 v[80:83], v[180:183], v[204:207], v[80:83]
	v_mfma_f32_16x16x32_bf16 v[68:71], v[172:175], v[212:215], v[68:71]
	v_mfma_f32_16x16x32_bf16 v[64:67], v[180:183], v[212:215], v[64:67]
	s_setprio 0
	s_barrier
; #define PG8_STAGE(bufoff, gbase, voff) do { _Pragma("unroll") for (int _i = 0; _i < 2; ++_i) \
;         __builtin_amdgcn_global_load_lds((const unsigned*)((const char*)(gbase) + (voff)[_i]), (LAS unsigned*)(lds + (bufoff) + ldsw + _i * 8192), 16, 0, 0); } while (0)
; #define PG8_LDA(dst, b, h) do { _Pragma("unroll") for (int m = 0; m < 4; ++m) _Pragma("unroll") for (int k = 0; k < 2; ++k) dst[m][k] = *(const LAS bf16x8*)(lds + PG8_SA(b, h) + aoff + m * 2048 + k * 1024); } while (0)
; #define PG8_MMA(ai, bj, At, Bt) do { __builtin_amdgcn_s_setprio(1); _Pragma("unroll") for (int m = 0; m < 4; ++m) _Pragma("unroll") for (int n = 0; n < 2; ++n) _Pragma("unroll") for (int k = 0; k < 2; ++k) \
;         acc[ai][bj][m][n] = __builtin_amdgcn_mfma_f32_16x16x32_bf16(Bt[n][k], At[m][k], acc[ai][bj][m][n], 0, 0, 0); __builtin_amdgcn_s_setprio(0); } while (0)
; #define PG8_WAIT_V(n) asm volatile("s_waitcnt vmcnt(" #n ")" ::: "memory")
; #define PG8_WAIT_L(n) asm volatile("s_waitcnt lgkmcnt(" #n ")" ::: "memory")
; #define PG8_BAR __builtin_amdgcn_s_barrier()
; #define PG8_SCHED __builtin_amdgcn_sched_barrier(0)
; template <class Epi>
; __device__ __forceinline__ void gemm_phase(LAS unsigned char* lds, const Gemm g, const StaticOrder& S, const Epi& E, int wave_s) {
;     ...
;             PG8_LDA(At, 1, 1); PG8_STAGE(PG8_SB(1, 0), b3, voffB); PG8_STAGE(PG8_SB(1, 1), b3 + hstepB, voffB); PG8_STAGE(PG8_SA(1, 0), a3, voffA);
;             PG8_WAIT_V(8); PG8_WAIT_L(0); PG8_BAR; PG8_MMA(1, 0, At, B0); PG8_MMA(1, 1, At, B1); PG8_BAR; PG8_SCHED;
;         }
	s_add_i32 s44, s65, s3
	v_lshl_add_u64 v[216:217], v[216:217], 0, s[14:15]
	s_mov_b32 m0, s44
	ds_read_b128 v[184:187], v159 offset:49152
	ds_read_b128 v[188:191], v159 offset:50176
	ds_read_b128 v[192:195], v159 offset:51200
	ds_read_b128 v[196:199], v159 offset:52224
	ds_read_b128 v[200:203], v159 offset:53248
	ds_read_b128 v[204:207], v159 offset:54272
	ds_read_b128 v[208:211], v159 offset:55296
	ds_read_b128 v[212:215], v159 offset:56320
	global_load_lds_dwordx4 v[216:217], off
	s_add_i32 m0, s44, 0x2000
	s_add_u32 s42, s42, 0x80080
	v_lshl_add_u64 v[216:217], v[218:219], 0, s[14:15]
	s_addc_u32 s43, s43, 0
	s_add_i32 s44, s66, s3
	global_load_lds_dwordx4 v[216:217], off
	v_lshl_add_u64 v[216:217], s[42:43], 0, v[130:131]
	s_mov_b32 m0, s44
	s_nop 0
	global_load_lds_dwordx4 v[216:217], off
	v_lshl_add_u64 v[216:217], s[42:43], 0, v[134:135]
	s_add_i32 m0, s44, 0x2000
	s_nop 0
	global_load_lds_dwordx4 v[216:217], off
	v_lshl_add_u64 v[216:217], v[220:221], 0, s[14:15]
	s_mov_b32 m0, s51
	s_nop 0
	global_load_lds_dwordx4 v[216:217], off
	v_lshl_add_u64 v[216:217], v[222:223], 0, s[14:15]
	s_mov_b32 m0, s56
	s_nop 0
	global_load_lds_dwordx4 v[216:217], off
	s_waitcnt vmcnt(8)
	s_waitcnt lgkmcnt(0)
	s_barrier
	s_setprio 1
	s_waitcnt lgkmcnt(0)
	v_mfma_f32_16x16x32_bf16 v[60:63], v[146:149], v[184:187], v[60:63]
	v_mfma_f32_16x16x32_bf16 v[56:59], v[160:163], v[184:187], v[56:59]
	v_mfma_f32_16x16x32_bf16 v[44:47], v[146:149], v[192:195], v[44:47]
	v_mfma_f32_16x16x32_bf16 v[40:43], v[160:163], v[192:195], v[40:43]
	v_mfma_f32_16x16x32_bf16 v[28:31], v[146:149], v[200:203], v[28:31]
	v_mfma_f32_16x16x32_bf16 v[24:27], v[160:163], v[200:203], v[24:27]
	v_mfma_f32_16x16x32_bf16 v[12:15], v[146:149], v[208:211], v[12:15]
	v_mfma_f32_16x16x32_bf16 v[8:11], v[160:163], v[208:211], v[8:11]
	v_mfma_f32_16x16x32_bf16 v[60:63], v[150:153], v[188:191], v[60:63]
	v_mfma_f32_16x16x32_bf16 v[56:59], v[164:167], v[188:191], v[56:59]
	v_mfma_f32_16x16x32_bf16 v[44:47], v[150:153], v[196:199], v[44:47]
	v_mfma_f32_16x16x32_bf16 v[40:43], v[164:167], v[196:199], v[40:43]
	v_mfma_f32_16x16x32_bf16 v[28:31], v[150:153], v[204:207], v[28:31]
	v_mfma_f32_16x16x32_bf16 v[24:27], v[164:167], v[204:207], v[24:27]
	v_mfma_f32_16x16x32_bf16 v[12:15], v[150:153], v[212:215], v[12:15]
	v_mfma_f32_16x16x32_bf16 v[8:11], v[164:167], v[212:215], v[8:11]
	s_setprio 0
	s_setprio 1
	v_mfma_f32_16x16x32_bf16 v[52:55], v[168:171], v[184:187], v[52:55]
	v_mfma_f32_16x16x32_bf16 v[48:51], v[176:179], v[184:187], v[48:51]
	v_mfma_f32_16x16x32_bf16 v[36:39], v[168:171], v[192:195], v[36:39]
	v_mfma_f32_16x16x32_bf16 v[32:35], v[176:179], v[192:195], v[32:35]
	v_mfma_f32_16x16x32_bf16 v[20:23], v[168:171], v[200:203], v[20:23]
	v_mfma_f32_16x16x32_bf16 v[16:19], v[176:179], v[200:203], v[16:19]
	v_mfma_f32_16x16x32_bf16 v[4:7], v[168:171], v[208:211], v[4:7]
	v_mfma_f32_16x16x32_bf16 v[0:3], v[176:179], v[208:211], v[0:3]
	v_mfma_f32_16x16x32_bf16 v[52:55], v[172:175], v[188:191], v[52:55]
	v_mfma_f32_16x16x32_bf16 v[48:51], v[180:183], v[188:191], v[48:51]
	v_mfma_f32_16x16x32_bf16 v[36:39], v[172:175], v[196:199], v[36:39]
	v_mfma_f32_16x16x32_bf16 v[32:35], v[180:183], v[196:199], v[32:35]
	v_mfma_f32_16x16x32_bf16 v[20:23], v[172:175], v[204:207], v[20:23]
	v_mfma_f32_16x16x32_bf16 v[16:19], v[180:183], v[204:207], v[16:19]
	v_mfma_f32_16x16x32_bf16 v[4:7], v[172:175], v[212:215], v[4:7]
	v_mfma_f32_16x16x32_bf16 v[0:3], v[180:183], v[212:215], v[0:3]
	s_setprio 0
	s_add_i32 s64, s64, 2
	s_add_u32 s40, s40, 0x100
	s_addc_u32 s41, s41, 0
	s_add_u32 s62, s62, 0x100
	s_addc_u32 s63, s63, 0
	s_cmp_gt_u32 s64, 29
	s_barrier
	s_cbranch_scc0 .LBB0_1101
	s_and_b64 vcc, exec, s[16:17]
	s_cbranch_vccz .LBB0_1104
	s_barrier

; #define PG8_STAGE(bufoff, gbase, voff) do { _Pragma("unroll") for (int _i = 0; _i < 2; ++_i) \
;         __builtin_amdgcn_global_load_lds((const unsigned*)((const char*)(gbase) + (voff)[_i]), (LAS unsigned*)(lds + (bufoff) + ldsw + _i * 8192), 16, 0, 0); } while (0)
; #define PG8_LDA(dst, b, h) do { _Pragma("unroll") for (int m = 0; m < 4; ++m) _Pragma("unroll") for (int k = 0; k < 2; ++k) dst[m][k] = *(const LAS bf16x8*)(lds + PG8_SA(b, h) + aoff + m * 2048 + k * 1024); } while (0)
; #define PG8_LDB(dst, b, h) do { _Pragma("unroll") for (int n = 0; n < 2; ++n) _Pragma("unroll") for (int k = 0; k < 2; ++k) dst[n][k] = *(const LAS bf16x8*)(lds + PG8_SB(b, h) + boff + n * 2048 + k * 1024); } while (0)
; #define PG8_MMA(ai, bj, At, Bt) do { __builtin_amdgcn_s_setprio(1); _Pragma("unroll") for (int m = 0; m < 4; ++m) _Pragma("unroll") for (int n = 0; n < 2; ++n) _Pragma("unroll") for (int k = 0; k < 2; ++k) \
;         acc[ai][bj][m][n] = __builtin_amdgcn_mfma_f32_16x16x32_bf16(Bt[n][k], At[m][k], acc[ai][bj][m][n], 0, 0, 0); __builtin_amdgcn_s_setprio(0); } while (0)
; #define PG8_WAIT_V(n) asm volatile("s_waitcnt vmcnt(" #n ")" ::: "memory")
; #define PG8_WAIT_L(n) asm volatile("s_waitcnt lgkmcnt(" #n ")" ::: "memory")
; #define PG8_BAR __builtin_amdgcn_s_barrier()
; #define PG8_SCHED __builtin_amdgcn_sched_barrier(0)
; template <class Epi>
; __device__ __forceinline__ void gemm_phase(LAS unsigned char* lds, const Gemm g, const StaticOrder& S, const Epi& E, int wave_s) {
;     ...
;             const bool last = (t == nt - 2);
;             const char* a1 = cA + (size_t)(t + 1) * kstep;
;             const char* a2 = last ? nA : cA + (size_t)(t + 2) * kstep; const char* b2 = last ? nB : cB + (size_t)(t + 2) * kstep;
;             const char* a3 = a2 + kstep; const char* b3 = b2 + kstep;
;             PG8_LDB(B0, 0, 0); PG8_LDB(B1, 0, 1); PG8_SCHED; PG8_LDA(At, 0, 0); PG8_STAGE(PG8_SA(1, 1), a1 + hstepA, voffA);
;             PG8_WAIT_V(8); PG8_WAIT_L(0); PG8_BAR; PG8_MMA(0, 0, At, B0); PG8_MMA(0, 1, At, B1); PG8_BAR; PG8_SCHED;
;             PG8_LDA(At, 0, 1); PG8_STAGE(PG8_SB(0, 0), b2, voffB); PG8_STAGE(PG8_SB(0, 1), b2 + hstepB, voffB); PG8_STAGE(PG8_SA(0, 0), a2, voffA);
;             PG8_WAIT_V(8); PG8_WAIT_L(0); PG8_BAR; PG8_MMA(1, 0, At, B0); PG8_MMA(1, 1, At, B1); PG8_BAR; PG8_SCHED;
.LBB0_1228:
	ds_read_b128 v[150:153], v147
	ds_read_b128 v[154:157], v147 offset:1024
	ds_read_b128 v[158:161], v147 offset:2048
	ds_read_b128 v[162:165], v147 offset:3072
	ds_read_b128 v[166:169], v148
	ds_read_b128 v[170:173], v148 offset:1024
	ds_read_b128 v[174:177], v148 offset:2048
	ds_read_b128 v[178:181], v148 offset:3072
	s_add_u32 s36, s34, 0xfff80080
	s_addc_u32 s37, s35, -1
	s_cmp_eq_u32 s59, 28
	s_cselect_b32 s39, s17, s37
	s_cselect_b32 s38, s55, s36
	s_cselect_b32 s37, s15, s58
	s_cselect_b32 s36, s56, s57
	v_lshl_add_u64 v[214:215], s[34:35], 0, v[136:137]
	s_add_i32 m0, s31, 0xc000
	ds_read_b128 v[182:185], v149
	ds_read_b128 v[186:189], v149 offset:1024
	ds_read_b128 v[190:193], v149 offset:2048
	ds_read_b128 v[194:197], v149 offset:3072
	ds_read_b128 v[198:201], v149 offset:4096
	ds_read_b128 v[202:205], v149 offset:5120
	ds_read_b128 v[206:209], v149 offset:6144
	ds_read_b128 v[210:213], v149 offset:7168
	global_load_lds_dwordx4 v[214:215], off
	v_lshl_add_u64 v[214:215], s[34:35], 0, v[138:139]
	s_add_i32 m0, s31, 0xe000
	s_nop 0
	global_load_lds_dwordx4 v[214:215], off
	s_waitcnt vmcnt(8)
	s_waitcnt lgkmcnt(0)
	s_barrier
	s_setprio 1
	s_waitcnt lgkmcnt(0)
	v_mfma_f32_16x16x32_bf16 v[124:127], v[150:153], v[182:185], v[124:127]
	v_mfma_f32_16x16x32_bf16 v[120:123], v[158:161], v[182:185], v[120:123]
	v_mfma_f32_16x16x32_bf16 v[108:111], v[150:153], v[190:193], v[108:111]
	v_mfma_f32_16x16x32_bf16 v[104:107], v[158:161], v[190:193], v[104:107]
	v_mfma_f32_16x16x32_bf16 v[92:95], v[150:153], v[198:201], v[92:95]
	v_mfma_f32_16x16x32_bf16 v[88:91], v[158:161], v[198:201], v[88:91]
	v_mfma_f32_16x16x32_bf16 v[76:79], v[150:153], v[206:209], v[76:79]
	v_mfma_f32_16x16x32_bf16 v[72:75], v[158:161], v[206:209], v[72:75]
	v_mfma_f32_16x16x32_bf16 v[124:127], v[154:157], v[186:189], v[124:127]
	v_mfma_f32_16x16x32_bf16 v[120:123], v[162:165], v[186:189], v[120:123]
	v_mfma_f32_16x16x32_bf16 v[108:111], v[154:157], v[194:197], v[108:111]
	v_mfma_f32_16x16x32_bf16 v[104:107], v[162:165], v[194:197], v[104:107]
	v_mfma_f32_16x16x32_bf16 v[92:95], v[154:157], v[202:205], v[92:95]
	v_mfma_f32_16x16x32_bf16 v[88:91], v[162:165], v[202:205], v[88:91]
	v_mfma_f32_16x16x32_bf16 v[76:79], v[154:157], v[210:213], v[76:79]
	v_mfma_f32_16x16x32_bf16 v[72:75], v[162:165], v[210:213], v[72:75]
	s_setprio 0
	s_setprio 1
	v_mfma_f32_16x16x32_bf16 v[116:119], v[166:169], v[182:185], v[116:119]
	v_mfma_f32_16x16x32_bf16 v[112:115], v[174:177], v[182:185], v[112:115]
	v_mfma_f32_16x16x32_bf16 v[100:103], v[166:169], v[190:193], v[100:103]
	v_mfma_f32_16x16x32_bf16 v[96:99], v[174:177], v[190:193], v[96:99]
	v_mfma_f32_16x16x32_bf16 v[84:87], v[166:169], v[198:201], v[84:87]
	v_mfma_f32_16x16x32_bf16 v[80:83], v[174:177], v[198:201], v[80:83]
	v_mfma_f32_16x16x32_bf16 v[68:71], v[166:169], v[206:209], v[68:71]
	v_mfma_f32_16x16x32_bf16 v[64:67], v[174:177], v[206:209], v[64:67]
	v_mfma_f32_16x16x32_bf16 v[116:119], v[170:173], v[186:189], v[116:119]
	v_mfma_f32_16x16x32_bf16 v[112:115], v[178:181], v[186:189], v[112:115]
	v_mfma_f32_16x16x32_bf16 v[100:103], v[170:173], v[194:197], v[100:103]
	v_mfma_f32_16x16x32_bf16 v[96:99], v[178:181], v[194:197], v[96:99]
	v_mfma_f32_16x16x32_bf16 v[84:87], v[170:173], v[202:205], v[84:87]
	v_mfma_f32_16x16x32_bf16 v[80:83], v[178:181], v[202:205], v[80:83]
	v_mfma_f32_16x16x32_bf16 v[68:71], v[170:173], v[210:213], v[68:71]
	v_mfma_f32_16x16x32_bf16 v[64:67], v[178:181], v[210:213], v[64:67]
	s_setprio 0
	s_barrier
	s_add_i32 s60, s51, s43
	v_lshl_add_u64 v[214:215], s[36:37], 0, v[130:131]
	s_mov_b32 m0, s60
	ds_read_b128 v[182:185], v149 offset:16384
	ds_read_b128 v[186:189], v149 offset:17408
	ds_read_b128 v[190:193], v149 offset:18432
	ds_read_b128 v[194:197], v149 offset:19456
	ds_read_b128 v[198:201], v149 offset:20480
	ds_read_b128 v[202:205], v149 offset:21504
	ds_read_b128 v[206:209], v149 offset:22528
	ds_read_b128 v[210:213], v149 offset:23552
	global_load_lds_dwordx4 v[214:215], off
	s_add_i32 m0, s60, 0x2000
	s_add_u32 s60, s36, 0x80000
	v_lshl_add_u64 v[216:217], s[36:37], 0, v[134:135]
	s_addc_u32 s61, s37, 0
	s_add_i32 s62, s52, s43
	global_load_lds_dwordx4 v[216:217], off
	v_lshl_add_u64 v[218:219], s[60:61], 0, v[130:131]
	s_mov_b32 m0, s62
	v_lshl_add_u64 v[220:221], s[38:39], 0, v[132:133]
	global_load_lds_dwordx4 v[218:219], off
	v_lshl_add_u64 v[218:219], s[60:61], 0, v[134:135]
	s_add_i32 m0, s62, 0x2000
	s_nop 0
	global_load_lds_dwordx4 v[218:219], off
	v_lshl_add_u64 v[218:219], s[38:39], 0, v[128:129]
	s_mov_b32 m0, s31
	s_nop 0
	global_load_lds_dwordx4 v[218:219], off
	s_mov_b32 m0, s44
	s_nop 0
	global_load_lds_dwordx4 v[220:221], off
	s_waitcnt vmcnt(8)
	s_waitcnt lgkmcnt(0)
	s_barrier
; #define PG8_STAGE(bufoff, gbase, voff) do { _Pragma("unroll") for (int _i = 0; _i < 2; ++_i) \
;         __builtin_amdgcn_global_load_lds((const unsigned*)((const char*)(gbase) + (voff)[_i]), (LAS unsigned*)(lds + (bufoff) + ldsw + _i * 8192), 16, 0, 0); } while (0)
; #define PG8_LDA(dst, b, h) do { _Pragma("unroll") for (int m = 0; m < 4; ++m) _Pragma("unroll") for (int k = 0; k < 2; ++k) dst[m][k] = *(const LAS bf16x8*)(lds + PG8_SA(b, h) + aoff + m * 2048 + k * 1024); } while (0)
; #define PG8_LDB(dst, b, h) do { _Pragma("unroll") for (int n = 0; n < 2; ++n) _Pragma("unroll") for (int k = 0; k < 2; ++k) dst[n][k] = *(const LAS bf16x8*)(lds + PG8_SB(b, h) + boff + n * 2048 + k * 1024); } while (0)
; #define PG8_MMA(ai, bj, At, Bt) do { __builtin_amdgcn_s_setprio(1); _Pragma("unroll") for (int m = 0; m < 4; ++m) _Pragma("unroll") for (int n = 0; n < 2; ++n) _Pragma("unroll") for (int k = 0; k < 2; ++k) \
;         acc[ai][bj][m][n] = __builtin_amdgcn_mfma_f32_16x16x32_bf16(Bt[n][k], At[m][k], acc[ai][bj][m][n], 0, 0, 0); __builtin_amdgcn_s_setprio(0); } while (0)
; #define PG8_WAIT_V(n) asm volatile("s_waitcnt vmcnt(" #n ")" ::: "memory")
; #define PG8_WAIT_L(n) asm volatile("s_waitcnt lgkmcnt(" #n ")" ::: "memory")
; #define PG8_BAR __builtin_amdgcn_s_barrier()
; #define PG8_SCHED __builtin_amdgcn_sched_barrier(0)
; template <class Epi>
; __device__ __forceinline__ void gemm_phase(LAS unsigned char* lds, const Gemm g, const StaticOrder& S, const Epi& E, int wave_s) {
;     ...
;             PG8_WAIT_V(8); PG8_WAIT_L(0); PG8_BAR; PG8_MMA(1, 0, At, B0); PG8_MMA(1, 1, At, B1); PG8_BAR; PG8_SCHED;
;             PG8_LDB(B0, 1, 0); PG8_LDB(B1, 1, 1); PG8_SCHED; PG8_LDA(At, 1, 0); PG8_STAGE(PG8_SA(0, 1), a2 + hstepA, voffA);
;             PG8_WAIT_V(8); PG8_WAIT_L(0); PG8_BAR; PG8_MMA(0, 0, At, B0); PG8_MMA(0, 1, At, B1); PG8_BAR; PG8_SCHED;
	s_setprio 1
	s_waitcnt lgkmcnt(0)
	v_mfma_f32_16x16x32_bf16 v[60:63], v[150:153], v[182:185], v[60:63]
	v_mfma_f32_16x16x32_bf16 v[56:59], v[158:161], v[182:185], v[56:59]
	v_mfma_f32_16x16x32_bf16 v[44:47], v[150:153], v[190:193], v[44:47]
	v_mfma_f32_16x16x32_bf16 v[40:43], v[158:161], v[190:193], v[40:43]
	v_mfma_f32_16x16x32_bf16 v[28:31], v[150:153], v[198:201], v[28:31]
	v_mfma_f32_16x16x32_bf16 v[24:27], v[158:161], v[198:201], v[24:27]
	v_mfma_f32_16x16x32_bf16 v[12:15], v[150:153], v[206:209], v[12:15]
	v_mfma_f32_16x16x32_bf16 v[8:11], v[158:161], v[206:209], v[8:11]
	v_mfma_f32_16x16x32_bf16 v[60:63], v[154:157], v[186:189], v[60:63]
	v_mfma_f32_16x16x32_bf16 v[56:59], v[162:165], v[186:189], v[56:59]
	v_mfma_f32_16x16x32_bf16 v[44:47], v[154:157], v[194:197], v[44:47]
	v_mfma_f32_16x16x32_bf16 v[40:43], v[162:165], v[194:197], v[40:43]
	v_mfma_f32_16x16x32_bf16 v[28:31], v[154:157], v[202:205], v[28:31]
	v_mfma_f32_16x16x32_bf16 v[24:27], v[162:165], v[202:205], v[24:27]
	v_mfma_f32_16x16x32_bf16 v[12:15], v[154:157], v[210:213], v[12:15]
	v_mfma_f32_16x16x32_bf16 v[8:11], v[162:165], v[210:213], v[8:11]
	s_setprio 0
	s_setprio 1
	v_mfma_f32_16x16x32_bf16 v[52:55], v[166:169], v[182:185], v[52:55]
	v_mfma_f32_16x16x32_bf16 v[48:51], v[174:177], v[182:185], v[48:51]
	v_mfma_f32_16x16x32_bf16 v[36:39], v[166:169], v[190:193], v[36:39]
	v_mfma_f32_16x16x32_bf16 v[32:35], v[174:177], v[190:193], v[32:35]
	v_mfma_f32_16x16x32_bf16 v[20:23], v[166:169], v[198:201], v[20:23]
	v_mfma_f32_16x16x32_bf16 v[16:19], v[174:177], v[198:201], v[16:19]
	v_mfma_f32_16x16x32_bf16 v[4:7], v[166:169], v[206:209], v[4:7]
	v_mfma_f32_16x16x32_bf16 v[0:3], v[174:177], v[206:209], v[0:3]
	v_mfma_f32_16x16x32_bf16 v[52:55], v[170:173], v[186:189], v[52:55]
	v_mfma_f32_16x16x32_bf16 v[48:51], v[178:181], v[186:189], v[48:51]
	v_mfma_f32_16x16x32_bf16 v[36:39], v[170:173], v[194:197], v[36:39]
	v_mfma_f32_16x16x32_bf16 v[32:35], v[178:181], v[194:197], v[32:35]
	v_mfma_f32_16x16x32_bf16 v[20:23], v[170:173], v[202:205], v[20:23]
	v_mfma_f32_16x16x32_bf16 v[16:19], v[178:181], v[202:205], v[16:19]
	v_mfma_f32_16x16x32_bf16 v[4:7], v[170:173], v[210:213], v[4:7]
	v_mfma_f32_16x16x32_bf16 v[0:3], v[178:181], v[210:213], v[0:3]
	s_setprio 0
	s_barrier
	s_add_i32 s60, 0, 0x18000
	s_add_i32 s61, 0, 0x1c000
	v_add_u32_e32 v162, s60, v145
	v_add_u32_e32 v178, s61, v145
	ds_read_b128 v[150:153], v162
	ds_read_b128 v[154:157], v162 offset:1024
	ds_read_b128 v[158:161], v162 offset:2048
	ds_read_b128 v[162:165], v162 offset:3072
	ds_read_b128 v[166:169], v178
	ds_read_b128 v[170:173], v178 offset:1024
	ds_read_b128 v[174:177], v178 offset:2048
	ds_read_b128 v[178:181], v178 offset:3072
	s_add_u32 s38, s38, 0x80000
	s_addc_u32 s39, s39, 0
	s_mov_b32 m0, s45
	v_lshl_add_u64 v[222:223], s[38:39], 0, v[128:129]
	ds_read_b128 v[182:185], v149 offset:32768
	ds_read_b128 v[186:189], v149 offset:33792
	ds_read_b128 v[190:193], v149 offset:34816
	ds_read_b128 v[194:197], v149 offset:35840
	ds_read_b128 v[198:201], v149 offset:36864
	ds_read_b128 v[202:205], v149 offset:37888
	ds_read_b128 v[206:209], v149 offset:38912
	ds_read_b128 v[210:213], v149 offset:39936
	global_load_lds_dwordx4 v[222:223], off
	v_lshl_add_u64 v[222:223], s[38:39], 0, v[132:133]
	s_mov_b32 m0, s46
	s_nop 0
	global_load_lds_dwordx4 v[222:223], off
	s_waitcnt vmcnt(8)
	s_waitcnt lgkmcnt(0)
	s_barrier
	s_setprio 1
	s_waitcnt lgkmcnt(0)
	v_mfma_f32_16x16x32_bf16 v[124:127], v[150:153], v[182:185], v[124:127]
	v_mfma_f32_16x16x32_bf16 v[120:123], v[158:161], v[182:185], v[120:123]
	v_mfma_f32_16x16x32_bf16 v[108:111], v[150:153], v[190:193], v[108:111]
	v_mfma_f32_16x16x32_bf16 v[104:107], v[158:161], v[190:193], v[104:107]
	v_mfma_f32_16x16x32_bf16 v[92:95], v[150:153], v[198:201], v[92:95]
	v_mfma_f32_16x16x32_bf16 v[88:91], v[158:161], v[198:201], v[88:91]
	v_mfma_f32_16x16x32_bf16 v[76:79], v[150:153], v[206:209], v[76:79]
	v_mfma_f32_16x16x32_bf16 v[72:75], v[158:161], v[206:209], v[72:75]
	v_mfma_f32_16x16x32_bf16 v[124:127], v[154:157], v[186:189], v[124:127]
	v_mfma_f32_16x16x32_bf16 v[120:123], v[162:165], v[186:189], v[120:123]
	v_mfma_f32_16x16x32_bf16 v[108:111], v[154:157], v[194:197], v[108:111]
	v_mfma_f32_16x16x32_bf16 v[104:107], v[162:165], v[194:197], v[104:107]
	v_mfma_f32_16x16x32_bf16 v[92:95], v[154:157], v[202:205], v[92:95]
	v_mfma_f32_16x16x32_bf16 v[88:91], v[162:165], v[202:205], v[88:91]
	v_mfma_f32_16x16x32_bf16 v[76:79], v[154:157], v[210:213], v[76:79]
	v_mfma_f32_16x16x32_bf16 v[72:75], v[162:165], v[210:213], v[72:75]
	s_setprio 0
	s_setprio 1
	v_mfma_f32_16x16x32_bf16 v[116:119], v[166:169], v[182:185], v[116:119]
	v_mfma_f32_16x16x32_bf16 v[112:115], v[174:177], v[182:185], v[112:115]
	v_mfma_f32_16x16x32_bf16 v[100:103], v[166:169], v[190:193], v[100:103]
	v_mfma_f32_16x16x32_bf16 v[96:99], v[174:177], v[190:193], v[96:99]
	v_mfma_f32_16x16x32_bf16 v[84:87], v[166:169], v[198:201], v[84:87]
	v_mfma_f32_16x16x32_bf16 v[80:83], v[174:177], v[198:201], v[80:83]
	v_mfma_f32_16x16x32_bf16 v[68:71], v[166:169], v[206:209], v[68:71]
	v_mfma_f32_16x16x32_bf16 v[64:67], v[174:177], v[206:209], v[64:67]
	v_mfma_f32_16x16x32_bf16 v[116:119], v[170:173], v[186:189], v[116:119]
	v_mfma_f32_16x16x32_bf16 v[112:115], v[178:181], v[186:189], v[112:115]
	v_mfma_f32_16x16x32_bf16 v[100:103], v[170:173], v[194:197], v[100:103]
	v_mfma_f32_16x16x32_bf16 v[96:99], v[178:181], v[194:197], v[96:99]
	v_mfma_f32_16x16x32_bf16 v[84:87], v[170:173], v[202:205], v[84:87]
	v_mfma_f32_16x16x32_bf16 v[80:83], v[178:181], v[202:205], v[80:83]
	v_mfma_f32_16x16x32_bf16 v[68:71], v[170:173], v[210:213], v[68:71]
	v_mfma_f32_16x16x32_bf16 v[64:67], v[178:181], v[210:213], v[64:67]
	s_setprio 0
	s_barrier
; #define PG8_STAGE(bufoff, gbase, voff) do { _Pragma("unroll") for (int _i = 0; _i < 2; ++_i) \
;         __builtin_amdgcn_global_load_lds((const unsigned*)((const char*)(gbase) + (voff)[_i]), (LAS unsigned*)(lds + (bufoff) + ldsw + _i * 8192), 16, 0, 0); } while (0)
; #define PG8_LDA(dst, b, h) do { _Pragma("unroll") for (int m = 0; m < 4; ++m) _Pragma("unroll") for (int k = 0; k < 2; ++k) dst[m][k] = *(const LAS bf16x8*)(lds + PG8_SA(b, h) + aoff + m * 2048 + k * 1024); } while (0)
; #define PG8_MMA(ai, bj, At, Bt) do { __builtin_amdgcn_s_setprio(1); _Pragma("unroll") for (int m = 0; m < 4; ++m) _Pragma("unroll") for (int n = 0; n < 2; ++n) _Pragma("unroll") for (int k = 0; k < 2; ++k) \
;         acc[ai][bj][m][n] = __builtin_amdgcn_mfma_f32_16x16x32_bf16(Bt[n][k], At[m][k], acc[ai][bj][m][n], 0, 0, 0); __builtin_amdgcn_s_setprio(0); } while (0)
; #define PG8_WAIT_V(n) asm volatile("s_waitcnt vmcnt(" #n ")" ::: "memory")
; #define PG8_WAIT_L(n) asm volatile("s_waitcnt lgkmcnt(" #n ")" ::: "memory")
; #define PG8_BAR __builtin_amdgcn_s_barrier()
; #define PG8_SCHED __builtin_amdgcn_sched_barrier(0)
; template <class Epi>
; __device__ __forceinline__ void gemm_phase(LAS unsigned char* lds, const Gemm g, const StaticOrder& S, const Epi& E, int wave_s) {
;     ...
;             PG8_LDA(At, 1, 1); PG8_STAGE(PG8_SB(1, 0), b3, voffB); PG8_STAGE(PG8_SB(1, 1), b3 + hstepB, voffB); PG8_STAGE(PG8_SA(1, 0), a3, voffA);
;             PG8_WAIT_V(8); PG8_WAIT_L(0); PG8_BAR; PG8_MMA(1, 0, At, B0); PG8_MMA(1, 1, At, B1); PG8_BAR; PG8_SCHED;
;         }
	s_add_i32 s38, s60, s43
	v_lshl_add_u64 v[214:215], v[214:215], 0, s[10:11]
	s_mov_b32 m0, s38
	ds_read_b128 v[182:185], v149 offset:49152
	ds_read_b128 v[186:189], v149 offset:50176
	ds_read_b128 v[190:193], v149 offset:51200
	ds_read_b128 v[194:197], v149 offset:52224
	ds_read_b128 v[198:201], v149 offset:53248
	ds_read_b128 v[202:205], v149 offset:54272
	ds_read_b128 v[206:209], v149 offset:55296
	ds_read_b128 v[210:213], v149 offset:56320
	global_load_lds_dwordx4 v[214:215], off
	s_add_i32 m0, s38, 0x2000
	s_add_u32 s36, s36, 0x80080
	v_lshl_add_u64 v[214:215], v[216:217], 0, s[10:11]
	s_addc_u32 s37, s37, 0
	s_add_i32 s38, s61, s43
	global_load_lds_dwordx4 v[214:215], off
	v_lshl_add_u64 v[214:215], s[36:37], 0, v[130:131]
	s_mov_b32 m0, s38
	s_nop 0
	global_load_lds_dwordx4 v[214:215], off
	v_lshl_add_u64 v[214:215], s[36:37], 0, v[134:135]
	s_add_i32 m0, s38, 0x2000
	s_nop 0
	global_load_lds_dwordx4 v[214:215], off
	v_lshl_add_u64 v[214:215], v[218:219], 0, s[10:11]
	s_mov_b32 m0, s48
	s_nop 0
	global_load_lds_dwordx4 v[214:215], off
	v_lshl_add_u64 v[214:215], v[220:221], 0, s[10:11]
	s_mov_b32 m0, s49
	s_nop 0
	global_load_lds_dwordx4 v[214:215], off
	s_waitcnt vmcnt(8)
	s_waitcnt lgkmcnt(0)
	s_barrier
	s_setprio 1
	s_waitcnt lgkmcnt(0)
	v_mfma_f32_16x16x32_bf16 v[60:63], v[150:153], v[182:185], v[60:63]
	v_mfma_f32_16x16x32_bf16 v[56:59], v[158:161], v[182:185], v[56:59]
	v_mfma_f32_16x16x32_bf16 v[44:47], v[150:153], v[190:193], v[44:47]
	v_mfma_f32_16x16x32_bf16 v[40:43], v[158:161], v[190:193], v[40:43]
	v_mfma_f32_16x16x32_bf16 v[28:31], v[150:153], v[198:201], v[28:31]
	v_mfma_f32_16x16x32_bf16 v[24:27], v[158:161], v[198:201], v[24:27]
	v_mfma_f32_16x16x32_bf16 v[12:15], v[150:153], v[206:209], v[12:15]
	v_mfma_f32_16x16x32_bf16 v[8:11], v[158:161], v[206:209], v[8:11]
	v_mfma_f32_16x16x32_bf16 v[60:63], v[154:157], v[186:189], v[60:63]
	v_mfma_f32_16x16x32_bf16 v[56:59], v[162:165], v[186:189], v[56:59]
	v_mfma_f32_16x16x32_bf16 v[44:47], v[154:157], v[194:197], v[44:47]
	v_mfma_f32_16x16x32_bf16 v[40:43], v[162:165], v[194:197], v[40:43]
	v_mfma_f32_16x16x32_bf16 v[28:31], v[154:157], v[202:205], v[28:31]
	v_mfma_f32_16x16x32_bf16 v[24:27], v[162:165], v[202:205], v[24:27]
	v_mfma_f32_16x16x32_bf16 v[12:15], v[154:157], v[210:213], v[12:15]
	v_mfma_f32_16x16x32_bf16 v[8:11], v[162:165], v[210:213], v[8:11]
	s_setprio 0
	s_setprio 1
	v_mfma_f32_16x16x32_bf16 v[52:55], v[166:169], v[182:185], v[52:55]
	v_mfma_f32_16x16x32_bf16 v[48:51], v[174:177], v[182:185], v[48:51]
	v_mfma_f32_16x16x32_bf16 v[36:39], v[166:169], v[190:193], v[36:39]
	v_mfma_f32_16x16x32_bf16 v[32:35], v[174:177], v[190:193], v[32:35]
	v_mfma_f32_16x16x32_bf16 v[20:23], v[166:169], v[198:201], v[20:23]
	v_mfma_f32_16x16x32_bf16 v[16:19], v[174:177], v[198:201], v[16:19]
	v_mfma_f32_16x16x32_bf16 v[4:7], v[166:169], v[206:209], v[4:7]
	v_mfma_f32_16x16x32_bf16 v[0:3], v[174:177], v[206:209], v[0:3]
	v_mfma_f32_16x16x32_bf16 v[52:55], v[170:173], v[186:189], v[52:55]
	v_mfma_f32_16x16x32_bf16 v[48:51], v[178:181], v[186:189], v[48:51]
	v_mfma_f32_16x16x32_bf16 v[36:39], v[170:173], v[194:197], v[36:39]
	v_mfma_f32_16x16x32_bf16 v[32:35], v[178:181], v[194:197], v[32:35]
	v_mfma_f32_16x16x32_bf16 v[20:23], v[170:173], v[202:205], v[20:23]
	v_mfma_f32_16x16x32_bf16 v[16:19], v[178:181], v[202:205], v[16:19]
	v_mfma_f32_16x16x32_bf16 v[4:7], v[170:173], v[210:213], v[4:7]
	v_mfma_f32_16x16x32_bf16 v[0:3], v[178:181], v[210:213], v[0:3]
	s_setprio 0
	s_add_i32 s59, s59, 2
	s_add_u32 s34, s34, 0x100
	s_addc_u32 s35, s35, 0
	s_add_u32 s57, s57, 0x100
	s_addc_u32 s58, s58, 0
	s_cmp_gt_u32 s59, 29
	s_barrier
	s_cbranch_scc0 .LBB0_1228
	s_and_b64 vcc, exec, s[12:13]
	s_cbranch_vccz .LBB0_1231
	s_barrier

; #define PG8_STAGE(bufoff, gbase, voff) do { _Pragma("unroll") for (int _i = 0; _i < 2; ++_i) \
;         __builtin_amdgcn_global_load_lds((const unsigned*)((const char*)(gbase) + (voff)[_i]), (LAS unsigned*)(lds + (bufoff) + ldsw + _i * 8192), 16, 0, 0); } while (0)
; #define PG8_LDA(dst, b, h) do { _Pragma("unroll") for (int m = 0; m < 4; ++m) _Pragma("unroll") for (int k = 0; k < 2; ++k) dst[m][k] = *(const LAS bf16x8*)(lds + PG8_SA(b, h) + aoff + m * 2048 + k * 1024); } while (0)
; #define PG8_LDB(dst, b, h) do { _Pragma("unroll") for (int n = 0; n < 2; ++n) _Pragma("unroll") for (int k = 0; k < 2; ++k) dst[n][k] = *(const LAS bf16x8*)(lds + PG8_SB(b, h) + boff + n * 2048 + k * 1024); } while (0)
; #define PG8_MMA(ai, bj, At, Bt) do { __builtin_amdgcn_s_setprio(1); _Pragma("unroll") for (int m = 0; m < 4; ++m) _Pragma("unroll") for (int n = 0; n < 2; ++n) _Pragma("unroll") for (int k = 0; k < 2; ++k) \
;         acc[ai][bj][m][n] = __builtin_amdgcn_mfma_f32_16x16x32_bf16(Bt[n][k], At[m][k], acc[ai][bj][m][n], 0, 0, 0); __builtin_amdgcn_s_setprio(0); } while (0)
; #define PG8_WAIT_V(n) asm volatile("s_waitcnt vmcnt(" #n ")" ::: "memory")
; #define PG8_WAIT_L(n) asm volatile("s_waitcnt lgkmcnt(" #n ")" ::: "memory")
; #define PG8_BAR __builtin_amdgcn_s_barrier()
; #define PG8_SCHED __builtin_amdgcn_sched_barrier(0)
; template <class Epi>
; __device__ __forceinline__ void gemm_phase(LAS unsigned char* lds, const Gemm g, const StaticOrder& S, const Epi& E, int wave_s) {
;     ...
;             const bool last = (t == nt - 2);
;             const char* a1 = cA + (size_t)(t + 1) * kstep;
;             const char* a2 = last ? nA : cA + (size_t)(t + 2) * kstep; const char* b2 = last ? nB : cB + (size_t)(t + 2) * kstep;
;             const char* a3 = a2 + kstep; const char* b3 = b2 + kstep;
;             PG8_LDB(B0, 0, 0); PG8_LDB(B1, 0, 1); PG8_SCHED; PG8_LDA(At, 0, 0); PG8_STAGE(PG8_SA(1, 1), a1 + hstepA, voffA);
;             PG8_WAIT_V(8); PG8_WAIT_L(0); PG8_BAR; PG8_MMA(0, 0, At, B0); PG8_MMA(0, 1, At, B1); PG8_BAR; PG8_SCHED;
;             PG8_LDA(At, 0, 1); PG8_STAGE(PG8_SB(0, 0), b2, voffB); PG8_STAGE(PG8_SB(0, 1), b2 + hstepB, voffB); PG8_STAGE(PG8_SA(0, 0), a2, voffA);
;             PG8_WAIT_V(8); PG8_WAIT_L(0); PG8_BAR; PG8_MMA(1, 0, At, B0); PG8_MMA(1, 1, At, B1); PG8_BAR; PG8_SCHED;
.LBB0_1288:
	ds_read_b128 v[128:131], v159
	ds_read_b128 v[132:135], v159 offset:1024
	ds_read_b128 v[152:155], v159 offset:2048
	ds_read_b128 v[162:165], v159 offset:3072
	ds_read_b128 v[166:169], v160
	ds_read_b128 v[170:173], v160 offset:1024
	ds_read_b128 v[174:177], v160 offset:2048
	ds_read_b128 v[178:181], v160 offset:3072
	s_add_u32 s34, s30, 0x100
	s_addc_u32 s35, s31, 0
	s_cmpk_eq_i32 s58, 0x54
	s_cselect_b32 s39, s5, s35
	s_cselect_b32 s38, s4, s34
	s_cselect_b32 s37, s29, s57
	s_cselect_b32 s36, s28, s56
	v_lshl_add_u64 v[214:215], s[30:31], 0, v[144:145]
	s_add_i32 m0, s42, 0xc000
	ds_read_b128 v[182:185], v161
	ds_read_b128 v[186:189], v161 offset:1024
	ds_read_b128 v[190:193], v161 offset:2048
	ds_read_b128 v[194:197], v161 offset:3072
	ds_read_b128 v[198:201], v161 offset:4096
	ds_read_b128 v[202:205], v161 offset:5120
	ds_read_b128 v[206:209], v161 offset:6144
	ds_read_b128 v[210:213], v161 offset:7168
	global_load_lds_dwordx4 v[214:215], off
	v_lshl_add_u64 v[214:215], s[30:31], 0, v[146:147]
	s_add_i32 m0, s42, 0xe000
	s_nop 0
	global_load_lds_dwordx4 v[214:215], off
	s_waitcnt vmcnt(8)
	s_waitcnt lgkmcnt(0)
	s_barrier
	s_setprio 1
	s_waitcnt lgkmcnt(0)
	v_mfma_f32_16x16x32_bf16 v[124:127], v[128:131], v[182:185], v[124:127]
	v_mfma_f32_16x16x32_bf16 v[120:123], v[152:155], v[182:185], v[120:123]
	v_mfma_f32_16x16x32_bf16 v[116:119], v[128:131], v[190:193], v[116:119]
	v_mfma_f32_16x16x32_bf16 v[108:111], v[152:155], v[190:193], v[108:111]
	v_mfma_f32_16x16x32_bf16 v[100:103], v[128:131], v[198:201], v[100:103]
	v_mfma_f32_16x16x32_bf16 v[92:95], v[152:155], v[198:201], v[92:95]
	v_mfma_f32_16x16x32_bf16 v[84:87], v[128:131], v[206:209], v[84:87]
	v_mfma_f32_16x16x32_bf16 v[76:79], v[152:155], v[206:209], v[76:79]
	v_mfma_f32_16x16x32_bf16 v[124:127], v[132:135], v[186:189], v[124:127]
	v_mfma_f32_16x16x32_bf16 v[120:123], v[162:165], v[186:189], v[120:123]
	v_mfma_f32_16x16x32_bf16 v[116:119], v[132:135], v[194:197], v[116:119]
	v_mfma_f32_16x16x32_bf16 v[108:111], v[162:165], v[194:197], v[108:111]
	v_mfma_f32_16x16x32_bf16 v[100:103], v[132:135], v[202:205], v[100:103]
	v_mfma_f32_16x16x32_bf16 v[92:95], v[162:165], v[202:205], v[92:95]
	v_mfma_f32_16x16x32_bf16 v[84:87], v[132:135], v[210:213], v[84:87]
	v_mfma_f32_16x16x32_bf16 v[76:79], v[162:165], v[210:213], v[76:79]
	s_setprio 0
	s_setprio 1
	v_mfma_f32_16x16x32_bf16 v[112:115], v[166:169], v[182:185], v[112:115]
	v_mfma_f32_16x16x32_bf16 v[104:107], v[174:177], v[182:185], v[104:107]
	v_mfma_f32_16x16x32_bf16 v[96:99], v[166:169], v[190:193], v[96:99]
	v_mfma_f32_16x16x32_bf16 v[88:91], v[174:177], v[190:193], v[88:91]
	v_mfma_f32_16x16x32_bf16 v[80:83], v[166:169], v[198:201], v[80:83]
	v_mfma_f32_16x16x32_bf16 v[72:75], v[174:177], v[198:201], v[72:75]
	v_mfma_f32_16x16x32_bf16 v[68:71], v[166:169], v[206:209], v[68:71]
	v_mfma_f32_16x16x32_bf16 v[64:67], v[174:177], v[206:209], v[64:67]
	v_mfma_f32_16x16x32_bf16 v[112:115], v[170:173], v[186:189], v[112:115]
	v_mfma_f32_16x16x32_bf16 v[104:107], v[178:181], v[186:189], v[104:107]
	v_mfma_f32_16x16x32_bf16 v[96:99], v[170:173], v[194:197], v[96:99]
	v_mfma_f32_16x16x32_bf16 v[88:91], v[178:181], v[194:197], v[88:91]
	v_mfma_f32_16x16x32_bf16 v[80:83], v[170:173], v[202:205], v[80:83]
	v_mfma_f32_16x16x32_bf16 v[72:75], v[178:181], v[202:205], v[72:75]
	v_mfma_f32_16x16x32_bf16 v[68:71], v[170:173], v[210:213], v[68:71]
	v_mfma_f32_16x16x32_bf16 v[64:67], v[178:181], v[210:213], v[64:67]
	s_setprio 0
	s_barrier
	s_add_i32 s30, s50, s41
	v_lshl_add_u64 v[214:215], s[36:37], 0, v[138:139]
	s_mov_b32 m0, s30
	ds_read_b128 v[182:185], v161 offset:16384
	ds_read_b128 v[186:189], v161 offset:17408
	ds_read_b128 v[190:193], v161 offset:18432
	ds_read_b128 v[194:197], v161 offset:19456
	ds_read_b128 v[198:201], v161 offset:20480
	ds_read_b128 v[202:205], v161 offset:21504
	ds_read_b128 v[206:209], v161 offset:22528
	ds_read_b128 v[210:213], v161 offset:23552
	global_load_lds_dwordx4 v[214:215], off
	s_add_i32 m0, s30, 0x2000
	s_add_u32 s30, s36, 0x160000
	v_lshl_add_u64 v[216:217], s[36:37], 0, v[142:143]
	s_addc_u32 s31, s37, 0
	s_add_i32 s59, s51, s41
	global_load_lds_dwordx4 v[216:217], off
	v_lshl_add_u64 v[218:219], s[30:31], 0, v[138:139]
	s_mov_b32 m0, s59
	v_lshl_add_u64 v[220:221], s[38:39], 0, v[140:141]
	global_load_lds_dwordx4 v[218:219], off
	v_lshl_add_u64 v[218:219], s[30:31], 0, v[142:143]
	s_add_i32 m0, s59, 0x2000
	s_nop 0
	global_load_lds_dwordx4 v[218:219], off
	v_lshl_add_u64 v[218:219], s[38:39], 0, v[136:137]
	s_mov_b32 m0, s42
	s_nop 0
	global_load_lds_dwordx4 v[218:219], off
	s_mov_b32 m0, s43
	s_nop 0
	global_load_lds_dwordx4 v[220:221], off
	s_waitcnt vmcnt(8)
	s_waitcnt lgkmcnt(0)
	s_barrier
; #define PG8_STAGE(bufoff, gbase, voff) do { _Pragma("unroll") for (int _i = 0; _i < 2; ++_i) \
;         __builtin_amdgcn_global_load_lds((const unsigned*)((const char*)(gbase) + (voff)[_i]), (LAS unsigned*)(lds + (bufoff) + ldsw + _i * 8192), 16, 0, 0); } while (0)
; #define PG8_LDA(dst, b, h) do { _Pragma("unroll") for (int m = 0; m < 4; ++m) _Pragma("unroll") for (int k = 0; k < 2; ++k) dst[m][k] = *(const LAS bf16x8*)(lds + PG8_SA(b, h) + aoff + m * 2048 + k * 1024); } while (0)
; #define PG8_LDB(dst, b, h) do { _Pragma("unroll") for (int n = 0; n < 2; ++n) _Pragma("unroll") for (int k = 0; k < 2; ++k) dst[n][k] = *(const LAS bf16x8*)(lds + PG8_SB(b, h) + boff + n * 2048 + k * 1024); } while (0)
; #define PG8_MMA(ai, bj, At, Bt) do { __builtin_amdgcn_s_setprio(1); _Pragma("unroll") for (int m = 0; m < 4; ++m) _Pragma("unroll") for (int n = 0; n < 2; ++n) _Pragma("unroll") for (int k = 0; k < 2; ++k) \
;         acc[ai][bj][m][n] = __builtin_amdgcn_mfma_f32_16x16x32_bf16(Bt[n][k], At[m][k], acc[ai][bj][m][n], 0, 0, 0); __builtin_amdgcn_s_setprio(0); } while (0)
; #define PG8_WAIT_V(n) asm volatile("s_waitcnt vmcnt(" #n ")" ::: "memory")
; #define PG8_WAIT_L(n) asm volatile("s_waitcnt lgkmcnt(" #n ")" ::: "memory")
; #define PG8_BAR __builtin_amdgcn_s_barrier()
; #define PG8_SCHED __builtin_amdgcn_sched_barrier(0)
; template <class Epi>
; __device__ __forceinline__ void gemm_phase(LAS unsigned char* lds, const Gemm g, const StaticOrder& S, const Epi& E, int wave_s) {
;     ...
;             PG8_WAIT_V(8); PG8_WAIT_L(0); PG8_BAR; PG8_MMA(1, 0, At, B0); PG8_MMA(1, 1, At, B1); PG8_BAR; PG8_SCHED;
;             PG8_LDB(B0, 1, 0); PG8_LDB(B1, 1, 1); PG8_SCHED; PG8_LDA(At, 1, 0); PG8_STAGE(PG8_SA(0, 1), a2 + hstepA, voffA);
;             PG8_WAIT_V(8); PG8_WAIT_L(0); PG8_BAR; PG8_MMA(0, 0, At, B0); PG8_MMA(0, 1, At, B1); PG8_BAR; PG8_SCHED;
	s_setprio 1
	s_waitcnt lgkmcnt(0)
	v_mfma_f32_16x16x32_bf16 v[60:63], v[128:131], v[182:185], v[60:63]
	v_mfma_f32_16x16x32_bf16 v[56:59], v[152:155], v[182:185], v[56:59]
	v_mfma_f32_16x16x32_bf16 v[44:47], v[128:131], v[190:193], v[44:47]
	v_mfma_f32_16x16x32_bf16 v[40:43], v[152:155], v[190:193], v[40:43]
	v_mfma_f32_16x16x32_bf16 v[28:31], v[128:131], v[198:201], v[28:31]
	v_mfma_f32_16x16x32_bf16 v[24:27], v[152:155], v[198:201], v[24:27]
	v_mfma_f32_16x16x32_bf16 v[12:15], v[128:131], v[206:209], v[12:15]
	v_mfma_f32_16x16x32_bf16 v[8:11], v[152:155], v[206:209], v[8:11]
	v_mfma_f32_16x16x32_bf16 v[60:63], v[132:135], v[186:189], v[60:63]
	v_mfma_f32_16x16x32_bf16 v[56:59], v[162:165], v[186:189], v[56:59]
	v_mfma_f32_16x16x32_bf16 v[44:47], v[132:135], v[194:197], v[44:47]
	v_mfma_f32_16x16x32_bf16 v[40:43], v[162:165], v[194:197], v[40:43]
	v_mfma_f32_16x16x32_bf16 v[28:31], v[132:135], v[202:205], v[28:31]
	v_mfma_f32_16x16x32_bf16 v[24:27], v[162:165], v[202:205], v[24:27]
	v_mfma_f32_16x16x32_bf16 v[12:15], v[132:135], v[210:213], v[12:15]
	v_mfma_f32_16x16x32_bf16 v[8:11], v[162:165], v[210:213], v[8:11]
	s_setprio 0
	s_setprio 1
	v_mfma_f32_16x16x32_bf16 v[52:55], v[166:169], v[182:185], v[52:55]
	v_mfma_f32_16x16x32_bf16 v[48:51], v[174:177], v[182:185], v[48:51]
	v_mfma_f32_16x16x32_bf16 v[36:39], v[166:169], v[190:193], v[36:39]
	v_mfma_f32_16x16x32_bf16 v[32:35], v[174:177], v[190:193], v[32:35]
	v_mfma_f32_16x16x32_bf16 v[20:23], v[166:169], v[198:201], v[20:23]
	v_mfma_f32_16x16x32_bf16 v[16:19], v[174:177], v[198:201], v[16:19]
	v_mfma_f32_16x16x32_bf16 v[4:7], v[166:169], v[206:209], v[4:7]
	v_mfma_f32_16x16x32_bf16 v[0:3], v[174:177], v[206:209], v[0:3]
	v_mfma_f32_16x16x32_bf16 v[52:55], v[170:173], v[186:189], v[52:55]
	v_mfma_f32_16x16x32_bf16 v[48:51], v[178:181], v[186:189], v[48:51]
	v_mfma_f32_16x16x32_bf16 v[36:39], v[170:173], v[194:197], v[36:39]
	v_mfma_f32_16x16x32_bf16 v[32:35], v[178:181], v[194:197], v[32:35]
	v_mfma_f32_16x16x32_bf16 v[20:23], v[170:173], v[202:205], v[20:23]
	v_mfma_f32_16x16x32_bf16 v[16:19], v[178:181], v[202:205], v[16:19]
	v_mfma_f32_16x16x32_bf16 v[4:7], v[170:173], v[210:213], v[4:7]
	v_mfma_f32_16x16x32_bf16 v[0:3], v[178:181], v[210:213], v[0:3]
	s_setprio 0
	s_barrier
	s_add_i32 s59, 0, 0x18000
	s_add_i32 s60, 0, 0x1c000
	v_add_u32_e32 v162, s59, v157
	v_add_u32_e32 v178, s60, v157
	ds_read_b128 v[128:131], v162
	ds_read_b128 v[132:135], v162 offset:1024
	ds_read_b128 v[152:155], v162 offset:2048
	ds_read_b128 v[162:165], v162 offset:3072
	ds_read_b128 v[166:169], v178
	ds_read_b128 v[170:173], v178 offset:1024
	ds_read_b128 v[174:177], v178 offset:2048
	ds_read_b128 v[178:181], v178 offset:3072
	s_add_u32 s30, s38, 0x160000
	s_addc_u32 s31, s39, 0
	s_mov_b32 m0, s44
	v_lshl_add_u64 v[222:223], s[30:31], 0, v[136:137]
	ds_read_b128 v[182:185], v161 offset:32768
	ds_read_b128 v[186:189], v161 offset:33792
	ds_read_b128 v[190:193], v161 offset:34816
	ds_read_b128 v[194:197], v161 offset:35840
	ds_read_b128 v[198:201], v161 offset:36864
	ds_read_b128 v[202:205], v161 offset:37888
	ds_read_b128 v[206:209], v161 offset:38912
	ds_read_b128 v[210:213], v161 offset:39936
	global_load_lds_dwordx4 v[222:223], off
	v_lshl_add_u64 v[222:223], s[30:31], 0, v[140:141]
	s_mov_b32 m0, s45
	s_nop 0
	global_load_lds_dwordx4 v[222:223], off
	s_waitcnt vmcnt(8)
	s_waitcnt lgkmcnt(0)
	s_barrier
	s_setprio 1
	s_waitcnt lgkmcnt(0)
	v_mfma_f32_16x16x32_bf16 v[124:127], v[128:131], v[182:185], v[124:127]
	v_mfma_f32_16x16x32_bf16 v[120:123], v[152:155], v[182:185], v[120:123]
	v_mfma_f32_16x16x32_bf16 v[116:119], v[128:131], v[190:193], v[116:119]
	v_mfma_f32_16x16x32_bf16 v[108:111], v[152:155], v[190:193], v[108:111]
	v_mfma_f32_16x16x32_bf16 v[100:103], v[128:131], v[198:201], v[100:103]
	v_mfma_f32_16x16x32_bf16 v[92:95], v[152:155], v[198:201], v[92:95]
	v_mfma_f32_16x16x32_bf16 v[84:87], v[128:131], v[206:209], v[84:87]
	v_mfma_f32_16x16x32_bf16 v[76:79], v[152:155], v[206:209], v[76:79]
	v_mfma_f32_16x16x32_bf16 v[124:127], v[132:135], v[186:189], v[124:127]
	v_mfma_f32_16x16x32_bf16 v[120:123], v[162:165], v[186:189], v[120:123]
	v_mfma_f32_16x16x32_bf16 v[116:119], v[132:135], v[194:197], v[116:119]
	v_mfma_f32_16x16x32_bf16 v[108:111], v[162:165], v[194:197], v[108:111]
	v_mfma_f32_16x16x32_bf16 v[100:103], v[132:135], v[202:205], v[100:103]
	v_mfma_f32_16x16x32_bf16 v[92:95], v[162:165], v[202:205], v[92:95]
	v_mfma_f32_16x16x32_bf16 v[84:87], v[132:135], v[210:213], v[84:87]
	v_mfma_f32_16x16x32_bf16 v[76:79], v[162:165], v[210:213], v[76:79]
	s_setprio 0
	s_setprio 1
	v_mfma_f32_16x16x32_bf16 v[112:115], v[166:169], v[182:185], v[112:115]
	v_mfma_f32_16x16x32_bf16 v[104:107], v[174:177], v[182:185], v[104:107]
	v_mfma_f32_16x16x32_bf16 v[96:99], v[166:169], v[190:193], v[96:99]
	v_mfma_f32_16x16x32_bf16 v[88:91], v[174:177], v[190:193], v[88:91]
	v_mfma_f32_16x16x32_bf16 v[80:83], v[166:169], v[198:201], v[80:83]
	v_mfma_f32_16x16x32_bf16 v[72:75], v[174:177], v[198:201], v[72:75]
	v_mfma_f32_16x16x32_bf16 v[68:71], v[166:169], v[206:209], v[68:71]
	v_mfma_f32_16x16x32_bf16 v[64:67], v[174:177], v[206:209], v[64:67]
	v_mfma_f32_16x16x32_bf16 v[112:115], v[170:173], v[186:189], v[112:115]
	v_mfma_f32_16x16x32_bf16 v[104:107], v[178:181], v[186:189], v[104:107]
	v_mfma_f32_16x16x32_bf16 v[96:99], v[170:173], v[194:197], v[96:99]
	v_mfma_f32_16x16x32_bf16 v[88:91], v[178:181], v[194:197], v[88:91]
	v_mfma_f32_16x16x32_bf16 v[80:83], v[170:173], v[202:205], v[80:83]
	v_mfma_f32_16x16x32_bf16 v[72:75], v[178:181], v[202:205], v[72:75]
	v_mfma_f32_16x16x32_bf16 v[68:71], v[170:173], v[210:213], v[68:71]
	v_mfma_f32_16x16x32_bf16 v[64:67], v[178:181], v[210:213], v[64:67]
	s_setprio 0
	s_barrier
; #define PG8_STAGE(bufoff, gbase, voff) do { _Pragma("unroll") for (int _i = 0; _i < 2; ++_i) \
;         __builtin_amdgcn_global_load_lds((const unsigned*)((const char*)(gbase) + (voff)[_i]), (LAS unsigned*)(lds + (bufoff) + ldsw + _i * 8192), 16, 0, 0); } while (0)
; #define PG8_LDA(dst, b, h) do { _Pragma("unroll") for (int m = 0; m < 4; ++m) _Pragma("unroll") for (int k = 0; k < 2; ++k) dst[m][k] = *(const LAS bf16x8*)(lds + PG8_SA(b, h) + aoff + m * 2048 + k * 1024); } while (0)
; #define PG8_MMA(ai, bj, At, Bt) do { __builtin_amdgcn_s_setprio(1); _Pragma("unroll") for (int m = 0; m < 4; ++m) _Pragma("unroll") for (int n = 0; n < 2; ++n) _Pragma("unroll") for (int k = 0; k < 2; ++k) \
;         acc[ai][bj][m][n] = __builtin_amdgcn_mfma_f32_16x16x32_bf16(Bt[n][k], At[m][k], acc[ai][bj][m][n], 0, 0, 0); __builtin_amdgcn_s_setprio(0); } while (0)
; #define PG8_WAIT_V(n) asm volatile("s_waitcnt vmcnt(" #n ")" ::: "memory")
; #define PG8_WAIT_L(n) asm volatile("s_waitcnt lgkmcnt(" #n ")" ::: "memory")
; #define PG8_BAR __builtin_amdgcn_s_barrier()
; #define PG8_SCHED __builtin_amdgcn_sched_barrier(0)
; template <class Epi>
; __device__ __forceinline__ void gemm_phase(LAS unsigned char* lds, const Gemm g, const StaticOrder& S, const Epi& E, int wave_s) {
;     ...
;             PG8_LDA(At, 1, 1); PG8_STAGE(PG8_SB(1, 0), b3, voffB); PG8_STAGE(PG8_SB(1, 1), b3 + hstepB, voffB); PG8_STAGE(PG8_SA(1, 0), a3, voffA);
;             PG8_WAIT_V(8); PG8_WAIT_L(0); PG8_BAR; PG8_MMA(1, 0, At, B0); PG8_MMA(1, 1, At, B1); PG8_BAR; PG8_SCHED;
;         }
	s_add_i32 s30, s59, s41
	v_lshl_add_u64 v[214:215], v[214:215], 0, s[16:17]
	s_mov_b32 m0, s30
	ds_read_b128 v[182:185], v161 offset:49152
	ds_read_b128 v[186:189], v161 offset:50176
	ds_read_b128 v[190:193], v161 offset:51200
	ds_read_b128 v[194:197], v161 offset:52224
	ds_read_b128 v[198:201], v161 offset:53248
	ds_read_b128 v[202:205], v161 offset:54272
	ds_read_b128 v[206:209], v161 offset:55296
	ds_read_b128 v[210:213], v161 offset:56320
	global_load_lds_dwordx4 v[214:215], off
	s_add_i32 m0, s30, 0x2000
	s_add_u32 s30, s36, 0x160080
	v_lshl_add_u64 v[214:215], v[216:217], 0, s[16:17]
	s_addc_u32 s31, s37, 0
	s_add_i32 s36, s60, s41
	global_load_lds_dwordx4 v[214:215], off
	v_lshl_add_u64 v[214:215], s[30:31], 0, v[138:139]
	s_mov_b32 m0, s36
	s_nop 0
	global_load_lds_dwordx4 v[214:215], off
	v_lshl_add_u64 v[214:215], s[30:31], 0, v[142:143]
	s_add_i32 m0, s36, 0x2000
	s_nop 0
	global_load_lds_dwordx4 v[214:215], off
	v_lshl_add_u64 v[214:215], v[218:219], 0, s[16:17]
	s_mov_b32 m0, s47
	s_nop 0
	global_load_lds_dwordx4 v[214:215], off
	v_lshl_add_u64 v[214:215], v[220:221], 0, s[16:17]
	s_mov_b32 m0, s48
	s_nop 0
	global_load_lds_dwordx4 v[214:215], off
	s_waitcnt vmcnt(8)
	s_waitcnt lgkmcnt(0)
	s_barrier
	s_setprio 1
	s_waitcnt lgkmcnt(0)
	v_mfma_f32_16x16x32_bf16 v[60:63], v[128:131], v[182:185], v[60:63]
	v_mfma_f32_16x16x32_bf16 v[56:59], v[152:155], v[182:185], v[56:59]
	v_mfma_f32_16x16x32_bf16 v[44:47], v[128:131], v[190:193], v[44:47]
	v_mfma_f32_16x16x32_bf16 v[40:43], v[152:155], v[190:193], v[40:43]
	v_mfma_f32_16x16x32_bf16 v[28:31], v[128:131], v[198:201], v[28:31]
	v_mfma_f32_16x16x32_bf16 v[24:27], v[152:155], v[198:201], v[24:27]
	v_mfma_f32_16x16x32_bf16 v[12:15], v[128:131], v[206:209], v[12:15]
	v_mfma_f32_16x16x32_bf16 v[8:11], v[152:155], v[206:209], v[8:11]
	v_mfma_f32_16x16x32_bf16 v[60:63], v[132:135], v[186:189], v[60:63]
	v_mfma_f32_16x16x32_bf16 v[56:59], v[162:165], v[186:189], v[56:59]
	v_mfma_f32_16x16x32_bf16 v[44:47], v[132:135], v[194:197], v[44:47]
	v_mfma_f32_16x16x32_bf16 v[40:43], v[162:165], v[194:197], v[40:43]
	v_mfma_f32_16x16x32_bf16 v[28:31], v[132:135], v[202:205], v[28:31]
	v_mfma_f32_16x16x32_bf16 v[24:27], v[162:165], v[202:205], v[24:27]
	v_mfma_f32_16x16x32_bf16 v[12:15], v[132:135], v[210:213], v[12:15]
	v_mfma_f32_16x16x32_bf16 v[8:11], v[162:165], v[210:213], v[8:11]
	s_setprio 0
	s_setprio 1
	v_mfma_f32_16x16x32_bf16 v[52:55], v[166:169], v[182:185], v[52:55]
	v_mfma_f32_16x16x32_bf16 v[48:51], v[174:177], v[182:185], v[48:51]
	v_mfma_f32_16x16x32_bf16 v[36:39], v[166:169], v[190:193], v[36:39]
	v_mfma_f32_16x16x32_bf16 v[32:35], v[174:177], v[190:193], v[32:35]
	v_mfma_f32_16x16x32_bf16 v[20:23], v[166:169], v[198:201], v[20:23]
	v_mfma_f32_16x16x32_bf16 v[16:19], v[174:177], v[198:201], v[16:19]
	v_mfma_f32_16x16x32_bf16 v[4:7], v[166:169], v[206:209], v[4:7]
	v_mfma_f32_16x16x32_bf16 v[0:3], v[174:177], v[206:209], v[0:3]
	v_mfma_f32_16x16x32_bf16 v[52:55], v[170:173], v[186:189], v[52:55]
	v_mfma_f32_16x16x32_bf16 v[48:51], v[178:181], v[186:189], v[48:51]
	v_mfma_f32_16x16x32_bf16 v[36:39], v[170:173], v[194:197], v[36:39]
	v_mfma_f32_16x16x32_bf16 v[32:35], v[178:181], v[194:197], v[32:35]
	v_mfma_f32_16x16x32_bf16 v[20:23], v[170:173], v[202:205], v[20:23]
	v_mfma_f32_16x16x32_bf16 v[16:19], v[178:181], v[202:205], v[16:19]
	v_mfma_f32_16x16x32_bf16 v[4:7], v[170:173], v[210:213], v[4:7]
	v_mfma_f32_16x16x32_bf16 v[0:3], v[178:181], v[210:213], v[0:3]
	s_setprio 0
	s_add_i32 s58, s58, 2
	s_add_u32 s56, s56, 0x100
	s_addc_u32 s57, s57, 0
	s_cmpk_gt_u32 s58, 0x55
	s_mov_b64 s[30:31], s[34:35]
	s_barrier
	s_cbranch_scc0 .LBB0_1288
	s_and_b64 vcc, exec, s[26:27]
	s_cbranch_vccz .LBB0_1291
	s_barrier

; #define PG8_STAGE(bufoff, gbase, voff) do { _Pragma("unroll") for (int _i = 0; _i < 2; ++_i) \
;         __builtin_amdgcn_global_load_lds((const unsigned*)((const char*)(gbase) + (voff)[_i]), (LAS unsigned*)(lds + (bufoff) + ldsw + _i * 8192), 16, 0, 0); } while (0)
; #define PG8_LDA(dst, b, h) do { _Pragma("unroll") for (int m = 0; m < 4; ++m) _Pragma("unroll") for (int k = 0; k < 2; ++k) dst[m][k] = *(const LAS bf16x8*)(lds + PG8_SA(b, h) + aoff + m * 2048 + k * 1024); } while (0)
; #define PG8_LDB(dst, b, h) do { _Pragma("unroll") for (int n = 0; n < 2; ++n) _Pragma("unroll") for (int k = 0; k < 2; ++k) dst[n][k] = *(const LAS bf16x8*)(lds + PG8_SB(b, h) + boff + n * 2048 + k * 1024); } while (0)
; #define PG8_MMA(ai, bj, At, Bt) do { __builtin_amdgcn_s_setprio(1); _Pragma("unroll") for (int m = 0; m < 4; ++m) _Pragma("unroll") for (int n = 0; n < 2; ++n) _Pragma("unroll") for (int k = 0; k < 2; ++k) \
;         acc[ai][bj][m][n] = __builtin_amdgcn_mfma_f32_16x16x32_bf16(Bt[n][k], At[m][k], acc[ai][bj][m][n], 0, 0, 0); __builtin_amdgcn_s_setprio(0); } while (0)
; #define PG8_WAIT_V(n) asm volatile("s_waitcnt vmcnt(" #n ")" ::: "memory")
; #define PG8_WAIT_L(n) asm volatile("s_waitcnt lgkmcnt(" #n ")" ::: "memory")
; #define PG8_BAR __builtin_amdgcn_s_barrier()
; #define PG8_SCHED __builtin_amdgcn_sched_barrier(0)
; template <class Epi>
; __device__ __forceinline__ void gemm_phase(LAS unsigned char* lds, const Gemm g, const StaticOrder& S, const Epi& E, int wave_s) {
;     ...
;             const bool last = (t == nt - 2);
;             const char* a1 = cA + (size_t)(t + 1) * kstep;
;             const char* a2 = last ? nA : cA + (size_t)(t + 2) * kstep; const char* b2 = last ? nB : cB + (size_t)(t + 2) * kstep;
;             const char* a3 = a2 + kstep; const char* b3 = b2 + kstep;
;             PG8_LDB(B0, 0, 0); PG8_LDB(B1, 0, 1); PG8_SCHED; PG8_LDA(At, 0, 0); PG8_STAGE(PG8_SA(1, 1), a1 + hstepA, voffA);
;             PG8_WAIT_V(8); PG8_WAIT_L(0); PG8_BAR; PG8_MMA(0, 0, At, B0); PG8_MMA(0, 1, At, B1); PG8_BAR; PG8_SCHED;
;             PG8_LDA(At, 0, 1); PG8_STAGE(PG8_SB(0, 0), b2, voffB); PG8_STAGE(PG8_SB(0, 1), b2 + hstepB, voffB); PG8_STAGE(PG8_SA(0, 0), a2, voffA);
;             PG8_WAIT_V(8); PG8_WAIT_L(0); PG8_BAR; PG8_MMA(1, 0, At, B0); PG8_MMA(1, 1, At, B1); PG8_BAR; PG8_SCHED;
.LBB0_1371:
	ds_read_b128 v[144:147], v151
	ds_read_b128 v[154:157], v151 offset:1024
	ds_read_b128 v[158:161], v151 offset:2048
	ds_read_b128 v[162:165], v151 offset:3072
	ds_read_b128 v[166:169], v152
	ds_read_b128 v[170:173], v152 offset:1024
	ds_read_b128 v[174:177], v152 offset:2048
	ds_read_b128 v[178:181], v152 offset:3072
	s_add_u32 s46, s44, 0xfff80080
	s_addc_u32 s47, s45, -1
	s_cmp_eq_u32 s64, 28
	s_cselect_b32 s49, s37, s47
	s_cselect_b32 s48, s60, s46
	s_cselect_b32 s47, s35, s63
	s_cselect_b32 s46, s61, s62
	v_lshl_add_u64 v[214:215], s[44:45], 0, v[136:137]
	s_add_i32 m0, s43, 0xc000
	ds_read_b128 v[182:185], v153
	ds_read_b128 v[186:189], v153 offset:1024
	ds_read_b128 v[190:193], v153 offset:2048
	ds_read_b128 v[194:197], v153 offset:3072
	ds_read_b128 v[198:201], v153 offset:4096
	ds_read_b128 v[202:205], v153 offset:5120
	ds_read_b128 v[206:209], v153 offset:6144
	ds_read_b128 v[210:213], v153 offset:7168
	global_load_lds_dwordx4 v[214:215], off
	v_lshl_add_u64 v[214:215], s[44:45], 0, v[138:139]
	s_add_i32 m0, s43, 0xe000
	s_nop 0
	global_load_lds_dwordx4 v[214:215], off
	s_waitcnt vmcnt(8)
	s_waitcnt lgkmcnt(0)
	s_barrier
	s_setprio 1
	s_waitcnt lgkmcnt(0)
	v_mfma_f32_16x16x32_bf16 v[124:127], v[144:147], v[182:185], v[124:127]
	v_mfma_f32_16x16x32_bf16 v[120:123], v[158:161], v[182:185], v[120:123]
	v_mfma_f32_16x16x32_bf16 v[108:111], v[144:147], v[190:193], v[108:111]
	v_mfma_f32_16x16x32_bf16 v[104:107], v[158:161], v[190:193], v[104:107]
	v_mfma_f32_16x16x32_bf16 v[92:95], v[144:147], v[198:201], v[92:95]
	v_mfma_f32_16x16x32_bf16 v[88:91], v[158:161], v[198:201], v[88:91]
	v_mfma_f32_16x16x32_bf16 v[76:79], v[144:147], v[206:209], v[76:79]
	v_mfma_f32_16x16x32_bf16 v[72:75], v[158:161], v[206:209], v[72:75]
	v_mfma_f32_16x16x32_bf16 v[124:127], v[154:157], v[186:189], v[124:127]
	v_mfma_f32_16x16x32_bf16 v[120:123], v[162:165], v[186:189], v[120:123]
	v_mfma_f32_16x16x32_bf16 v[108:111], v[154:157], v[194:197], v[108:111]
	v_mfma_f32_16x16x32_bf16 v[104:107], v[162:165], v[194:197], v[104:107]
	v_mfma_f32_16x16x32_bf16 v[92:95], v[154:157], v[202:205], v[92:95]
	v_mfma_f32_16x16x32_bf16 v[88:91], v[162:165], v[202:205], v[88:91]
	v_mfma_f32_16x16x32_bf16 v[76:79], v[154:157], v[210:213], v[76:79]
	v_mfma_f32_16x16x32_bf16 v[72:75], v[162:165], v[210:213], v[72:75]
	s_setprio 0
	s_setprio 1
	v_mfma_f32_16x16x32_bf16 v[116:119], v[166:169], v[182:185], v[116:119]
	v_mfma_f32_16x16x32_bf16 v[112:115], v[174:177], v[182:185], v[112:115]
	v_mfma_f32_16x16x32_bf16 v[100:103], v[166:169], v[190:193], v[100:103]
	v_mfma_f32_16x16x32_bf16 v[96:99], v[174:177], v[190:193], v[96:99]
	v_mfma_f32_16x16x32_bf16 v[84:87], v[166:169], v[198:201], v[84:87]
	v_mfma_f32_16x16x32_bf16 v[80:83], v[174:177], v[198:201], v[80:83]
	v_mfma_f32_16x16x32_bf16 v[68:71], v[166:169], v[206:209], v[68:71]
	v_mfma_f32_16x16x32_bf16 v[64:67], v[174:177], v[206:209], v[64:67]
	v_mfma_f32_16x16x32_bf16 v[116:119], v[170:173], v[186:189], v[116:119]
	v_mfma_f32_16x16x32_bf16 v[112:115], v[178:181], v[186:189], v[112:115]
	v_mfma_f32_16x16x32_bf16 v[100:103], v[170:173], v[194:197], v[100:103]
	v_mfma_f32_16x16x32_bf16 v[96:99], v[178:181], v[194:197], v[96:99]
	v_mfma_f32_16x16x32_bf16 v[84:87], v[170:173], v[202:205], v[84:87]
	v_mfma_f32_16x16x32_bf16 v[80:83], v[178:181], v[202:205], v[80:83]
	v_mfma_f32_16x16x32_bf16 v[68:71], v[170:173], v[210:213], v[68:71]
	v_mfma_f32_16x16x32_bf16 v[64:67], v[178:181], v[210:213], v[64:67]
	s_setprio 0
	s_barrier
	s_add_i32 s65, s57, s25
	v_lshl_add_u64 v[214:215], s[46:47], 0, v[130:131]
	s_mov_b32 m0, s65
	ds_read_b128 v[182:185], v153 offset:16384
	ds_read_b128 v[186:189], v153 offset:17408
	ds_read_b128 v[190:193], v153 offset:18432
	ds_read_b128 v[194:197], v153 offset:19456
	ds_read_b128 v[198:201], v153 offset:20480
	ds_read_b128 v[202:205], v153 offset:21504
	ds_read_b128 v[206:209], v153 offset:22528
	ds_read_b128 v[210:213], v153 offset:23552
	global_load_lds_dwordx4 v[214:215], off
	s_add_i32 m0, s65, 0x2000
	s_add_u32 s66, s46, 0x80000
	v_lshl_add_u64 v[216:217], s[46:47], 0, v[134:135]
	s_addc_u32 s67, s47, 0
	s_add_i32 s65, s58, s25
	global_load_lds_dwordx4 v[216:217], off
	v_lshl_add_u64 v[218:219], s[66:67], 0, v[130:131]
	s_mov_b32 m0, s65
	v_lshl_add_u64 v[220:221], s[48:49], 0, v[132:133]
	global_load_lds_dwordx4 v[218:219], off
	v_lshl_add_u64 v[218:219], s[66:67], 0, v[134:135]
	s_add_i32 m0, s65, 0x2000
	s_nop 0
	global_load_lds_dwordx4 v[218:219], off
	v_lshl_add_u64 v[218:219], s[48:49], 0, v[128:129]
	s_mov_b32 m0, s43
	s_nop 0
	global_load_lds_dwordx4 v[218:219], off
	s_mov_b32 m0, s50
	s_nop 0
	global_load_lds_dwordx4 v[220:221], off
	s_waitcnt vmcnt(8)
	s_waitcnt lgkmcnt(0)
	s_barrier
; #define PG8_STAGE(bufoff, gbase, voff) do { _Pragma("unroll") for (int _i = 0; _i < 2; ++_i) \
;         __builtin_amdgcn_global_load_lds((const unsigned*)((const char*)(gbase) + (voff)[_i]), (LAS unsigned*)(lds + (bufoff) + ldsw + _i * 8192), 16, 0, 0); } while (0)
; #define PG8_LDA(dst, b, h) do { _Pragma("unroll") for (int m = 0; m < 4; ++m) _Pragma("unroll") for (int k = 0; k < 2; ++k) dst[m][k] = *(const LAS bf16x8*)(lds + PG8_SA(b, h) + aoff + m * 2048 + k * 1024); } while (0)
; #define PG8_LDB(dst, b, h) do { _Pragma("unroll") for (int n = 0; n < 2; ++n) _Pragma("unroll") for (int k = 0; k < 2; ++k) dst[n][k] = *(const LAS bf16x8*)(lds + PG8_SB(b, h) + boff + n * 2048 + k * 1024); } while (0)
; #define PG8_MMA(ai, bj, At, Bt) do { __builtin_amdgcn_s_setprio(1); _Pragma("unroll") for (int m = 0; m < 4; ++m) _Pragma("unroll") for (int n = 0; n < 2; ++n) _Pragma("unroll") for (int k = 0; k < 2; ++k) \
;         acc[ai][bj][m][n] = __builtin_amdgcn_mfma_f32_16x16x32_bf16(Bt[n][k], At[m][k], acc[ai][bj][m][n], 0, 0, 0); __builtin_amdgcn_s_setprio(0); } while (0)
; #define PG8_WAIT_V(n) asm volatile("s_waitcnt vmcnt(" #n ")" ::: "memory")
; #define PG8_WAIT_L(n) asm volatile("s_waitcnt lgkmcnt(" #n ")" ::: "memory")
; #define PG8_BAR __builtin_amdgcn_s_barrier()
; #define PG8_SCHED __builtin_amdgcn_sched_barrier(0)
; template <class Epi>
; __device__ __forceinline__ void gemm_phase(LAS unsigned char* lds, const Gemm g, const StaticOrder& S, const Epi& E, int wave_s) {
;     ...
;             PG8_WAIT_V(8); PG8_WAIT_L(0); PG8_BAR; PG8_MMA(1, 0, At, B0); PG8_MMA(1, 1, At, B1); PG8_BAR; PG8_SCHED;
;             PG8_LDB(B0, 1, 0); PG8_LDB(B1, 1, 1); PG8_SCHED; PG8_LDA(At, 1, 0); PG8_STAGE(PG8_SA(0, 1), a2 + hstepA, voffA);
;             PG8_WAIT_V(8); PG8_WAIT_L(0); PG8_BAR; PG8_MMA(0, 0, At, B0); PG8_MMA(0, 1, At, B1); PG8_BAR; PG8_SCHED;
	s_setprio 1
	s_waitcnt lgkmcnt(0)
	v_mfma_f32_16x16x32_bf16 v[60:63], v[144:147], v[182:185], v[60:63]
	v_mfma_f32_16x16x32_bf16 v[56:59], v[158:161], v[182:185], v[56:59]
	v_mfma_f32_16x16x32_bf16 v[44:47], v[144:147], v[190:193], v[44:47]
	v_mfma_f32_16x16x32_bf16 v[40:43], v[158:161], v[190:193], v[40:43]
	v_mfma_f32_16x16x32_bf16 v[28:31], v[144:147], v[198:201], v[28:31]
	v_mfma_f32_16x16x32_bf16 v[24:27], v[158:161], v[198:201], v[24:27]
	v_mfma_f32_16x16x32_bf16 v[12:15], v[144:147], v[206:209], v[12:15]
	v_mfma_f32_16x16x32_bf16 v[8:11], v[158:161], v[206:209], v[8:11]
	v_mfma_f32_16x16x32_bf16 v[60:63], v[154:157], v[186:189], v[60:63]
	v_mfma_f32_16x16x32_bf16 v[56:59], v[162:165], v[186:189], v[56:59]
	v_mfma_f32_16x16x32_bf16 v[44:47], v[154:157], v[194:197], v[44:47]
	v_mfma_f32_16x16x32_bf16 v[40:43], v[162:165], v[194:197], v[40:43]
	v_mfma_f32_16x16x32_bf16 v[28:31], v[154:157], v[202:205], v[28:31]
	v_mfma_f32_16x16x32_bf16 v[24:27], v[162:165], v[202:205], v[24:27]
	v_mfma_f32_16x16x32_bf16 v[12:15], v[154:157], v[210:213], v[12:15]
	v_mfma_f32_16x16x32_bf16 v[8:11], v[162:165], v[210:213], v[8:11]
	s_setprio 0
	s_setprio 1
	v_mfma_f32_16x16x32_bf16 v[52:55], v[166:169], v[182:185], v[52:55]
	v_mfma_f32_16x16x32_bf16 v[48:51], v[174:177], v[182:185], v[48:51]
	v_mfma_f32_16x16x32_bf16 v[36:39], v[166:169], v[190:193], v[36:39]
	v_mfma_f32_16x16x32_bf16 v[32:35], v[174:177], v[190:193], v[32:35]
	v_mfma_f32_16x16x32_bf16 v[20:23], v[166:169], v[198:201], v[20:23]
	v_mfma_f32_16x16x32_bf16 v[16:19], v[174:177], v[198:201], v[16:19]
	v_mfma_f32_16x16x32_bf16 v[4:7], v[166:169], v[206:209], v[4:7]
	v_mfma_f32_16x16x32_bf16 v[0:3], v[174:177], v[206:209], v[0:3]
	v_mfma_f32_16x16x32_bf16 v[52:55], v[170:173], v[186:189], v[52:55]
	v_mfma_f32_16x16x32_bf16 v[48:51], v[178:181], v[186:189], v[48:51]
	v_mfma_f32_16x16x32_bf16 v[36:39], v[170:173], v[194:197], v[36:39]
	v_mfma_f32_16x16x32_bf16 v[32:35], v[178:181], v[194:197], v[32:35]
	v_mfma_f32_16x16x32_bf16 v[20:23], v[170:173], v[202:205], v[20:23]
	v_mfma_f32_16x16x32_bf16 v[16:19], v[178:181], v[202:205], v[16:19]
	v_mfma_f32_16x16x32_bf16 v[4:7], v[170:173], v[210:213], v[4:7]
	v_mfma_f32_16x16x32_bf16 v[0:3], v[178:181], v[210:213], v[0:3]
	s_setprio 0
	s_barrier
	s_add_i32 s65, 0, 0x18000
	s_add_i32 s66, 0, 0x1c000
	v_add_u32_e32 v162, s65, v149
	v_add_u32_e32 v178, s66, v149
	ds_read_b128 v[144:147], v162
	ds_read_b128 v[154:157], v162 offset:1024
	ds_read_b128 v[158:161], v162 offset:2048
	ds_read_b128 v[162:165], v162 offset:3072
	ds_read_b128 v[166:169], v178
	ds_read_b128 v[170:173], v178 offset:1024
	ds_read_b128 v[174:177], v178 offset:2048
	ds_read_b128 v[178:181], v178 offset:3072
	s_add_u32 s48, s48, 0x80000
	s_addc_u32 s49, s49, 0
	s_mov_b32 m0, s51
	v_lshl_add_u64 v[222:223], s[48:49], 0, v[128:129]
	ds_read_b128 v[182:185], v153 offset:32768
	ds_read_b128 v[186:189], v153 offset:33792
	ds_read_b128 v[190:193], v153 offset:34816
	ds_read_b128 v[194:197], v153 offset:35840
	ds_read_b128 v[198:201], v153 offset:36864
	ds_read_b128 v[202:205], v153 offset:37888
	ds_read_b128 v[206:209], v153 offset:38912
	ds_read_b128 v[210:213], v153 offset:39936
	global_load_lds_dwordx4 v[222:223], off
	v_lshl_add_u64 v[222:223], s[48:49], 0, v[132:133]
	s_mov_b32 m0, s52
	s_nop 0
	global_load_lds_dwordx4 v[222:223], off
	s_waitcnt vmcnt(8)
	s_waitcnt lgkmcnt(0)
	s_barrier
	s_setprio 1
	s_waitcnt lgkmcnt(0)
	v_mfma_f32_16x16x32_bf16 v[124:127], v[144:147], v[182:185], v[124:127]
	v_mfma_f32_16x16x32_bf16 v[120:123], v[158:161], v[182:185], v[120:123]
	v_mfma_f32_16x16x32_bf16 v[108:111], v[144:147], v[190:193], v[108:111]
	v_mfma_f32_16x16x32_bf16 v[104:107], v[158:161], v[190:193], v[104:107]
	v_mfma_f32_16x16x32_bf16 v[92:95], v[144:147], v[198:201], v[92:95]
	v_mfma_f32_16x16x32_bf16 v[88:91], v[158:161], v[198:201], v[88:91]
	v_mfma_f32_16x16x32_bf16 v[76:79], v[144:147], v[206:209], v[76:79]
	v_mfma_f32_16x16x32_bf16 v[72:75], v[158:161], v[206:209], v[72:75]
	v_mfma_f32_16x16x32_bf16 v[124:127], v[154:157], v[186:189], v[124:127]
	v_mfma_f32_16x16x32_bf16 v[120:123], v[162:165], v[186:189], v[120:123]
	v_mfma_f32_16x16x32_bf16 v[108:111], v[154:157], v[194:197], v[108:111]
	v_mfma_f32_16x16x32_bf16 v[104:107], v[162:165], v[194:197], v[104:107]
	v_mfma_f32_16x16x32_bf16 v[92:95], v[154:157], v[202:205], v[92:95]
	v_mfma_f32_16x16x32_bf16 v[88:91], v[162:165], v[202:205], v[88:91]
	v_mfma_f32_16x16x32_bf16 v[76:79], v[154:157], v[210:213], v[76:79]
	v_mfma_f32_16x16x32_bf16 v[72:75], v[162:165], v[210:213], v[72:75]
	s_setprio 0
	s_setprio 1
	v_mfma_f32_16x16x32_bf16 v[116:119], v[166:169], v[182:185], v[116:119]
	v_mfma_f32_16x16x32_bf16 v[112:115], v[174:177], v[182:185], v[112:115]
	v_mfma_f32_16x16x32_bf16 v[100:103], v[166:169], v[190:193], v[100:103]
	v_mfma_f32_16x16x32_bf16 v[96:99], v[174:177], v[190:193], v[96:99]
	v_mfma_f32_16x16x32_bf16 v[84:87], v[166:169], v[198:201], v[84:87]
	v_mfma_f32_16x16x32_bf16 v[80:83], v[174:177], v[198:201], v[80:83]
	v_mfma_f32_16x16x32_bf16 v[68:71], v[166:169], v[206:209], v[68:71]
	v_mfma_f32_16x16x32_bf16 v[64:67], v[174:177], v[206:209], v[64:67]
	v_mfma_f32_16x16x32_bf16 v[116:119], v[170:173], v[186:189], v[116:119]
	v_mfma_f32_16x16x32_bf16 v[112:115], v[178:181], v[186:189], v[112:115]
	v_mfma_f32_16x16x32_bf16 v[100:103], v[170:173], v[194:197], v[100:103]
	v_mfma_f32_16x16x32_bf16 v[96:99], v[178:181], v[194:197], v[96:99]
	v_mfma_f32_16x16x32_bf16 v[84:87], v[170:173], v[202:205], v[84:87]
	v_mfma_f32_16x16x32_bf16 v[80:83], v[178:181], v[202:205], v[80:83]
	v_mfma_f32_16x16x32_bf16 v[68:71], v[170:173], v[210:213], v[68:71]
	v_mfma_f32_16x16x32_bf16 v[64:67], v[178:181], v[210:213], v[64:67]
	s_setprio 0
	s_barrier
; #define PG8_STAGE(bufoff, gbase, voff) do { _Pragma("unroll") for (int _i = 0; _i < 2; ++_i) \
;         __builtin_amdgcn_global_load_lds((const unsigned*)((const char*)(gbase) + (voff)[_i]), (LAS unsigned*)(lds + (bufoff) + ldsw + _i * 8192), 16, 0, 0); } while (0)
; #define PG8_LDA(dst, b, h) do { _Pragma("unroll") for (int m = 0; m < 4; ++m) _Pragma("unroll") for (int k = 0; k < 2; ++k) dst[m][k] = *(const LAS bf16x8*)(lds + PG8_SA(b, h) + aoff + m * 2048 + k * 1024); } while (0)
; #define PG8_MMA(ai, bj, At, Bt) do { __builtin_amdgcn_s_setprio(1); _Pragma("unroll") for (int m = 0; m < 4; ++m) _Pragma("unroll") for (int n = 0; n < 2; ++n) _Pragma("unroll") for (int k = 0; k < 2; ++k) \
;         acc[ai][bj][m][n] = __builtin_amdgcn_mfma_f32_16x16x32_bf16(Bt[n][k], At[m][k], acc[ai][bj][m][n], 0, 0, 0); __builtin_amdgcn_s_setprio(0); } while (0)
; #define PG8_WAIT_V(n) asm volatile("s_waitcnt vmcnt(" #n ")" ::: "memory")
; #define PG8_WAIT_L(n) asm volatile("s_waitcnt lgkmcnt(" #n ")" ::: "memory")
; #define PG8_BAR __builtin_amdgcn_s_barrier()
; #define PG8_SCHED __builtin_amdgcn_sched_barrier(0)
; template <class Epi>
; __device__ __forceinline__ void gemm_phase(LAS unsigned char* lds, const Gemm g, const StaticOrder& S, const Epi& E, int wave_s) {
;     ...
;             PG8_LDA(At, 1, 1); PG8_STAGE(PG8_SB(1, 0), b3, voffB); PG8_STAGE(PG8_SB(1, 1), b3 + hstepB, voffB); PG8_STAGE(PG8_SA(1, 0), a3, voffA);
;             PG8_WAIT_V(8); PG8_WAIT_L(0); PG8_BAR; PG8_MMA(1, 0, At, B0); PG8_MMA(1, 1, At, B1); PG8_BAR; PG8_SCHED;
;         }
	s_add_i32 s48, s65, s25
	v_lshl_add_u64 v[214:215], v[214:215], 0, s[28:29]
	s_mov_b32 m0, s48
	ds_read_b128 v[182:185], v153 offset:49152
	ds_read_b128 v[186:189], v153 offset:50176
	ds_read_b128 v[190:193], v153 offset:51200
	ds_read_b128 v[194:197], v153 offset:52224
	ds_read_b128 v[198:201], v153 offset:53248
	ds_read_b128 v[202:205], v153 offset:54272
	ds_read_b128 v[206:209], v153 offset:55296
	ds_read_b128 v[210:213], v153 offset:56320
	global_load_lds_dwordx4 v[214:215], off
	s_add_i32 m0, s48, 0x2000
	s_add_u32 s46, s46, 0x80080
	v_lshl_add_u64 v[214:215], v[216:217], 0, s[28:29]
	s_addc_u32 s47, s47, 0
	s_add_i32 s48, s66, s25
	global_load_lds_dwordx4 v[214:215], off
	v_lshl_add_u64 v[214:215], s[46:47], 0, v[130:131]
	s_mov_b32 m0, s48
	s_nop 0
	global_load_lds_dwordx4 v[214:215], off
	v_lshl_add_u64 v[214:215], s[46:47], 0, v[134:135]
	s_add_i32 m0, s48, 0x2000
	s_nop 0
	global_load_lds_dwordx4 v[214:215], off
	v_lshl_add_u64 v[214:215], v[218:219], 0, s[28:29]
	s_mov_b32 m0, s54
	s_nop 0
	global_load_lds_dwordx4 v[214:215], off
	v_lshl_add_u64 v[214:215], v[220:221], 0, s[28:29]
	s_mov_b32 m0, s55
	s_nop 0
	global_load_lds_dwordx4 v[214:215], off
	s_waitcnt vmcnt(8)
	s_waitcnt lgkmcnt(0)
	s_barrier
	s_setprio 1
	s_waitcnt lgkmcnt(0)
	v_mfma_f32_16x16x32_bf16 v[60:63], v[144:147], v[182:185], v[60:63]
	v_mfma_f32_16x16x32_bf16 v[56:59], v[158:161], v[182:185], v[56:59]
	v_mfma_f32_16x16x32_bf16 v[44:47], v[144:147], v[190:193], v[44:47]
	v_mfma_f32_16x16x32_bf16 v[40:43], v[158:161], v[190:193], v[40:43]
	v_mfma_f32_16x16x32_bf16 v[28:31], v[144:147], v[198:201], v[28:31]
	v_mfma_f32_16x16x32_bf16 v[24:27], v[158:161], v[198:201], v[24:27]
	v_mfma_f32_16x16x32_bf16 v[12:15], v[144:147], v[206:209], v[12:15]
	v_mfma_f32_16x16x32_bf16 v[8:11], v[158:161], v[206:209], v[8:11]
	v_mfma_f32_16x16x32_bf16 v[60:63], v[154:157], v[186:189], v[60:63]
	v_mfma_f32_16x16x32_bf16 v[56:59], v[162:165], v[186:189], v[56:59]
	v_mfma_f32_16x16x32_bf16 v[44:47], v[154:157], v[194:197], v[44:47]
	v_mfma_f32_16x16x32_bf16 v[40:43], v[162:165], v[194:197], v[40:43]
	v_mfma_f32_16x16x32_bf16 v[28:31], v[154:157], v[202:205], v[28:31]
	v_mfma_f32_16x16x32_bf16 v[24:27], v[162:165], v[202:205], v[24:27]
	v_mfma_f32_16x16x32_bf16 v[12:15], v[154:157], v[210:213], v[12:15]
	v_mfma_f32_16x16x32_bf16 v[8:11], v[162:165], v[210:213], v[8:11]
	s_setprio 0
	s_setprio 1
	v_mfma_f32_16x16x32_bf16 v[52:55], v[166:169], v[182:185], v[52:55]
	v_mfma_f32_16x16x32_bf16 v[48:51], v[174:177], v[182:185], v[48:51]
	v_mfma_f32_16x16x32_bf16 v[36:39], v[166:169], v[190:193], v[36:39]
	v_mfma_f32_16x16x32_bf16 v[32:35], v[174:177], v[190:193], v[32:35]
	v_mfma_f32_16x16x32_bf16 v[20:23], v[166:169], v[198:201], v[20:23]
	v_mfma_f32_16x16x32_bf16 v[16:19], v[174:177], v[198:201], v[16:19]
	v_mfma_f32_16x16x32_bf16 v[4:7], v[166:169], v[206:209], v[4:7]
	v_mfma_f32_16x16x32_bf16 v[0:3], v[174:177], v[206:209], v[0:3]
	v_mfma_f32_16x16x32_bf16 v[52:55], v[170:173], v[186:189], v[52:55]
	v_mfma_f32_16x16x32_bf16 v[48:51], v[178:181], v[186:189], v[48:51]
	v_mfma_f32_16x16x32_bf16 v[36:39], v[170:173], v[194:197], v[36:39]
	v_mfma_f32_16x16x32_bf16 v[32:35], v[178:181], v[194:197], v[32:35]
	v_mfma_f32_16x16x32_bf16 v[20:23], v[170:173], v[202:205], v[20:23]
	v_mfma_f32_16x16x32_bf16 v[16:19], v[178:181], v[202:205], v[16:19]
	v_mfma_f32_16x16x32_bf16 v[4:7], v[170:173], v[210:213], v[4:7]
	v_mfma_f32_16x16x32_bf16 v[0:3], v[178:181], v[210:213], v[0:3]
	s_setprio 0
	s_add_i32 s64, s64, 2
	s_add_u32 s44, s44, 0x100
	s_addc_u32 s45, s45, 0
	s_add_u32 s62, s62, 0x100
	s_addc_u32 s63, s63, 0
	s_cmp_gt_u32 s64, 29
	s_barrier
	s_cbranch_scc0 .LBB0_1371
	s_and_b64 vcc, exec, s[30:31]
	s_cbranch_vccz .LBB0_1374
	s_barrier
